# m1+m2, priority given to the GEMM load segments instead of the MFMA segments
# speedup vs baseline: 1.0132x; 1.0017x over previous
; #define PG8_STAGE(bufoff, gbase, voff) do { _Pragma("unroll") for (int _i = 0; _i < 2; ++_i) \
;         __builtin_amdgcn_global_load_lds((const unsigned*)((const char*)(gbase) + (voff)[_i]), (PG8_LAS unsigned*)(lds + (bufoff) + ldsw + _i * 8192), 16, 0, 0); } while (0)
; #define PG8_LDA(dst, b, h) do { _Pragma("unroll") for (int m = 0; m < 4; ++m) _Pragma("unroll") for (int k = 0; k < 2; ++k) dst[m][k] = *(const PG8_LAS bf16x8*)(lds + PG8_SA(b, h) + aoff + m * 2048 + k * 1024); } while (0)
; #define PG8_LDB(dst, b, h) do { _Pragma("unroll") for (int n = 0; n < 2; ++n) _Pragma("unroll") for (int k = 0; k < 2; ++k) dst[n][k] = *(const PG8_LAS bf16x8*)(lds + PG8_SB(b, h) + boff + n * 2048 + k * 1024); } while (0)
; #define PG8_MMA(ai, bj, At, Bt) do { __builtin_amdgcn_s_setprio(1); _Pragma("unroll") for (int m = 0; m < 4; ++m) _Pragma("unroll") for (int n = 0; n < 2; ++n) _Pragma("unroll") for (int k = 0; k < 2; ++k) \
;         acc[ai][bj][m][n] = __builtin_amdgcn_mfma_f32_16x16x32_bf16(Bt[n][k], At[m][k], acc[ai][bj][m][n], 0, 0, 0); __builtin_amdgcn_s_setprio(0); } while (0)
; #define PG8_WAIT_V(n) asm volatile("s_waitcnt vmcnt(" #n ")" ::: "memory")
; #define PG8_WAIT_L(n) asm volatile("s_waitcnt lgkmcnt(" #n ")" ::: "memory")
; #define PG8_BAR __builtin_amdgcn_s_barrier()
; #define PG8_SCHED __builtin_amdgcn_sched_barrier(0)
; template <class Epi, class Sched, bool ALIGN_EPI = false, bool SP2 = false>
; __device__ __forceinline__ void gemm_phase(PG8_LAS unsigned char* lds, const Gemm g, const Sched& S, const Epi& E, const int tid) {
;     ...
;             const bool last = (t == nt - 2);
;             const char* a1 = cA + (size_t)(t + 1) * kstep;
;             const char* a2 = last ? nA : cA + (size_t)(t + 2) * kstep; const char* b2 = last ? nB : cB + (size_t)(t + 2) * kstep;
;             const char* a3 = a2 + kstep; const char* b3 = b2 + kstep;
;             if (last && has_next) S.a_ready(nxt);
;             if constexpr (SP2) {
;             PG8_LDB(B0, 0, 0); PG8_LDB(B1, 0, 1); PG8_SCHED; PG8_LDA(At, 0, 0); PG8_STAGE(PG8_SA(1, 1), a1 + hstep, voffA);
;             PG8_WAIT_V(8); PG8_WAIT_L(0); PG8_BAR; PG8_MMA(0, 0, At, B0); PG8_MMA(0, 1, At, B1); PG8_BAR; PG8_SCHED;
;             PG8_LDA(At, 0, 1); PG8_STAGE(PG8_SB(0, 0), b2, voffB); PG8_STAGE(PG8_SB(0, 1), b2 + hstep, voffB); PG8_STAGE(PG8_SA(0, 0), a2, voffA);
.LBB0_38:
	s_add_u32 s58, s44, 0xfffc0080
	s_addc_u32 s59, s45, -1
	s_add_i32 s73, 0, 0x10000
	s_cmp_eq_u32 s72, 12
	s_cselect_b32 s79, s17, s59
	s_cselect_b32 s78, s60, s58
	v_add_u32_e32 v138, s73, v140
	s_cselect_b32 s59, s15, s71
	s_cselect_b32 s58, s70, s62
	s_add_i32 s76, 0, 0x14000
	ds_read_b128 v[142:145], v138
	ds_read_b128 v[146:149], v138 offset:1024
	ds_read_b128 v[150:153], v138 offset:2048
	ds_read_b128 v[154:157], v138 offset:3072
	v_add_u32_e32 v138, s76, v140
	ds_read_b128 v[158:161], v138
	ds_read_b128 v[162:165], v138 offset:1024
	ds_read_b128 v[166:169], v138 offset:2048
	ds_read_b128 v[170:173], v138 offset:3072
	v_lshl_add_u64 v[138:139], s[44:45], 0, v[134:135]
	s_add_i32 m0, s38, 0xc000
	ds_read_b128 v[174:177], v141
	ds_read_b128 v[178:181], v141 offset:1024
	ds_read_b128 v[182:185], v141 offset:2048
	ds_read_b128 v[186:189], v141 offset:3072
	ds_read_b128 v[212:215], v141 offset:4096
	ds_read_b128 v[216:219], v141 offset:5120
	ds_read_b128 v[232:235], v141 offset:6144
	ds_read_b128 v[236:239], v141 offset:7168
	global_load_lds_dwordx4 v[138:139], off
	v_lshl_add_u64 v[138:139], s[44:45], 0, v[136:137]
	s_add_i32 m0, s38, 0xe000
	s_nop 0
	global_load_lds_dwordx4 v[138:139], off
	s_waitcnt vmcnt(8)
	s_waitcnt lgkmcnt(0)
	s_barrier
	s_setprio 0
	s_waitcnt lgkmcnt(0)
	v_mfma_f32_16x16x32_bf16 v[124:127], v[142:145], v[174:177], v[124:127]
	v_mfma_f32_16x16x32_bf16 v[120:123], v[150:153], v[174:177], v[120:123]
	v_mfma_f32_16x16x32_bf16 v[108:111], v[142:145], v[182:185], v[108:111]
	v_mfma_f32_16x16x32_bf16 v[104:107], v[150:153], v[182:185], v[104:107]
	v_mfma_f32_16x16x32_bf16 v[92:95], v[142:145], v[212:215], v[92:95]
	v_mfma_f32_16x16x32_bf16 v[88:91], v[150:153], v[212:215], v[88:91]
	v_mfma_f32_16x16x32_bf16 v[76:79], v[142:145], v[232:235], v[76:79]
	v_mfma_f32_16x16x32_bf16 v[72:75], v[150:153], v[232:235], v[72:75]
	v_mfma_f32_16x16x32_bf16 v[124:127], v[146:149], v[178:181], v[124:127]
	v_mfma_f32_16x16x32_bf16 v[120:123], v[154:157], v[178:181], v[120:123]
	v_mfma_f32_16x16x32_bf16 v[108:111], v[146:149], v[186:189], v[108:111]
	v_mfma_f32_16x16x32_bf16 v[104:107], v[154:157], v[186:189], v[104:107]
	v_mfma_f32_16x16x32_bf16 v[92:95], v[146:149], v[216:219], v[92:95]
	v_mfma_f32_16x16x32_bf16 v[88:91], v[154:157], v[216:219], v[88:91]
	v_mfma_f32_16x16x32_bf16 v[76:79], v[146:149], v[236:239], v[76:79]
	v_mfma_f32_16x16x32_bf16 v[72:75], v[154:157], v[236:239], v[72:75]
	v_mfma_f32_16x16x32_bf16 v[116:119], v[158:161], v[174:177], v[116:119]
	v_mfma_f32_16x16x32_bf16 v[112:115], v[166:169], v[174:177], v[112:115]
	v_mfma_f32_16x16x32_bf16 v[100:103], v[158:161], v[182:185], v[100:103]
	v_mfma_f32_16x16x32_bf16 v[96:99], v[166:169], v[182:185], v[96:99]
	v_mfma_f32_16x16x32_bf16 v[84:87], v[158:161], v[212:215], v[84:87]
	v_mfma_f32_16x16x32_bf16 v[80:83], v[166:169], v[212:215], v[80:83]
	v_mfma_f32_16x16x32_bf16 v[68:71], v[158:161], v[232:235], v[68:71]
	v_mfma_f32_16x16x32_bf16 v[64:67], v[166:169], v[232:235], v[64:67]
	v_mfma_f32_16x16x32_bf16 v[116:119], v[162:165], v[178:181], v[116:119]
	v_mfma_f32_16x16x32_bf16 v[112:115], v[170:173], v[178:181], v[112:115]
	v_mfma_f32_16x16x32_bf16 v[100:103], v[162:165], v[186:189], v[100:103]
	v_mfma_f32_16x16x32_bf16 v[96:99], v[170:173], v[186:189], v[96:99]
	v_mfma_f32_16x16x32_bf16 v[84:87], v[162:165], v[216:219], v[84:87]
	v_mfma_f32_16x16x32_bf16 v[80:83], v[170:173], v[216:219], v[80:83]
	v_mfma_f32_16x16x32_bf16 v[68:71], v[162:165], v[236:239], v[68:71]
	v_mfma_f32_16x16x32_bf16 v[64:67], v[170:173], v[236:239], v[64:67]
	s_setprio 1
	s_barrier
	s_add_i32 s73, s73, s35
	v_lshl_add_u64 v[138:139], s[58:59], 0, v[192:193]
	s_mov_b32 m0, s73
	ds_read_b128 v[174:177], v141 offset:16384
	ds_read_b128 v[178:181], v141 offset:17408
	ds_read_b128 v[182:185], v141 offset:18432
	ds_read_b128 v[186:189], v141 offset:19456
	ds_read_b128 v[212:215], v141 offset:20480
	ds_read_b128 v[216:219], v141 offset:21504
	ds_read_b128 v[232:235], v141 offset:22528
	ds_read_b128 v[236:239], v141 offset:23552
	global_load_lds_dwordx4 v[138:139], off
	s_add_i32 m0, s73, 0x2000
	s_add_u32 s74, s58, 0x40000
	v_lshl_add_u64 v[190:191], s[58:59], 0, v[132:133]
	s_addc_u32 s75, s59, 0
	s_add_i32 s73, s76, s35
	global_load_lds_dwordx4 v[190:191], off
	v_lshl_add_u64 v[194:195], s[74:75], 0, v[192:193]
	s_mov_b32 m0, s73
	v_lshl_add_u64 v[196:197], s[78:79], 0, v[130:131]
	global_load_lds_dwordx4 v[194:195], off
	v_lshl_add_u64 v[194:195], s[74:75], 0, v[132:133]
	s_add_i32 m0, s73, 0x2000
	s_nop 0
	global_load_lds_dwordx4 v[194:195], off
	v_lshl_add_u64 v[194:195], s[78:79], 0, v[128:129]
	s_mov_b32 m0, s38
	s_nop 0
	global_load_lds_dwordx4 v[194:195], off
	s_mov_b32 m0, s40
	s_nop 0
	global_load_lds_dwordx4 v[196:197], off
	s_waitcnt vmcnt(8)
	s_waitcnt lgkmcnt(0)
	s_barrier
; #define PG8_STAGE(bufoff, gbase, voff) do { _Pragma("unroll") for (int _i = 0; _i < 2; ++_i) \
;         __builtin_amdgcn_global_load_lds((const unsigned*)((const char*)(gbase) + (voff)[_i]), (PG8_LAS unsigned*)(lds + (bufoff) + ldsw + _i * 8192), 16, 0, 0); } while (0)
; #define PG8_LDA(dst, b, h) do { _Pragma("unroll") for (int m = 0; m < 4; ++m) _Pragma("unroll") for (int k = 0; k < 2; ++k) dst[m][k] = *(const PG8_LAS bf16x8*)(lds + PG8_SA(b, h) + aoff + m * 2048 + k * 1024); } while (0)
; #define PG8_LDB(dst, b, h) do { _Pragma("unroll") for (int n = 0; n < 2; ++n) _Pragma("unroll") for (int k = 0; k < 2; ++k) dst[n][k] = *(const PG8_LAS bf16x8*)(lds + PG8_SB(b, h) + boff + n * 2048 + k * 1024); } while (0)
; #define PG8_MMA(ai, bj, At, Bt) do { __builtin_amdgcn_s_setprio(1); _Pragma("unroll") for (int m = 0; m < 4; ++m) _Pragma("unroll") for (int n = 0; n < 2; ++n) _Pragma("unroll") for (int k = 0; k < 2; ++k) \
;         acc[ai][bj][m][n] = __builtin_amdgcn_mfma_f32_16x16x32_bf16(Bt[n][k], At[m][k], acc[ai][bj][m][n], 0, 0, 0); __builtin_amdgcn_s_setprio(0); } while (0)
; #define PG8_WAIT_V(n) asm volatile("s_waitcnt vmcnt(" #n ")" ::: "memory")
; #define PG8_WAIT_L(n) asm volatile("s_waitcnt lgkmcnt(" #n ")" ::: "memory")
; #define PG8_BAR __builtin_amdgcn_s_barrier()
; #define PG8_SCHED __builtin_amdgcn_sched_barrier(0)
; template <class Epi, class Sched, bool ALIGN_EPI = false, bool SP2 = false>
; __device__ __forceinline__ void gemm_phase(PG8_LAS unsigned char* lds, const Gemm g, const Sched& S, const Epi& E, const int tid) {
;     ...
;             PG8_WAIT_V(8); PG8_WAIT_L(0); PG8_BAR; PG8_MMA(1, 0, At, B0); PG8_MMA(1, 1, At, B1); PG8_BAR; PG8_SCHED;
;             PG8_LDB(B0, 1, 0); PG8_LDB(B1, 1, 1); PG8_SCHED; PG8_LDA(At, 1, 0); PG8_STAGE(PG8_SA(0, 1), a2 + hstep, voffA);
;             PG8_WAIT_V(8); PG8_WAIT_L(0); PG8_BAR; PG8_MMA(0, 0, At, B0); PG8_MMA(0, 1, At, B1); PG8_BAR; PG8_SCHED;
	s_setprio 0
	s_waitcnt lgkmcnt(0)
	v_mfma_f32_16x16x32_bf16 v[60:63], v[142:145], v[174:177], v[60:63]
	v_mfma_f32_16x16x32_bf16 v[56:59], v[150:153], v[174:177], v[56:59]
	v_mfma_f32_16x16x32_bf16 v[44:47], v[142:145], v[182:185], v[44:47]
	v_mfma_f32_16x16x32_bf16 v[40:43], v[150:153], v[182:185], v[40:43]
	v_mfma_f32_16x16x32_bf16 v[28:31], v[142:145], v[212:215], v[28:31]
	v_mfma_f32_16x16x32_bf16 v[24:27], v[150:153], v[212:215], v[24:27]
	v_mfma_f32_16x16x32_bf16 v[12:15], v[142:145], v[232:235], v[12:15]
	v_mfma_f32_16x16x32_bf16 v[8:11], v[150:153], v[232:235], v[8:11]
	v_mfma_f32_16x16x32_bf16 v[60:63], v[146:149], v[178:181], v[60:63]
	v_mfma_f32_16x16x32_bf16 v[56:59], v[154:157], v[178:181], v[56:59]
	v_mfma_f32_16x16x32_bf16 v[44:47], v[146:149], v[186:189], v[44:47]
	v_mfma_f32_16x16x32_bf16 v[40:43], v[154:157], v[186:189], v[40:43]
	v_mfma_f32_16x16x32_bf16 v[28:31], v[146:149], v[216:219], v[28:31]
	v_mfma_f32_16x16x32_bf16 v[24:27], v[154:157], v[216:219], v[24:27]
	v_mfma_f32_16x16x32_bf16 v[12:15], v[146:149], v[236:239], v[12:15]
	v_mfma_f32_16x16x32_bf16 v[8:11], v[154:157], v[236:239], v[8:11]
	v_mfma_f32_16x16x32_bf16 v[52:55], v[158:161], v[174:177], v[52:55]
	v_mfma_f32_16x16x32_bf16 v[48:51], v[166:169], v[174:177], v[48:51]
	v_mfma_f32_16x16x32_bf16 v[36:39], v[158:161], v[182:185], v[36:39]
	v_mfma_f32_16x16x32_bf16 v[32:35], v[166:169], v[182:185], v[32:35]
	v_mfma_f32_16x16x32_bf16 v[20:23], v[158:161], v[212:215], v[20:23]
	v_mfma_f32_16x16x32_bf16 v[16:19], v[166:169], v[212:215], v[16:19]
	v_mfma_f32_16x16x32_bf16 v[4:7], v[158:161], v[232:235], v[4:7]
	v_mfma_f32_16x16x32_bf16 v[0:3], v[166:169], v[232:235], v[0:3]
	v_mfma_f32_16x16x32_bf16 v[52:55], v[162:165], v[178:181], v[52:55]
	v_mfma_f32_16x16x32_bf16 v[48:51], v[170:173], v[178:181], v[48:51]
	v_mfma_f32_16x16x32_bf16 v[36:39], v[162:165], v[186:189], v[36:39]
	v_mfma_f32_16x16x32_bf16 v[32:35], v[170:173], v[186:189], v[32:35]
	v_mfma_f32_16x16x32_bf16 v[20:23], v[162:165], v[216:219], v[20:23]
	v_mfma_f32_16x16x32_bf16 v[16:19], v[170:173], v[216:219], v[16:19]
	v_mfma_f32_16x16x32_bf16 v[4:7], v[162:165], v[236:239], v[4:7]
	v_mfma_f32_16x16x32_bf16 v[0:3], v[170:173], v[236:239], v[0:3]
	s_setprio 1
	s_barrier
	s_add_i32 s73, 0, 0x18000
	s_add_i32 s76, 0, 0x1c000
	v_add_u32_e32 v154, s73, v140
	v_add_u32_e32 v170, s76, v140
	ds_read_b128 v[142:145], v154
	ds_read_b128 v[146:149], v154 offset:1024
	ds_read_b128 v[150:153], v154 offset:2048
	ds_read_b128 v[154:157], v154 offset:3072
	ds_read_b128 v[158:161], v170
	ds_read_b128 v[162:165], v170 offset:1024
	ds_read_b128 v[166:169], v170 offset:2048
	ds_read_b128 v[170:173], v170 offset:3072
	s_add_u32 s74, s78, 0x40000
	s_addc_u32 s75, s79, 0
	s_mov_b32 m0, s41
	v_lshl_add_u64 v[202:203], s[74:75], 0, v[128:129]
	ds_read_b128 v[174:177], v141 offset:32768
	ds_read_b128 v[178:181], v141 offset:33792
	ds_read_b128 v[182:185], v141 offset:34816
	ds_read_b128 v[186:189], v141 offset:35840
	ds_read_b128 v[212:215], v141 offset:36864
	ds_read_b128 v[216:219], v141 offset:37888
	ds_read_b128 v[232:235], v141 offset:38912
	ds_read_b128 v[236:239], v141 offset:39936
	global_load_lds_dwordx4 v[202:203], off
	v_lshl_add_u64 v[202:203], s[74:75], 0, v[130:131]
	s_mov_b32 m0, s46
	s_nop 0
	global_load_lds_dwordx4 v[202:203], off
	s_waitcnt vmcnt(8)
	s_waitcnt lgkmcnt(0)
	s_barrier
	s_setprio 0
	s_waitcnt lgkmcnt(0)
	v_mfma_f32_16x16x32_bf16 v[124:127], v[142:145], v[174:177], v[124:127]
	v_mfma_f32_16x16x32_bf16 v[120:123], v[150:153], v[174:177], v[120:123]
	v_mfma_f32_16x16x32_bf16 v[108:111], v[142:145], v[182:185], v[108:111]
	v_mfma_f32_16x16x32_bf16 v[104:107], v[150:153], v[182:185], v[104:107]
	v_mfma_f32_16x16x32_bf16 v[92:95], v[142:145], v[212:215], v[92:95]
	v_mfma_f32_16x16x32_bf16 v[88:91], v[150:153], v[212:215], v[88:91]
	v_mfma_f32_16x16x32_bf16 v[76:79], v[142:145], v[232:235], v[76:79]
	v_mfma_f32_16x16x32_bf16 v[72:75], v[150:153], v[232:235], v[72:75]
	v_mfma_f32_16x16x32_bf16 v[124:127], v[146:149], v[178:181], v[124:127]
	v_mfma_f32_16x16x32_bf16 v[120:123], v[154:157], v[178:181], v[120:123]
	v_mfma_f32_16x16x32_bf16 v[108:111], v[146:149], v[186:189], v[108:111]
	v_mfma_f32_16x16x32_bf16 v[104:107], v[154:157], v[186:189], v[104:107]
	v_mfma_f32_16x16x32_bf16 v[92:95], v[146:149], v[216:219], v[92:95]
	v_mfma_f32_16x16x32_bf16 v[88:91], v[154:157], v[216:219], v[88:91]
	v_mfma_f32_16x16x32_bf16 v[76:79], v[146:149], v[236:239], v[76:79]
	v_mfma_f32_16x16x32_bf16 v[72:75], v[154:157], v[236:239], v[72:75]
	v_mfma_f32_16x16x32_bf16 v[116:119], v[158:161], v[174:177], v[116:119]
	v_mfma_f32_16x16x32_bf16 v[112:115], v[166:169], v[174:177], v[112:115]
	v_mfma_f32_16x16x32_bf16 v[100:103], v[158:161], v[182:185], v[100:103]
	v_mfma_f32_16x16x32_bf16 v[96:99], v[166:169], v[182:185], v[96:99]
	v_mfma_f32_16x16x32_bf16 v[84:87], v[158:161], v[212:215], v[84:87]
	v_mfma_f32_16x16x32_bf16 v[80:83], v[166:169], v[212:215], v[80:83]
	v_mfma_f32_16x16x32_bf16 v[68:71], v[158:161], v[232:235], v[68:71]
	v_mfma_f32_16x16x32_bf16 v[64:67], v[166:169], v[232:235], v[64:67]
	v_mfma_f32_16x16x32_bf16 v[116:119], v[162:165], v[178:181], v[116:119]
	v_mfma_f32_16x16x32_bf16 v[112:115], v[170:173], v[178:181], v[112:115]
	v_mfma_f32_16x16x32_bf16 v[100:103], v[162:165], v[186:189], v[100:103]
	v_mfma_f32_16x16x32_bf16 v[96:99], v[170:173], v[186:189], v[96:99]
	v_mfma_f32_16x16x32_bf16 v[84:87], v[162:165], v[216:219], v[84:87]
	v_mfma_f32_16x16x32_bf16 v[80:83], v[170:173], v[216:219], v[80:83]
	v_mfma_f32_16x16x32_bf16 v[68:71], v[162:165], v[236:239], v[68:71]
	v_mfma_f32_16x16x32_bf16 v[64:67], v[170:173], v[236:239], v[64:67]
	s_setprio 1
	s_barrier
; #define PG8_STAGE(bufoff, gbase, voff) do { _Pragma("unroll") for (int _i = 0; _i < 2; ++_i) \
;         __builtin_amdgcn_global_load_lds((const unsigned*)((const char*)(gbase) + (voff)[_i]), (PG8_LAS unsigned*)(lds + (bufoff) + ldsw + _i * 8192), 16, 0, 0); } while (0)
; #define PG8_LDA(dst, b, h) do { _Pragma("unroll") for (int m = 0; m < 4; ++m) _Pragma("unroll") for (int k = 0; k < 2; ++k) dst[m][k] = *(const PG8_LAS bf16x8*)(lds + PG8_SA(b, h) + aoff + m * 2048 + k * 1024); } while (0)
; #define PG8_MMA(ai, bj, At, Bt) do { __builtin_amdgcn_s_setprio(1); _Pragma("unroll") for (int m = 0; m < 4; ++m) _Pragma("unroll") for (int n = 0; n < 2; ++n) _Pragma("unroll") for (int k = 0; k < 2; ++k) \
;         acc[ai][bj][m][n] = __builtin_amdgcn_mfma_f32_16x16x32_bf16(Bt[n][k], At[m][k], acc[ai][bj][m][n], 0, 0, 0); __builtin_amdgcn_s_setprio(0); } while (0)
; #define PG8_WAIT_V(n) asm volatile("s_waitcnt vmcnt(" #n ")" ::: "memory")
; #define PG8_WAIT_L(n) asm volatile("s_waitcnt lgkmcnt(" #n ")" ::: "memory")
; #define PG8_BAR __builtin_amdgcn_s_barrier()
; #define PG8_SCHED __builtin_amdgcn_sched_barrier(0)
; template <class Epi, class Sched, bool ALIGN_EPI = false, bool SP2 = false>
; __device__ __forceinline__ void gemm_phase(PG8_LAS unsigned char* lds, const Gemm g, const Sched& S, const Epi& E, const int tid) {
;     ...
;         for (int t = 0; t < nt; t += 2) {
;     ...
;             PG8_LDA(At, 1, 1); PG8_STAGE(PG8_SB(1, 0), b3, voffB); PG8_STAGE(PG8_SB(1, 1), b3 + hstep, voffB); PG8_STAGE(PG8_SA(1, 0), a3, voffA);
;             PG8_WAIT_V(8); PG8_WAIT_L(0); PG8_BAR; PG8_MMA(1, 0, At, B0); PG8_MMA(1, 1, At, B1); PG8_BAR; PG8_SCHED;
	s_add_i32 s73, s73, s35
	v_lshl_add_u64 v[138:139], v[138:139], 0, s[36:37]
	s_mov_b32 m0, s73
	ds_read_b128 v[174:177], v141 offset:49152
	ds_read_b128 v[178:181], v141 offset:50176
	ds_read_b128 v[182:185], v141 offset:51200
	ds_read_b128 v[186:189], v141 offset:52224
	ds_read_b128 v[212:215], v141 offset:53248
	ds_read_b128 v[216:219], v141 offset:54272
	ds_read_b128 v[232:235], v141 offset:55296
	ds_read_b128 v[236:239], v141 offset:56320
	global_load_lds_dwordx4 v[138:139], off
	s_add_i32 m0, s73, 0x2000
	s_add_u32 s58, s58, 0x40080
	v_lshl_add_u64 v[138:139], v[190:191], 0, s[36:37]
	s_addc_u32 s59, s59, 0
	s_add_i32 s73, s76, s35
	global_load_lds_dwordx4 v[138:139], off
	v_lshl_add_u64 v[138:139], s[58:59], 0, v[192:193]
	s_mov_b32 m0, s73
	s_nop 0
	global_load_lds_dwordx4 v[138:139], off
	v_lshl_add_u64 v[138:139], s[58:59], 0, v[132:133]
	s_add_i32 m0, s73, 0x2000
	s_nop 0
	global_load_lds_dwordx4 v[138:139], off
	v_lshl_add_u64 v[138:139], v[194:195], 0, s[36:37]
	s_mov_b32 m0, s47
	s_nop 0
	global_load_lds_dwordx4 v[138:139], off
	v_lshl_add_u64 v[138:139], v[196:197], 0, s[36:37]
	s_mov_b32 m0, s53
	s_nop 0
	global_load_lds_dwordx4 v[138:139], off
	s_waitcnt vmcnt(8)
	s_waitcnt lgkmcnt(0)
	s_barrier
	s_setprio 0
	s_waitcnt lgkmcnt(0)
	v_mfma_f32_16x16x32_bf16 v[60:63], v[142:145], v[174:177], v[60:63]
	v_mfma_f32_16x16x32_bf16 v[56:59], v[150:153], v[174:177], v[56:59]
	v_mfma_f32_16x16x32_bf16 v[44:47], v[142:145], v[182:185], v[44:47]
	v_mfma_f32_16x16x32_bf16 v[40:43], v[150:153], v[182:185], v[40:43]
	v_mfma_f32_16x16x32_bf16 v[28:31], v[142:145], v[212:215], v[28:31]
	v_mfma_f32_16x16x32_bf16 v[24:27], v[150:153], v[212:215], v[24:27]
	v_mfma_f32_16x16x32_bf16 v[12:15], v[142:145], v[232:235], v[12:15]
	v_mfma_f32_16x16x32_bf16 v[8:11], v[150:153], v[232:235], v[8:11]
	v_mfma_f32_16x16x32_bf16 v[60:63], v[146:149], v[178:181], v[60:63]
	v_mfma_f32_16x16x32_bf16 v[56:59], v[154:157], v[178:181], v[56:59]
	v_mfma_f32_16x16x32_bf16 v[44:47], v[146:149], v[186:189], v[44:47]
	v_mfma_f32_16x16x32_bf16 v[40:43], v[154:157], v[186:189], v[40:43]
	v_mfma_f32_16x16x32_bf16 v[28:31], v[146:149], v[216:219], v[28:31]
	v_mfma_f32_16x16x32_bf16 v[24:27], v[154:157], v[216:219], v[24:27]
	v_mfma_f32_16x16x32_bf16 v[12:15], v[146:149], v[236:239], v[12:15]
	v_mfma_f32_16x16x32_bf16 v[8:11], v[154:157], v[236:239], v[8:11]
	v_mfma_f32_16x16x32_bf16 v[52:55], v[158:161], v[174:177], v[52:55]
	v_mfma_f32_16x16x32_bf16 v[48:51], v[166:169], v[174:177], v[48:51]
	v_mfma_f32_16x16x32_bf16 v[36:39], v[158:161], v[182:185], v[36:39]
	v_mfma_f32_16x16x32_bf16 v[32:35], v[166:169], v[182:185], v[32:35]
	v_mfma_f32_16x16x32_bf16 v[20:23], v[158:161], v[212:215], v[20:23]
	v_mfma_f32_16x16x32_bf16 v[16:19], v[166:169], v[212:215], v[16:19]
	v_mfma_f32_16x16x32_bf16 v[4:7], v[158:161], v[232:235], v[4:7]
	v_mfma_f32_16x16x32_bf16 v[0:3], v[166:169], v[232:235], v[0:3]
	v_mfma_f32_16x16x32_bf16 v[52:55], v[162:165], v[178:181], v[52:55]
	v_mfma_f32_16x16x32_bf16 v[48:51], v[170:173], v[178:181], v[48:51]
	v_mfma_f32_16x16x32_bf16 v[36:39], v[162:165], v[186:189], v[36:39]
	v_mfma_f32_16x16x32_bf16 v[32:35], v[170:173], v[186:189], v[32:35]
	v_mfma_f32_16x16x32_bf16 v[20:23], v[162:165], v[216:219], v[20:23]
	v_mfma_f32_16x16x32_bf16 v[16:19], v[170:173], v[216:219], v[16:19]
	v_mfma_f32_16x16x32_bf16 v[4:7], v[162:165], v[236:239], v[4:7]
	v_mfma_f32_16x16x32_bf16 v[0:3], v[170:173], v[236:239], v[0:3]
	s_setprio 1
	s_barrier
	s_add_i32 s72, s72, 2
	s_add_u32 s44, s44, 0x100
	s_addc_u32 s45, s45, 0
	s_add_u32 s62, s62, 0x100
	s_addc_u32 s71, s71, 0
	s_cmp_gt_u32 s72, 13
	s_cbranch_scc0 .LBB0_38
	s_and_b64 vcc, exec, s[10:11]
	s_mov_b64 s[72:73], 0x20000
	s_cbranch_vccz .LBB0_41
	s_barrier

; #define PG8_STAGE(bufoff, gbase, voff) do { _Pragma("unroll") for (int _i = 0; _i < 2; ++_i) \
;         __builtin_amdgcn_global_load_lds((const unsigned*)((const char*)(gbase) + (voff)[_i]), (PG8_LAS unsigned*)(lds + (bufoff) + ldsw + _i * 8192), 16, 0, 0); } while (0)
; #define PG8_LDA(dst, b, h) do { _Pragma("unroll") for (int m = 0; m < 4; ++m) _Pragma("unroll") for (int k = 0; k < 2; ++k) dst[m][k] = *(const PG8_LAS bf16x8*)(lds + PG8_SA(b, h) + aoff + m * 2048 + k * 1024); } while (0)
; #define PG8_LDB(dst, b, h) do { _Pragma("unroll") for (int n = 0; n < 2; ++n) _Pragma("unroll") for (int k = 0; k < 2; ++k) dst[n][k] = *(const PG8_LAS bf16x8*)(lds + PG8_SB(b, h) + boff + n * 2048 + k * 1024); } while (0)
; #define PG8_MMA(ai, bj, At, Bt) do { __builtin_amdgcn_s_setprio(1); _Pragma("unroll") for (int m = 0; m < 4; ++m) _Pragma("unroll") for (int n = 0; n < 2; ++n) _Pragma("unroll") for (int k = 0; k < 2; ++k) \
;         acc[ai][bj][m][n] = __builtin_amdgcn_mfma_f32_16x16x32_bf16(Bt[n][k], At[m][k], acc[ai][bj][m][n], 0, 0, 0); __builtin_amdgcn_s_setprio(0); } while (0)
; template <class Epi, class Sched, bool ALIGN_EPI = false, bool SP2 = false>
; __device__ __forceinline__ void gemm_phase(PG8_LAS unsigned char* lds, const Gemm g, const Sched& S, const Epi& E, const int tid) {
;     ...
;         const bool has_next = S.next(ui + 1, nxt);
;         const char* nA = has_next ? (const char*)g.A + (size_t)nxt.pm * tstep : cA; const char* nB = has_next ? (const char*)g.Bt + (size_t)nxt.pn * tstep : cB;
;         for (int t = 0; t < nt; t += 2) {
;             const bool last = (t == nt - 2);
;             const char* a1 = cA + (size_t)(t + 1) * kstep;
;             const char* a2 = last ? nA : cA + (size_t)(t + 2) * kstep; const char* b2 = last ? nB : cB + (size_t)(t + 2) * kstep;
;             const char* a3 = a2 + kstep; const char* b3 = b2 + kstep;
;             if (last && has_next) S.a_ready(nxt);
;             if constexpr (SP2) {
;             PG8_LDB(B0, 0, 0); PG8_LDB(B1, 0, 1); PG8_SCHED; PG8_LDA(At, 0, 0); PG8_STAGE(PG8_SA(1, 1), a1 + hstep, voffA);
;             PG8_WAIT_V(8); PG8_WAIT_L(0); PG8_BAR; PG8_MMA(0, 0, At, B0); PG8_MMA(0, 1, At, B1); PG8_BAR; PG8_SCHED;
;             PG8_LDA(At, 0, 1); PG8_STAGE(PG8_SB(0, 0), b2, voffB); PG8_STAGE(PG8_SB(0, 1), b2 + hstep, voffB); PG8_STAGE(PG8_SA(0, 0), a2, voffA);
.LBB0_61:
	s_ashr_i32 s23, s22, 31
	s_lshl_b64 s[44:45], s[22:23], 17
	s_add_u32 s44, s0, s44
	s_addc_u32 s45, s1, s45
	s_and_b64 s[58:59], s[6:7], exec
	s_cselect_b32 s87, s45, s81
	s_cselect_b32 s86, s44, s80
	s_ashr_i32 s21, s20, 31
	s_lshl_b64 s[58:59], s[20:21], 17
	s_add_u32 s58, s2, s58
	s_addc_u32 s59, s26, s59
	s_and_b64 s[70:71], s[6:7], exec
	s_cselect_b32 s85, s59, s83
	s_cselect_b32 s84, s58, s82
	s_add_i32 s62, 0, 0x10000
	s_add_i32 s55, 0, 0x14000
	v_add_u32_e32 v204, s62, v140
	v_add_u32_e32 v205, s55, v140
	ds_read_b128 v[0:3], v204
	ds_read_b128 v[4:7], v204 offset:1024
	ds_read_b128 v[8:11], v204 offset:2048
	ds_read_b128 v[12:15], v204 offset:3072
	ds_read_b128 v[16:19], v205
	ds_read_b128 v[20:23], v205 offset:1024
	ds_read_b128 v[24:27], v205 offset:2048
	ds_read_b128 v[28:31], v205 offset:3072
	v_mov_b64_e32 v[228:229], 0xff
	v_mov_b64_e32 v[200:201], 0x100
	v_mov_b64_e32 v[198:199], 0x1ff
	v_mov_b64_e32 v[252:253], 0x200
	s_add_u32 s72, s80, 0x10080
	s_addc_u32 s73, s81, 0
	s_add_i32 s71, s35, 0xc000
	v_lshl_add_u64 v[64:65], s[72:73], 0, v[128:129]
	s_mov_b32 m0, s71
	s_add_i32 s21, s35, 0xe000
	ds_read_b128 v[32:35], v141
	ds_read_b128 v[36:39], v141 offset:1024
	ds_read_b128 v[40:43], v141 offset:2048
	ds_read_b128 v[44:47], v141 offset:3072
	ds_read_b128 v[48:51], v141 offset:4096
	ds_read_b128 v[52:55], v141 offset:5120
	ds_read_b128 v[56:59], v141 offset:6144
	ds_read_b128 v[60:63], v141 offset:7168
	global_load_lds_dwordx4 v[64:65], off
	v_lshl_add_u64 v[64:65], s[72:73], 0, v[130:131]
	s_mov_b32 m0, s21
	s_nop 0
	global_load_lds_dwordx4 v[64:65], off
	s_waitcnt vmcnt(8)
	s_waitcnt lgkmcnt(0)
	s_barrier
	s_setprio 0
	s_waitcnt lgkmcnt(0)
	v_mfma_f32_16x16x32_bf16 v[64:67], v[0:3], v[32:35], 0
	v_mfma_f32_16x16x32_bf16 v[68:71], v[8:11], v[32:35], 0
	v_mfma_f32_16x16x32_bf16 v[72:75], v[0:3], v[40:43], 0
	v_mfma_f32_16x16x32_bf16 v[76:79], v[8:11], v[40:43], 0
	v_mfma_f32_16x16x32_bf16 v[80:83], v[0:3], v[48:51], 0
	v_mfma_f32_16x16x32_bf16 v[84:87], v[8:11], v[48:51], 0
	v_mfma_f32_16x16x32_bf16 v[88:91], v[0:3], v[56:59], 0
	v_mfma_f32_16x16x32_bf16 v[92:95], v[8:11], v[56:59], 0
	v_mfma_f32_16x16x32_bf16 v[64:67], v[4:7], v[36:39], v[64:67]
	v_mfma_f32_16x16x32_bf16 v[68:71], v[12:15], v[36:39], v[68:71]
	v_mfma_f32_16x16x32_bf16 v[72:75], v[4:7], v[44:47], v[72:75]
	v_mfma_f32_16x16x32_bf16 v[76:79], v[12:15], v[44:47], v[76:79]
	v_mfma_f32_16x16x32_bf16 v[80:83], v[4:7], v[52:55], v[80:83]
	v_mfma_f32_16x16x32_bf16 v[84:87], v[12:15], v[52:55], v[84:87]
	v_mfma_f32_16x16x32_bf16 v[88:91], v[4:7], v[60:63], v[88:91]
	v_mfma_f32_16x16x32_bf16 v[92:95], v[12:15], v[60:63], v[92:95]
	v_mfma_f32_16x16x32_bf16 v[96:99], v[16:19], v[32:35], 0
	v_mfma_f32_16x16x32_bf16 v[32:35], v[24:27], v[32:35], 0
	v_mfma_f32_16x16x32_bf16 v[96:99], v[20:23], v[36:39], v[96:99]
	v_mfma_f32_16x16x32_bf16 v[32:35], v[28:31], v[36:39], v[32:35]
	v_mfma_f32_16x16x32_bf16 v[36:39], v[16:19], v[40:43], 0
	v_mfma_f32_16x16x32_bf16 v[40:43], v[24:27], v[40:43], 0
	v_mfma_f32_16x16x32_bf16 v[36:39], v[20:23], v[44:47], v[36:39]
	v_mfma_f32_16x16x32_bf16 v[40:43], v[28:31], v[44:47], v[40:43]
	v_mfma_f32_16x16x32_bf16 v[44:47], v[16:19], v[48:51], 0
	v_mfma_f32_16x16x32_bf16 v[48:51], v[24:27], v[48:51], 0
	v_mfma_f32_16x16x32_bf16 v[44:47], v[20:23], v[52:55], v[44:47]
	v_mfma_f32_16x16x32_bf16 v[48:51], v[28:31], v[52:55], v[48:51]
	v_mfma_f32_16x16x32_bf16 v[52:55], v[16:19], v[56:59], 0
	v_mfma_f32_16x16x32_bf16 v[56:59], v[24:27], v[56:59], 0
	v_mfma_f32_16x16x32_bf16 v[52:55], v[20:23], v[60:63], v[52:55]
	v_mfma_f32_16x16x32_bf16 v[56:59], v[28:31], v[60:63], v[56:59]
	s_setprio 1
	s_barrier
	s_add_i32 s62, s62, s34
	v_lshl_add_u64 v[138:139], s[82:83], 0, v[192:193]
	s_mov_b64 s[74:75], 0x100
	s_add_i32 s23, s62, 0x2000
	v_lshl_add_u64 v[134:135], v[138:139], 0, s[74:75]
	s_mov_b32 m0, s62
	v_lshl_add_u64 v[190:191], s[82:83], 0, v[132:133]
	s_add_u32 s72, s82, 0x10100
	ds_read_b128 v[60:63], v141 offset:16384
	ds_read_b128 v[100:103], v141 offset:17408
	ds_read_b128 v[104:107], v141 offset:18432
	ds_read_b128 v[108:111], v141 offset:19456
	ds_read_b128 v[112:115], v141 offset:20480
	ds_read_b128 v[116:119], v141 offset:21504
	ds_read_b128 v[120:123], v141 offset:22528
	ds_read_b128 v[124:127], v141 offset:23552
	global_load_lds_dwordx4 v[134:135], off
	v_lshl_add_u64 v[134:135], v[190:191], 0, s[74:75]
	s_mov_b32 m0, s23
	s_addc_u32 s73, s83, 0
	s_add_i32 s55, s55, s34
	global_load_lds_dwordx4 v[134:135], off
	v_lshl_add_u64 v[134:135], s[72:73], 0, v[192:193]
	s_mov_b32 m0, s55
	s_add_i32 s60, s55, 0x2000
	global_load_lds_dwordx4 v[134:135], off
	v_lshl_add_u64 v[134:135], s[72:73], 0, v[132:133]
	s_mov_b32 m0, s60
	v_lshl_add_u64 v[194:195], s[80:81], 0, v[128:129]
	global_load_lds_dwordx4 v[134:135], off
	v_lshl_add_u64 v[134:135], v[194:195], 0, s[74:75]
	s_mov_b32 m0, s35
	v_lshl_add_u64 v[196:197], s[80:81], 0, v[130:131]
	global_load_lds_dwordx4 v[134:135], off
	v_lshl_add_u64 v[134:135], v[196:197], 0, s[74:75]
	s_mov_b32 m0, s38
	s_nop 0
	global_load_lds_dwordx4 v[134:135], off
	s_waitcnt vmcnt(8)
	s_waitcnt lgkmcnt(0)
	s_barrier
; #define PG8_STAGE(bufoff, gbase, voff) do { _Pragma("unroll") for (int _i = 0; _i < 2; ++_i) \
;         __builtin_amdgcn_global_load_lds((const unsigned*)((const char*)(gbase) + (voff)[_i]), (PG8_LAS unsigned*)(lds + (bufoff) + ldsw + _i * 8192), 16, 0, 0); } while (0)
; #define PG8_LDA(dst, b, h) do { _Pragma("unroll") for (int m = 0; m < 4; ++m) _Pragma("unroll") for (int k = 0; k < 2; ++k) dst[m][k] = *(const PG8_LAS bf16x8*)(lds + PG8_SA(b, h) + aoff + m * 2048 + k * 1024); } while (0)
; #define PG8_LDB(dst, b, h) do { _Pragma("unroll") for (int n = 0; n < 2; ++n) _Pragma("unroll") for (int k = 0; k < 2; ++k) dst[n][k] = *(const PG8_LAS bf16x8*)(lds + PG8_SB(b, h) + boff + n * 2048 + k * 1024); } while (0)
; #define PG8_MMA(ai, bj, At, Bt) do { __builtin_amdgcn_s_setprio(1); _Pragma("unroll") for (int m = 0; m < 4; ++m) _Pragma("unroll") for (int n = 0; n < 2; ++n) _Pragma("unroll") for (int k = 0; k < 2; ++k) \
;         acc[ai][bj][m][n] = __builtin_amdgcn_mfma_f32_16x16x32_bf16(Bt[n][k], At[m][k], acc[ai][bj][m][n], 0, 0, 0); __builtin_amdgcn_s_setprio(0); } while (0)
; #define PG8_WAIT_V(n) asm volatile("s_waitcnt vmcnt(" #n ")" ::: "memory")
; #define PG8_WAIT_L(n) asm volatile("s_waitcnt lgkmcnt(" #n ")" ::: "memory")
; #define PG8_BAR __builtin_amdgcn_s_barrier()
; #define PG8_SCHED __builtin_amdgcn_sched_barrier(0)
; template <class Epi, class Sched, bool ALIGN_EPI = false, bool SP2 = false>
; __device__ __forceinline__ void gemm_phase(PG8_LAS unsigned char* lds, const Gemm g, const Sched& S, const Epi& E, const int tid) {
;     ...
;             PG8_WAIT_V(8); PG8_WAIT_L(0); PG8_BAR; PG8_MMA(1, 0, At, B0); PG8_MMA(1, 1, At, B1); PG8_BAR; PG8_SCHED;
;             PG8_LDB(B0, 1, 0); PG8_LDB(B1, 1, 1); PG8_SCHED; PG8_LDA(At, 1, 0); PG8_STAGE(PG8_SA(0, 1), a2 + hstep, voffA);
;             PG8_WAIT_V(8); PG8_WAIT_L(0); PG8_BAR; PG8_MMA(0, 0, At, B0); PG8_MMA(0, 1, At, B1); PG8_BAR; PG8_SCHED;
	s_setprio 0
	s_waitcnt lgkmcnt(0)
	v_mfma_f32_16x16x32_bf16 v[134:137], v[0:3], v[60:63], 0
	v_mfma_f32_16x16x32_bf16 v[146:149], v[0:3], v[104:107], 0
	v_mfma_f32_16x16x32_bf16 v[154:157], v[0:3], v[112:115], 0
	v_mfma_f32_16x16x32_bf16 v[0:3], v[0:3], v[120:123], 0
	v_mfma_f32_16x16x32_bf16 v[134:137], v[4:7], v[100:103], v[134:137]
	v_mfma_f32_16x16x32_bf16 v[146:149], v[4:7], v[108:111], v[146:149]
	v_mfma_f32_16x16x32_bf16 v[154:157], v[4:7], v[116:119], v[154:157]
	v_mfma_f32_16x16x32_bf16 v[0:3], v[4:7], v[124:127], v[0:3]
	v_mfma_f32_16x16x32_bf16 v[4:7], v[8:11], v[120:123], 0
	v_mfma_f32_16x16x32_bf16 v[142:145], v[8:11], v[60:63], 0
	v_mfma_f32_16x16x32_bf16 v[150:153], v[8:11], v[104:107], 0
	v_mfma_f32_16x16x32_bf16 v[158:161], v[8:11], v[112:115], 0
	v_mfma_f32_16x16x32_bf16 v[4:7], v[12:15], v[124:127], v[4:7]
	v_mfma_f32_16x16x32_bf16 v[142:145], v[12:15], v[100:103], v[142:145]
	v_mfma_f32_16x16x32_bf16 v[150:153], v[12:15], v[108:111], v[150:153]
	v_mfma_f32_16x16x32_bf16 v[158:161], v[12:15], v[116:119], v[158:161]
	v_mfma_f32_16x16x32_bf16 v[8:11], v[16:19], v[60:63], 0
	v_mfma_f32_16x16x32_bf16 v[12:15], v[24:27], v[60:63], 0
	v_mfma_f32_16x16x32_bf16 v[8:11], v[20:23], v[100:103], v[8:11]
	v_mfma_f32_16x16x32_bf16 v[12:15], v[28:31], v[100:103], v[12:15]
	v_mfma_f32_16x16x32_bf16 v[60:63], v[16:19], v[104:107], 0
	v_mfma_f32_16x16x32_bf16 v[100:103], v[24:27], v[104:107], 0
	v_mfma_f32_16x16x32_bf16 v[104:107], v[16:19], v[112:115], 0
	v_mfma_f32_16x16x32_bf16 v[16:19], v[16:19], v[120:123], 0
	v_mfma_f32_16x16x32_bf16 v[60:63], v[20:23], v[108:111], v[60:63]
	v_mfma_f32_16x16x32_bf16 v[100:103], v[28:31], v[108:111], v[100:103]
	v_mfma_f32_16x16x32_bf16 v[104:107], v[20:23], v[116:119], v[104:107]
	v_mfma_f32_16x16x32_bf16 v[108:111], v[24:27], v[112:115], 0
	v_mfma_f32_16x16x32_bf16 v[16:19], v[20:23], v[124:127], v[16:19]
	v_mfma_f32_16x16x32_bf16 v[20:23], v[24:27], v[120:123], 0
	v_mfma_f32_16x16x32_bf16 v[108:111], v[28:31], v[116:119], v[108:111]
	v_mfma_f32_16x16x32_bf16 v[20:23], v[28:31], v[124:127], v[20:23]
	s_setprio 1
	s_barrier
	s_add_i32 s74, 0, 0x18000
	s_add_i32 s75, 0, 0x1c000
	v_add_u32_e32 v206, s74, v140
	v_add_u32_e32 v207, s75, v140
	ds_read_b128 v[24:27], v206
	ds_read_b128 v[28:31], v206 offset:1024
	ds_read_b128 v[112:115], v206 offset:2048
	ds_read_b128 v[116:119], v206 offset:3072
	ds_read_b128 v[120:123], v207
	ds_read_b128 v[124:127], v207 offset:1024
	ds_read_b128 v[162:165], v207 offset:2048
	ds_read_b128 v[166:169], v207 offset:3072
	s_add_u32 s72, s80, 0x10100
	s_addc_u32 s73, s81, 0
	s_mov_b32 m0, s40
	v_lshl_add_u64 v[202:203], s[72:73], 0, v[128:129]
	ds_read_b128 v[170:173], v141 offset:32768
	ds_read_b128 v[174:177], v141 offset:33792
	ds_read_b128 v[178:181], v141 offset:34816
	ds_read_b128 v[182:185], v141 offset:35840
	ds_read_b128 v[186:189], v141 offset:36864
	ds_read_b128 v[212:215], v141 offset:37888
	ds_read_b128 v[216:219], v141 offset:38912
	ds_read_b128 v[232:235], v141 offset:39936
	global_load_lds_dwordx4 v[202:203], off
	v_lshl_add_u64 v[202:203], s[72:73], 0, v[130:131]
	s_mov_b32 m0, s41
	s_nop 0
	global_load_lds_dwordx4 v[202:203], off
	s_waitcnt vmcnt(8)
	s_waitcnt lgkmcnt(0)
	s_barrier
	s_setprio 0
	s_waitcnt lgkmcnt(0)
	v_mfma_f32_16x16x32_bf16 v[64:67], v[24:27], v[170:173], v[64:67]
	v_mfma_f32_16x16x32_bf16 v[68:71], v[112:115], v[170:173], v[68:71]
	v_mfma_f32_16x16x32_bf16 v[72:75], v[24:27], v[178:181], v[72:75]
	v_mfma_f32_16x16x32_bf16 v[76:79], v[112:115], v[178:181], v[76:79]
	v_mfma_f32_16x16x32_bf16 v[80:83], v[24:27], v[186:189], v[80:83]
	v_mfma_f32_16x16x32_bf16 v[84:87], v[112:115], v[186:189], v[84:87]
	v_mfma_f32_16x16x32_bf16 v[88:91], v[24:27], v[216:219], v[88:91]
	v_mfma_f32_16x16x32_bf16 v[92:95], v[112:115], v[216:219], v[92:95]
	v_mfma_f32_16x16x32_bf16 v[64:67], v[28:31], v[174:177], v[64:67]
	v_mfma_f32_16x16x32_bf16 v[68:71], v[116:119], v[174:177], v[68:71]
	v_mfma_f32_16x16x32_bf16 v[72:75], v[28:31], v[182:185], v[72:75]
	v_mfma_f32_16x16x32_bf16 v[76:79], v[116:119], v[182:185], v[76:79]
	v_mfma_f32_16x16x32_bf16 v[80:83], v[28:31], v[212:215], v[80:83]
	v_mfma_f32_16x16x32_bf16 v[84:87], v[116:119], v[212:215], v[84:87]
	v_mfma_f32_16x16x32_bf16 v[88:91], v[28:31], v[232:235], v[88:91]
	v_mfma_f32_16x16x32_bf16 v[92:95], v[116:119], v[232:235], v[92:95]
	v_mfma_f32_16x16x32_bf16 v[96:99], v[120:123], v[170:173], v[96:99]
	v_mfma_f32_16x16x32_bf16 v[32:35], v[162:165], v[170:173], v[32:35]
	v_mfma_f32_16x16x32_bf16 v[36:39], v[120:123], v[178:181], v[36:39]
	v_mfma_f32_16x16x32_bf16 v[40:43], v[162:165], v[178:181], v[40:43]
	v_mfma_f32_16x16x32_bf16 v[44:47], v[120:123], v[186:189], v[44:47]
	v_mfma_f32_16x16x32_bf16 v[48:51], v[162:165], v[186:189], v[48:51]
	v_mfma_f32_16x16x32_bf16 v[52:55], v[120:123], v[216:219], v[52:55]
	v_mfma_f32_16x16x32_bf16 v[56:59], v[162:165], v[216:219], v[56:59]
	v_mfma_f32_16x16x32_bf16 v[96:99], v[124:127], v[174:177], v[96:99]
	v_mfma_f32_16x16x32_bf16 v[32:35], v[166:169], v[174:177], v[32:35]
	v_mfma_f32_16x16x32_bf16 v[36:39], v[124:127], v[182:185], v[36:39]
	v_mfma_f32_16x16x32_bf16 v[40:43], v[166:169], v[182:185], v[40:43]
	v_mfma_f32_16x16x32_bf16 v[44:47], v[124:127], v[212:215], v[44:47]
	v_mfma_f32_16x16x32_bf16 v[48:51], v[166:169], v[212:215], v[48:51]
	v_mfma_f32_16x16x32_bf16 v[52:55], v[124:127], v[232:235], v[52:55]
	v_mfma_f32_16x16x32_bf16 v[56:59], v[166:169], v[232:235], v[56:59]
	s_setprio 1
	s_barrier
; #define PG8_STAGE(bufoff, gbase, voff) do { _Pragma("unroll") for (int _i = 0; _i < 2; ++_i) \
;         __builtin_amdgcn_global_load_lds((const unsigned*)((const char*)(gbase) + (voff)[_i]), (PG8_LAS unsigned*)(lds + (bufoff) + ldsw + _i * 8192), 16, 0, 0); } while (0)
; #define PG8_LDA(dst, b, h) do { _Pragma("unroll") for (int m = 0; m < 4; ++m) _Pragma("unroll") for (int k = 0; k < 2; ++k) dst[m][k] = *(const PG8_LAS bf16x8*)(lds + PG8_SA(b, h) + aoff + m * 2048 + k * 1024); } while (0)
; #define PG8_LDB(dst, b, h) do { _Pragma("unroll") for (int n = 0; n < 2; ++n) _Pragma("unroll") for (int k = 0; k < 2; ++k) dst[n][k] = *(const PG8_LAS bf16x8*)(lds + PG8_SB(b, h) + boff + n * 2048 + k * 1024); } while (0)
; #define PG8_MMA(ai, bj, At, Bt) do { __builtin_amdgcn_s_setprio(1); _Pragma("unroll") for (int m = 0; m < 4; ++m) _Pragma("unroll") for (int n = 0; n < 2; ++n) _Pragma("unroll") for (int k = 0; k < 2; ++k) \
;         acc[ai][bj][m][n] = __builtin_amdgcn_mfma_f32_16x16x32_bf16(Bt[n][k], At[m][k], acc[ai][bj][m][n], 0, 0, 0); __builtin_amdgcn_s_setprio(0); } while (0)
; #define PG8_WAIT_V(n) asm volatile("s_waitcnt vmcnt(" #n ")" ::: "memory")
; #define PG8_WAIT_L(n) asm volatile("s_waitcnt lgkmcnt(" #n ")" ::: "memory")
; #define PG8_BAR __builtin_amdgcn_s_barrier()
; #define PG8_SCHED __builtin_amdgcn_sched_barrier(0)
; template <class Epi, class Sched, bool ALIGN_EPI = false, bool SP2 = false>
; __device__ __forceinline__ void gemm_phase(PG8_LAS unsigned char* lds, const Gemm g, const Sched& S, const Epi& E, const int tid) {
;     ...
;             PG8_LDB(B0, 0, 0); PG8_LDB(B1, 0, 1); PG8_SCHED; PG8_LDA(At, 0, 0); PG8_STAGE(PG8_SA(1, 1), a1 + hstep, voffA);
;     ...
;             PG8_LDA(At, 1, 1); PG8_STAGE(PG8_SB(1, 0), b3, voffB); PG8_STAGE(PG8_SB(1, 1), b3 + hstep, voffB); PG8_STAGE(PG8_SA(1, 0), a3, voffA);
;             PG8_WAIT_V(8); PG8_WAIT_L(0); PG8_BAR; PG8_MMA(1, 0, At, B0); PG8_MMA(1, 1, At, B1); PG8_BAR; PG8_SCHED;
	s_add_i32 s74, s74, s34
	s_mov_b64 s[88:89], 0x180
	s_add_i32 s70, s74, 0x2000
	v_lshl_add_u64 v[138:139], v[138:139], 0, s[88:89]
	s_mov_b32 m0, s74
	s_add_u32 s76, s82, 0x10180
	ds_read_b128 v[170:173], v141 offset:49152
	ds_read_b128 v[174:177], v141 offset:50176
	ds_read_b128 v[178:181], v141 offset:51200
	ds_read_b128 v[182:185], v141 offset:52224
	ds_read_b128 v[186:189], v141 offset:53248
	ds_read_b128 v[212:215], v141 offset:54272
	ds_read_b128 v[216:219], v141 offset:55296
	ds_read_b128 v[232:235], v141 offset:56320
	global_load_lds_dwordx4 v[138:139], off
	v_lshl_add_u64 v[138:139], v[190:191], 0, s[88:89]
	s_mov_b32 m0, s70
	s_addc_u32 s77, s83, 0
	s_add_i32 s72, s75, s34
	global_load_lds_dwordx4 v[138:139], off
	v_lshl_add_u64 v[138:139], s[76:77], 0, v[192:193]
	s_mov_b32 m0, s72
	s_add_i32 s73, s72, 0x2000
	global_load_lds_dwordx4 v[138:139], off
	v_lshl_add_u64 v[138:139], s[76:77], 0, v[132:133]
	s_mov_b32 m0, s73
	s_nop 0
	global_load_lds_dwordx4 v[138:139], off
	v_lshl_add_u64 v[138:139], v[194:195], 0, s[88:89]
	s_mov_b32 m0, s46
	s_nop 0
	global_load_lds_dwordx4 v[138:139], off
	v_lshl_add_u64 v[138:139], v[196:197], 0, s[88:89]
	s_mov_b32 m0, s47
	s_nop 0
	global_load_lds_dwordx4 v[138:139], off
	s_waitcnt vmcnt(8)
	s_waitcnt lgkmcnt(0)
	s_barrier
	s_setprio 0
	s_waitcnt lgkmcnt(0)
	v_mfma_f32_16x16x32_bf16 v[0:3], v[24:27], v[216:219], v[0:3]
	v_mfma_f32_16x16x32_bf16 v[4:7], v[112:115], v[216:219], v[4:7]
	v_mfma_f32_16x16x32_bf16 v[134:137], v[24:27], v[170:173], v[134:137]
	v_mfma_f32_16x16x32_bf16 v[142:145], v[112:115], v[170:173], v[142:145]
	v_mfma_f32_16x16x32_bf16 v[146:149], v[24:27], v[178:181], v[146:149]
	v_mfma_f32_16x16x32_bf16 v[150:153], v[112:115], v[178:181], v[150:153]
	v_mfma_f32_16x16x32_bf16 v[154:157], v[24:27], v[186:189], v[154:157]
	v_mfma_f32_16x16x32_bf16 v[158:161], v[112:115], v[186:189], v[158:161]
	v_mfma_f32_16x16x32_bf16 v[0:3], v[28:31], v[232:235], v[0:3]
	v_mfma_f32_16x16x32_bf16 v[4:7], v[116:119], v[232:235], v[4:7]
	v_mfma_f32_16x16x32_bf16 v[134:137], v[28:31], v[174:177], v[134:137]
	v_mfma_f32_16x16x32_bf16 v[142:145], v[116:119], v[174:177], v[142:145]
	v_mfma_f32_16x16x32_bf16 v[146:149], v[28:31], v[182:185], v[146:149]
	v_mfma_f32_16x16x32_bf16 v[150:153], v[116:119], v[182:185], v[150:153]
	v_mfma_f32_16x16x32_bf16 v[154:157], v[28:31], v[212:215], v[154:157]
	v_mfma_f32_16x16x32_bf16 v[158:161], v[116:119], v[212:215], v[158:161]
	v_mfma_f32_16x16x32_bf16 v[8:11], v[120:123], v[170:173], v[8:11]
	v_mfma_f32_16x16x32_bf16 v[12:15], v[162:165], v[170:173], v[12:15]
	v_mfma_f32_16x16x32_bf16 v[24:27], v[120:123], v[178:181], v[60:63]
	v_mfma_f32_16x16x32_bf16 v[28:31], v[162:165], v[178:181], v[100:103]
	v_mfma_f32_16x16x32_bf16 v[60:63], v[120:123], v[186:189], v[104:107]
	v_mfma_f32_16x16x32_bf16 v[100:103], v[162:165], v[186:189], v[108:111]
	v_mfma_f32_16x16x32_bf16 v[16:19], v[120:123], v[216:219], v[16:19]
	v_mfma_f32_16x16x32_bf16 v[20:23], v[162:165], v[216:219], v[20:23]
	v_mfma_f32_16x16x32_bf16 v[8:11], v[124:127], v[174:177], v[8:11]
	v_mfma_f32_16x16x32_bf16 v[12:15], v[166:169], v[174:177], v[12:15]
	v_mfma_f32_16x16x32_bf16 v[24:27], v[124:127], v[182:185], v[24:27]
	v_mfma_f32_16x16x32_bf16 v[28:31], v[166:169], v[182:185], v[28:31]
	v_mfma_f32_16x16x32_bf16 v[60:63], v[124:127], v[212:215], v[60:63]
	v_mfma_f32_16x16x32_bf16 v[100:103], v[166:169], v[212:215], v[100:103]
	v_mfma_f32_16x16x32_bf16 v[16:19], v[124:127], v[232:235], v[16:19]
	v_mfma_f32_16x16x32_bf16 v[20:23], v[166:169], v[232:235], v[20:23]
	s_setprio 1
	s_barrier
	ds_read_b128 v[104:107], v204
	ds_read_b128 v[108:111], v204 offset:1024
	ds_read_b128 v[112:115], v204 offset:2048
	ds_read_b128 v[116:119], v204 offset:3072
	ds_read_b128 v[120:123], v205
	ds_read_b128 v[124:127], v205 offset:1024
	ds_read_b128 v[162:165], v205 offset:2048
	ds_read_b128 v[166:169], v205 offset:3072
	s_add_u32 s76, s80, 0x10180
	s_addc_u32 s77, s81, 0
	s_mov_b32 m0, s71
	v_lshl_add_u64 v[138:139], s[76:77], 0, v[128:129]
	ds_read_b128 v[170:173], v141
	ds_read_b128 v[174:177], v141 offset:1024
	ds_read_b128 v[178:181], v141 offset:2048
	ds_read_b128 v[182:185], v141 offset:3072
	ds_read_b128 v[186:189], v141 offset:4096
	ds_read_b128 v[212:215], v141 offset:5120
	ds_read_b128 v[216:219], v141 offset:6144
	ds_read_b128 v[232:235], v141 offset:7168
	global_load_lds_dwordx4 v[138:139], off
	v_lshl_add_u64 v[138:139], s[76:77], 0, v[130:131]
	s_mov_b32 m0, s21
	s_nop 0
	global_load_lds_dwordx4 v[138:139], off
	s_waitcnt vmcnt(8)
	s_waitcnt lgkmcnt(0)
	s_barrier
; #define PG8_STAGE(bufoff, gbase, voff) do { _Pragma("unroll") for (int _i = 0; _i < 2; ++_i) \
;         __builtin_amdgcn_global_load_lds((const unsigned*)((const char*)(gbase) + (voff)[_i]), (PG8_LAS unsigned*)(lds + (bufoff) + ldsw + _i * 8192), 16, 0, 0); } while (0)
; #define PG8_LDA(dst, b, h) do { _Pragma("unroll") for (int m = 0; m < 4; ++m) _Pragma("unroll") for (int k = 0; k < 2; ++k) dst[m][k] = *(const PG8_LAS bf16x8*)(lds + PG8_SA(b, h) + aoff + m * 2048 + k * 1024); } while (0)
; #define PG8_MMA(ai, bj, At, Bt) do { __builtin_amdgcn_s_setprio(1); _Pragma("unroll") for (int m = 0; m < 4; ++m) _Pragma("unroll") for (int n = 0; n < 2; ++n) _Pragma("unroll") for (int k = 0; k < 2; ++k) \
;         acc[ai][bj][m][n] = __builtin_amdgcn_mfma_f32_16x16x32_bf16(Bt[n][k], At[m][k], acc[ai][bj][m][n], 0, 0, 0); __builtin_amdgcn_s_setprio(0); } while (0)
; #define PG8_WAIT_V(n) asm volatile("s_waitcnt vmcnt(" #n ")" ::: "memory")
; #define PG8_WAIT_L(n) asm volatile("s_waitcnt lgkmcnt(" #n ")" ::: "memory")
; #define PG8_BAR __builtin_amdgcn_s_barrier()
; #define PG8_SCHED __builtin_amdgcn_sched_barrier(0)
; template <class Epi, class Sched, bool ALIGN_EPI = false, bool SP2 = false>
; __device__ __forceinline__ void gemm_phase(PG8_LAS unsigned char* lds, const Gemm g, const Sched& S, const Epi& E, const int tid) {
;     ...
;             PG8_WAIT_V(8); PG8_WAIT_L(0); PG8_BAR; PG8_MMA(0, 0, At, B0); PG8_MMA(0, 1, At, B1); PG8_BAR; PG8_SCHED;
;             PG8_LDA(At, 0, 1); PG8_STAGE(PG8_SB(0, 0), b2, voffB); PG8_STAGE(PG8_SB(0, 1), b2 + hstep, voffB); PG8_STAGE(PG8_SA(0, 0), a2, voffA);
;             PG8_WAIT_V(8); PG8_WAIT_L(0); PG8_BAR; PG8_MMA(1, 0, At, B0); PG8_MMA(1, 1, At, B1); PG8_BAR; PG8_SCHED;
	s_setprio 0
	s_waitcnt lgkmcnt(0)
	v_mfma_f32_16x16x32_bf16 v[64:67], v[104:107], v[170:173], v[64:67]
	v_mfma_f32_16x16x32_bf16 v[68:71], v[112:115], v[170:173], v[68:71]
	v_mfma_f32_16x16x32_bf16 v[72:75], v[104:107], v[178:181], v[72:75]
	v_mfma_f32_16x16x32_bf16 v[76:79], v[112:115], v[178:181], v[76:79]
	v_mfma_f32_16x16x32_bf16 v[80:83], v[104:107], v[186:189], v[80:83]
	v_mfma_f32_16x16x32_bf16 v[84:87], v[112:115], v[186:189], v[84:87]
	v_mfma_f32_16x16x32_bf16 v[88:91], v[104:107], v[216:219], v[88:91]
	v_mfma_f32_16x16x32_bf16 v[64:67], v[108:111], v[174:177], v[64:67]
	v_mfma_f32_16x16x32_bf16 v[68:71], v[116:119], v[174:177], v[68:71]
	v_mfma_f32_16x16x32_bf16 v[72:75], v[108:111], v[182:185], v[72:75]
	v_mfma_f32_16x16x32_bf16 v[76:79], v[116:119], v[182:185], v[76:79]
	v_mfma_f32_16x16x32_bf16 v[80:83], v[108:111], v[212:215], v[80:83]
	v_mfma_f32_16x16x32_bf16 v[84:87], v[116:119], v[212:215], v[84:87]
	v_mfma_f32_16x16x32_bf16 v[236:239], v[108:111], v[232:235], v[88:91]
	v_mfma_f32_16x16x32_bf16 v[88:91], v[112:115], v[216:219], v[92:95]
	v_mfma_f32_16x16x32_bf16 v[240:243], v[116:119], v[232:235], v[88:91]
	v_mfma_f32_16x16x32_bf16 v[88:91], v[120:123], v[170:173], v[96:99]
	v_mfma_f32_16x16x32_bf16 v[32:35], v[162:165], v[170:173], v[32:35]
	v_mfma_f32_16x16x32_bf16 v[36:39], v[120:123], v[178:181], v[36:39]
	v_mfma_f32_16x16x32_bf16 v[40:43], v[162:165], v[178:181], v[40:43]
	v_mfma_f32_16x16x32_bf16 v[44:47], v[120:123], v[186:189], v[44:47]
	v_mfma_f32_16x16x32_bf16 v[48:51], v[162:165], v[186:189], v[48:51]
	v_mfma_f32_16x16x32_bf16 v[52:55], v[120:123], v[216:219], v[52:55]
	v_mfma_f32_16x16x32_bf16 v[56:59], v[162:165], v[216:219], v[56:59]
	v_mfma_f32_16x16x32_bf16 v[96:99], v[124:127], v[174:177], v[88:91]
	v_mfma_f32_16x16x32_bf16 v[32:35], v[166:169], v[174:177], v[32:35]
	v_mfma_f32_16x16x32_bf16 v[36:39], v[124:127], v[182:185], v[36:39]
	v_mfma_f32_16x16x32_bf16 v[40:43], v[166:169], v[182:185], v[40:43]
	v_mfma_f32_16x16x32_bf16 v[44:47], v[124:127], v[212:215], v[44:47]
	v_mfma_f32_16x16x32_bf16 v[48:51], v[166:169], v[212:215], v[48:51]
	v_mfma_f32_16x16x32_bf16 v[52:55], v[124:127], v[232:235], v[52:55]
	v_mfma_f32_16x16x32_bf16 v[56:59], v[166:169], v[232:235], v[56:59]
	s_setprio 1
	s_barrier
	s_mov_b32 m0, s62
	v_lshl_add_u64 v[138:139], s[84:85], 0, v[192:193]
	s_add_u32 s76, s84, 0x10000
	ds_read_b128 v[88:91], v141 offset:16384
	ds_read_b128 v[92:95], v141 offset:17408
	ds_read_b128 v[170:173], v141 offset:18432
	ds_read_b128 v[174:177], v141 offset:19456
	ds_read_b128 v[178:181], v141 offset:20480
	ds_read_b128 v[182:185], v141 offset:21504
	ds_read_b128 v[186:189], v141 offset:22528
	ds_read_b128 v[212:215], v141 offset:23552
	global_load_lds_dwordx4 v[138:139], off
	v_lshl_add_u64 v[190:191], s[84:85], 0, v[132:133]
	s_mov_b32 m0, s23
	s_addc_u32 s77, s85, 0
	global_load_lds_dwordx4 v[190:191], off
	v_lshl_add_u64 v[194:195], s[76:77], 0, v[192:193]
	s_mov_b32 m0, s55
	v_lshl_add_u64 v[220:221], s[86:87], 0, v[128:129]
	global_load_lds_dwordx4 v[194:195], off
	v_lshl_add_u64 v[194:195], s[76:77], 0, v[132:133]
	s_mov_b32 m0, s60
	v_lshl_add_u64 v[230:231], s[86:87], 0, v[130:131]
	global_load_lds_dwordx4 v[194:195], off
	s_mov_b32 m0, s35
	s_nop 0
	global_load_lds_dwordx4 v[220:221], off
	s_mov_b32 m0, s38
	s_nop 0
	global_load_lds_dwordx4 v[230:231], off
	s_waitcnt vmcnt(8)
	s_waitcnt lgkmcnt(0)
	s_barrier
	s_setprio 0
	s_waitcnt lgkmcnt(0)
	v_mfma_f32_16x16x32_bf16 v[0:3], v[104:107], v[186:189], v[0:3]
	v_mfma_f32_16x16x32_bf16 v[4:7], v[112:115], v[186:189], v[4:7]
	v_mfma_f32_16x16x32_bf16 v[134:137], v[104:107], v[88:91], v[134:137]
	v_mfma_f32_16x16x32_bf16 v[142:145], v[112:115], v[88:91], v[142:145]
	v_mfma_f32_16x16x32_bf16 v[146:149], v[104:107], v[170:173], v[146:149]
	v_mfma_f32_16x16x32_bf16 v[150:153], v[112:115], v[170:173], v[150:153]
	v_mfma_f32_16x16x32_bf16 v[154:157], v[104:107], v[178:181], v[154:157]
	v_mfma_f32_16x16x32_bf16 v[158:161], v[112:115], v[178:181], v[158:161]
	v_mfma_f32_16x16x32_bf16 v[0:3], v[108:111], v[212:215], v[0:3]
	v_mfma_f32_16x16x32_bf16 v[4:7], v[116:119], v[212:215], v[4:7]
	v_mfma_f32_16x16x32_bf16 v[134:137], v[108:111], v[92:95], v[134:137]
	v_mfma_f32_16x16x32_bf16 v[142:145], v[116:119], v[92:95], v[142:145]
	v_mfma_f32_16x16x32_bf16 v[146:149], v[108:111], v[174:177], v[146:149]
	v_mfma_f32_16x16x32_bf16 v[150:153], v[116:119], v[174:177], v[150:153]
	v_mfma_f32_16x16x32_bf16 v[154:157], v[108:111], v[182:185], v[154:157]
	v_mfma_f32_16x16x32_bf16 v[158:161], v[116:119], v[182:185], v[158:161]
	v_mfma_f32_16x16x32_bf16 v[8:11], v[120:123], v[88:91], v[8:11]
	v_mfma_f32_16x16x32_bf16 v[216:219], v[124:127], v[92:95], v[8:11]
	v_mfma_f32_16x16x32_bf16 v[8:11], v[162:165], v[88:91], v[12:15]
	v_mfma_f32_16x16x32_bf16 v[232:235], v[166:169], v[92:95], v[8:11]
	v_mfma_f32_16x16x32_bf16 v[8:11], v[120:123], v[170:173], v[24:27]
	v_mfma_f32_16x16x32_bf16 v[244:247], v[124:127], v[174:177], v[8:11]
	v_mfma_f32_16x16x32_bf16 v[8:11], v[162:165], v[170:173], v[28:31]
	v_mfma_f32_16x16x32_bf16 v[170:173], v[166:169], v[174:177], v[8:11]
	v_mfma_f32_16x16x32_bf16 v[8:11], v[120:123], v[178:181], v[60:63]
	v_mfma_f32_16x16x32_bf16 v[174:177], v[124:127], v[182:185], v[8:11]
	v_mfma_f32_16x16x32_bf16 v[8:11], v[162:165], v[178:181], v[100:103]
	v_mfma_f32_16x16x32_bf16 v[178:181], v[166:169], v[182:185], v[8:11]
	v_mfma_f32_16x16x32_bf16 v[8:11], v[120:123], v[186:189], v[16:19]
	v_mfma_f32_16x16x32_bf16 v[182:185], v[124:127], v[212:215], v[8:11]
	v_mfma_f32_16x16x32_bf16 v[8:11], v[162:165], v[186:189], v[20:23]
	v_mfma_f32_16x16x32_bf16 v[162:165], v[166:169], v[212:215], v[8:11]
	s_setprio 1
	s_barrier
; #define PG8_STAGE(bufoff, gbase, voff) do { _Pragma("unroll") for (int _i = 0; _i < 2; ++_i) \
;         __builtin_amdgcn_global_load_lds((const unsigned*)((const char*)(gbase) + (voff)[_i]), (PG8_LAS unsigned*)(lds + (bufoff) + ldsw + _i * 8192), 16, 0, 0); } while (0)
; #define PG8_LDA(dst, b, h) do { _Pragma("unroll") for (int m = 0; m < 4; ++m) _Pragma("unroll") for (int k = 0; k < 2; ++k) dst[m][k] = *(const PG8_LAS bf16x8*)(lds + PG8_SA(b, h) + aoff + m * 2048 + k * 1024); } while (0)
; #define PG8_LDB(dst, b, h) do { _Pragma("unroll") for (int n = 0; n < 2; ++n) _Pragma("unroll") for (int k = 0; k < 2; ++k) dst[n][k] = *(const PG8_LAS bf16x8*)(lds + PG8_SB(b, h) + boff + n * 2048 + k * 1024); } while (0)
; #define PG8_MMA(ai, bj, At, Bt) do { __builtin_amdgcn_s_setprio(1); _Pragma("unroll") for (int m = 0; m < 4; ++m) _Pragma("unroll") for (int n = 0; n < 2; ++n) _Pragma("unroll") for (int k = 0; k < 2; ++k) \
;         acc[ai][bj][m][n] = __builtin_amdgcn_mfma_f32_16x16x32_bf16(Bt[n][k], At[m][k], acc[ai][bj][m][n], 0, 0, 0); __builtin_amdgcn_s_setprio(0); } while (0)
; #define PG8_WAIT_V(n) asm volatile("s_waitcnt vmcnt(" #n ")" ::: "memory")
; #define PG8_WAIT_L(n) asm volatile("s_waitcnt lgkmcnt(" #n ")" ::: "memory")
; #define PG8_BAR __builtin_amdgcn_s_barrier()
; #define PG8_SCHED __builtin_amdgcn_sched_barrier(0)
; template <class Epi, class Sched, bool ALIGN_EPI = false, bool SP2 = false>
; __device__ __forceinline__ void gemm_phase(PG8_LAS unsigned char* lds, const Gemm g, const Sched& S, const Epi& E, const int tid) {
;     ...
;             PG8_LDB(B0, 1, 0); PG8_LDB(B1, 1, 1); PG8_SCHED; PG8_LDA(At, 1, 0); PG8_STAGE(PG8_SA(0, 1), a2 + hstep, voffA);
;             PG8_WAIT_V(8); PG8_WAIT_L(0); PG8_BAR; PG8_MMA(0, 0, At, B0); PG8_MMA(0, 1, At, B1); PG8_BAR; PG8_SCHED;
;             PG8_LDA(At, 1, 1); PG8_STAGE(PG8_SB(1, 0), b3, voffB); PG8_STAGE(PG8_SB(1, 1), b3 + hstep, voffB); PG8_STAGE(PG8_SA(1, 0), a3, voffA);
;             PG8_WAIT_V(8); PG8_WAIT_L(0); PG8_BAR; PG8_MMA(1, 0, At, B0); PG8_MMA(1, 1, At, B1); PG8_BAR; PG8_SCHED;
;     ...
;         if constexpr (ALIGN_EPI) { if (wr == 0) PG8_BAR; }
	s_nop 4
	ds_read_b128 v[8:11], v206
	ds_read_b128 v[12:15], v206 offset:1024
	ds_read_b128 v[16:19], v206 offset:2048
	ds_read_b128 v[20:23], v206 offset:3072
	ds_read_b128 v[166:169], v207
	ds_read_b128 v[186:189], v207 offset:1024
	ds_read_b128 v[212:215], v207 offset:2048
	ds_read_b128 v[248:251], v207 offset:3072
	s_add_u32 s76, s86, 0x10000
	s_addc_u32 s77, s87, 0
	s_mov_b32 m0, s40
	v_lshl_add_u64 v[88:89], s[76:77], 0, v[128:129]
	ds_read_b128 v[24:27], v141 offset:32768
	ds_read_b128 v[28:31], v141 offset:33792
	ds_read_b128 v[60:63], v141 offset:34816
	ds_read_b128 v[100:103], v141 offset:35840
	ds_read_b128 v[224:227], v141 offset:36864
	ds_read_b128 v[194:197], v141 offset:37888
	ds_read_b128 v[202:205], v141 offset:38912
	ds_read_b128 v[206:209], v141 offset:39936
	global_load_lds_dwordx4 v[88:89], off
	v_lshl_add_u64 v[88:89], s[76:77], 0, v[130:131]
	s_mov_b32 m0, s41
	s_nop 0
	global_load_lds_dwordx4 v[88:89], off
	s_waitcnt vmcnt(8)
	s_waitcnt lgkmcnt(0)
	s_barrier
	s_setprio 0
	s_waitcnt lgkmcnt(0)
	v_mfma_f32_16x16x32_bf16 v[64:67], v[8:11], v[24:27], v[64:67]
	v_mfma_f32_16x16x32_bf16 v[124:127], v[12:15], v[28:31], v[64:67]
	v_mfma_f32_16x16x32_bf16 v[64:67], v[16:19], v[24:27], v[68:71]
	v_mfma_f32_16x16x32_bf16 v[120:123], v[20:23], v[28:31], v[64:67]
	v_mfma_f32_16x16x32_bf16 v[64:67], v[8:11], v[60:63], v[72:75]
	v_mfma_f32_16x16x32_bf16 v[108:111], v[12:15], v[100:103], v[64:67]
	v_mfma_f32_16x16x32_bf16 v[64:67], v[16:19], v[60:63], v[76:79]
	v_mfma_f32_16x16x32_bf16 v[104:107], v[20:23], v[100:103], v[64:67]
	v_mfma_f32_16x16x32_bf16 v[64:67], v[8:11], v[224:227], v[80:83]
	v_mfma_f32_16x16x32_bf16 v[92:95], v[12:15], v[194:197], v[64:67]
	v_mfma_f32_16x16x32_bf16 v[64:67], v[16:19], v[224:227], v[84:87]
	v_mfma_f32_16x16x32_bf16 v[88:91], v[20:23], v[194:197], v[64:67]
	v_mfma_f32_16x16x32_bf16 v[64:67], v[8:11], v[202:205], v[236:239]
	v_mfma_f32_16x16x32_bf16 v[76:79], v[12:15], v[206:209], v[64:67]
	v_mfma_f32_16x16x32_bf16 v[64:67], v[16:19], v[202:205], v[240:243]
	v_mfma_f32_16x16x32_bf16 v[72:75], v[20:23], v[206:209], v[64:67]
	v_mfma_f32_16x16x32_bf16 v[64:67], v[166:169], v[24:27], v[96:99]
	v_mfma_f32_16x16x32_bf16 v[24:27], v[212:215], v[24:27], v[32:35]
	v_mfma_f32_16x16x32_bf16 v[116:119], v[248:251], v[28:31], v[24:27]
	v_mfma_f32_16x16x32_bf16 v[24:27], v[166:169], v[60:63], v[36:39]
	v_mfma_f32_16x16x32_bf16 v[96:99], v[186:189], v[100:103], v[24:27]
	v_mfma_f32_16x16x32_bf16 v[24:27], v[212:215], v[60:63], v[40:43]
	v_mfma_f32_16x16x32_bf16 v[100:103], v[248:251], v[100:103], v[24:27]
	v_mfma_f32_16x16x32_bf16 v[24:27], v[166:169], v[224:227], v[44:47]
	v_mfma_f32_16x16x32_bf16 v[80:83], v[186:189], v[194:197], v[24:27]
	v_mfma_f32_16x16x32_bf16 v[24:27], v[212:215], v[224:227], v[48:51]
	v_mfma_f32_16x16x32_bf16 v[84:87], v[248:251], v[194:197], v[24:27]
	v_mfma_f32_16x16x32_bf16 v[24:27], v[166:169], v[202:205], v[52:55]
	v_mfma_f32_16x16x32_bf16 v[60:63], v[186:189], v[206:209], v[24:27]
	v_mfma_f32_16x16x32_bf16 v[24:27], v[212:215], v[202:205], v[56:59]
	v_mfma_f32_16x16x32_bf16 v[112:115], v[186:189], v[28:31], v[64:67]
	v_mfma_f32_16x16x32_bf16 v[64:67], v[248:251], v[206:209], v[24:27]
	s_setprio 1
	s_barrier
	s_mov_b32 m0, s74
	s_nop 2
	v_lshl_add_u64 v[24:25], v[138:139], 0, s[36:37]
	ds_read_b128 v[32:35], v141 offset:49152
	ds_read_b128 v[36:39], v141 offset:50176
	ds_read_b128 v[194:197], v141 offset:51200
	ds_read_b128 v[202:205], v141 offset:52224
	ds_read_b128 v[206:209], v141 offset:53248
	ds_read_b128 v[224:227], v141 offset:54272
	ds_read_b128 v[236:239], v141 offset:55296
	ds_read_b128 v[240:243], v141 offset:56320
	global_load_lds_dwordx4 v[24:25], off
	s_mov_b32 m0, s70
	s_add_u32 s70, s84, 0x10080
	v_lshl_add_u64 v[24:25], v[190:191], 0, s[36:37]
	s_addc_u32 s71, s85, 0
	global_load_lds_dwordx4 v[24:25], off
	v_lshl_add_u64 v[24:25], s[70:71], 0, v[192:193]
	s_mov_b32 m0, s72
	s_nop 0
	global_load_lds_dwordx4 v[24:25], off
	v_lshl_add_u64 v[24:25], s[70:71], 0, v[132:133]
	s_mov_b32 m0, s73
	s_nop 0
	global_load_lds_dwordx4 v[24:25], off
	v_lshl_add_u64 v[24:25], v[220:221], 0, s[36:37]
	s_mov_b32 m0, s46
	s_nop 0
	global_load_lds_dwordx4 v[24:25], off
	v_lshl_add_u64 v[24:25], v[230:231], 0, s[36:37]
	s_mov_b32 m0, s47
	s_nop 0
	global_load_lds_dwordx4 v[24:25], off
	s_waitcnt vmcnt(8)
	s_waitcnt lgkmcnt(0)
	s_barrier
	s_setprio 0
	s_waitcnt lgkmcnt(0)
	v_mfma_f32_16x16x32_bf16 v[24:27], v[8:11], v[32:35], v[134:137]
	v_mfma_f32_16x16x32_bf16 v[68:71], v[12:15], v[36:39], v[24:27]
	v_mfma_f32_16x16x32_bf16 v[24:27], v[16:19], v[32:35], v[142:145]
	v_mfma_f32_16x16x32_bf16 v[56:59], v[20:23], v[36:39], v[24:27]
	v_mfma_f32_16x16x32_bf16 v[24:27], v[8:11], v[194:197], v[146:149]
	v_mfma_f32_16x16x32_bf16 v[44:47], v[12:15], v[202:205], v[24:27]
	v_mfma_f32_16x16x32_bf16 v[24:27], v[16:19], v[194:197], v[150:153]
	v_mfma_f32_16x16x32_bf16 v[40:43], v[20:23], v[202:205], v[24:27]
	v_mfma_f32_16x16x32_bf16 v[24:27], v[8:11], v[206:209], v[154:157]
	v_mfma_f32_16x16x32_bf16 v[0:3], v[8:11], v[236:239], v[0:3]
	v_mfma_f32_16x16x32_bf16 v[28:31], v[12:15], v[224:227], v[24:27]
	v_mfma_f32_16x16x32_bf16 v[24:27], v[16:19], v[206:209], v[158:161]
	v_mfma_f32_16x16x32_bf16 v[12:15], v[12:15], v[240:243], v[0:3]
	v_mfma_f32_16x16x32_bf16 v[0:3], v[16:19], v[236:239], v[4:7]
	v_mfma_f32_16x16x32_bf16 v[24:27], v[20:23], v[224:227], v[24:27]
	v_mfma_f32_16x16x32_bf16 v[8:11], v[20:23], v[240:243], v[0:3]
	v_mfma_f32_16x16x32_bf16 v[0:3], v[166:169], v[32:35], v[216:219]
	v_mfma_f32_16x16x32_bf16 v[48:51], v[186:189], v[36:39], v[0:3]
	v_mfma_f32_16x16x32_bf16 v[0:3], v[212:215], v[32:35], v[232:235]
	v_mfma_f32_16x16x32_bf16 v[52:55], v[248:251], v[36:39], v[0:3]
	v_mfma_f32_16x16x32_bf16 v[0:3], v[166:169], v[194:197], v[244:247]
	v_mfma_f32_16x16x32_bf16 v[32:35], v[186:189], v[202:205], v[0:3]
	v_mfma_f32_16x16x32_bf16 v[0:3], v[212:215], v[194:197], v[170:173]
	v_mfma_f32_16x16x32_bf16 v[36:39], v[248:251], v[202:205], v[0:3]
	v_mfma_f32_16x16x32_bf16 v[0:3], v[166:169], v[206:209], v[174:177]
	v_mfma_f32_16x16x32_bf16 v[16:19], v[186:189], v[224:227], v[0:3]
	v_mfma_f32_16x16x32_bf16 v[0:3], v[212:215], v[206:209], v[178:181]
	v_mfma_f32_16x16x32_bf16 v[20:23], v[248:251], v[224:227], v[0:3]
	v_mfma_f32_16x16x32_bf16 v[0:3], v[166:169], v[236:239], v[182:185]
	v_mfma_f32_16x16x32_bf16 v[4:7], v[212:215], v[236:239], v[162:165]
	v_mfma_f32_16x16x32_bf16 v[0:3], v[186:189], v[240:243], v[0:3]
	v_mfma_f32_16x16x32_bf16 v[4:7], v[248:251], v[240:243], v[4:7]
	s_setprio 1
	s_barrier
	s_andn2_b64 vcc, exec, s[16:17]
	s_cbranch_vccnz .LBB0_63
	s_barrier

; #define PG8_STAGE(bufoff, gbase, voff) do { _Pragma("unroll") for (int _i = 0; _i < 2; ++_i) \
;         __builtin_amdgcn_global_load_lds((const unsigned*)((const char*)(gbase) + (voff)[_i]), (PG8_LAS unsigned*)(lds + (bufoff) + ldsw + _i * 8192), 16, 0, 0); } while (0)
; #define PG8_LDA(dst, b, h) do { _Pragma("unroll") for (int m = 0; m < 4; ++m) _Pragma("unroll") for (int k = 0; k < 2; ++k) dst[m][k] = *(const PG8_LAS bf16x8*)(lds + PG8_SA(b, h) + aoff + m * 2048 + k * 1024); } while (0)
; #define PG8_LDB(dst, b, h) do { _Pragma("unroll") for (int n = 0; n < 2; ++n) _Pragma("unroll") for (int k = 0; k < 2; ++k) dst[n][k] = *(const PG8_LAS bf16x8*)(lds + PG8_SB(b, h) + boff + n * 2048 + k * 1024); } while (0)
; #define PG8_MMA(ai, bj, At, Bt) do { __builtin_amdgcn_s_setprio(1); _Pragma("unroll") for (int m = 0; m < 4; ++m) _Pragma("unroll") for (int n = 0; n < 2; ++n) _Pragma("unroll") for (int k = 0; k < 2; ++k) \
;         acc[ai][bj][m][n] = __builtin_amdgcn_mfma_f32_16x16x32_bf16(Bt[n][k], At[m][k], acc[ai][bj][m][n], 0, 0, 0); __builtin_amdgcn_s_setprio(0); } while (0)
; #define PG8_WAIT_V(n) asm volatile("s_waitcnt vmcnt(" #n ")" ::: "memory")
; #define PG8_WAIT_L(n) asm volatile("s_waitcnt lgkmcnt(" #n ")" ::: "memory")
; #define PG8_BAR __builtin_amdgcn_s_barrier()
; #define PG8_SCHED __builtin_amdgcn_sched_barrier(0)
; template <class Epi, class Sched, bool ALIGN_EPI = false, bool SP2 = false>
; __device__ __forceinline__ void gemm_phase(PG8_LAS unsigned char* lds, const Gemm g, const Sched& S, const Epi& E, const int tid) {
;     ...
;             const bool last = (t == nt - 2);
;             const char* a1 = cA + (size_t)(t + 1) * kstep;
;             const char* a2 = last ? nA : cA + (size_t)(t + 2) * kstep; const char* b2 = last ? nB : cB + (size_t)(t + 2) * kstep;
;             const char* a3 = a2 + kstep; const char* b3 = b2 + kstep;
;             if (last && has_next) S.a_ready(nxt);
;             if constexpr (SP2) {
;             PG8_LDB(B0, 0, 0); PG8_LDB(B1, 0, 1); PG8_SCHED; PG8_LDA(At, 0, 0); PG8_STAGE(PG8_SA(1, 1), a1 + hstep, voffA);
;             PG8_WAIT_V(8); PG8_WAIT_L(0); PG8_BAR; PG8_MMA(0, 0, At, B0); PG8_MMA(0, 1, At, B1); PG8_BAR; PG8_SCHED;
;             PG8_LDA(At, 0, 1); PG8_STAGE(PG8_SB(0, 0), b2, voffB); PG8_STAGE(PG8_SB(0, 1), b2 + hstep, voffB); PG8_STAGE(PG8_SA(0, 0), a2, voffA);
.LBB0_99:
	s_add_u32 s20, s18, 0x100
	s_addc_u32 s21, s19, 0
	s_add_i32 s73, 0, 0x10000
	s_cmp_eq_u32 s72, 40
	s_cselect_b32 s45, s9, s21
	s_cselect_b32 s44, s8, s20
	s_cselect_b32 s23, s17, s71
	s_cselect_b32 s22, s16, s62
	s_add_i32 s74, 0, 0x14000
	v_add_u32_e32 v152, s73, v138
	v_add_u32_e32 v168, s74, v138
	ds_read_b128 v[140:143], v152
	ds_read_b128 v[144:147], v152 offset:1024
	ds_read_b128 v[148:151], v152 offset:2048
	ds_read_b128 v[152:155], v152 offset:3072
	ds_read_b128 v[156:159], v168
	ds_read_b128 v[160:163], v168 offset:1024
	ds_read_b128 v[164:167], v168 offset:2048
	ds_read_b128 v[168:171], v168 offset:3072
	v_lshl_add_u64 v[194:195], s[18:19], 0, v[134:135]
	s_add_i32 m0, s38, 0xc000
	ds_read_b128 v[172:175], v139
	ds_read_b128 v[176:179], v139 offset:1024
	ds_read_b128 v[180:183], v139 offset:2048
	ds_read_b128 v[184:187], v139 offset:3072
	ds_read_b128 v[188:191], v139 offset:4096
	ds_read_b128 v[212:215], v139 offset:5120
	ds_read_b128 v[216:219], v139 offset:6144
	ds_read_b128 v[232:235], v139 offset:7168
	global_load_lds_dwordx4 v[194:195], off
	v_lshl_add_u64 v[194:195], s[18:19], 0, v[136:137]
	s_add_i32 m0, s38, 0xe000
	s_nop 0
	global_load_lds_dwordx4 v[194:195], off
	s_waitcnt vmcnt(8)
	s_waitcnt lgkmcnt(0)
	s_barrier
	s_setprio 0
	s_waitcnt lgkmcnt(0)
	v_mfma_f32_16x16x32_bf16 v[124:127], v[140:143], v[172:175], v[124:127]
	v_mfma_f32_16x16x32_bf16 v[120:123], v[148:151], v[172:175], v[120:123]
	v_mfma_f32_16x16x32_bf16 v[116:119], v[140:143], v[180:183], v[116:119]
	v_mfma_f32_16x16x32_bf16 v[112:115], v[148:151], v[180:183], v[112:115]
	v_mfma_f32_16x16x32_bf16 v[100:103], v[140:143], v[188:191], v[100:103]
	v_mfma_f32_16x16x32_bf16 v[96:99], v[148:151], v[188:191], v[96:99]
	v_mfma_f32_16x16x32_bf16 v[84:87], v[140:143], v[216:219], v[84:87]
	v_mfma_f32_16x16x32_bf16 v[80:83], v[148:151], v[216:219], v[80:83]
	v_mfma_f32_16x16x32_bf16 v[124:127], v[144:147], v[176:179], v[124:127]
	v_mfma_f32_16x16x32_bf16 v[120:123], v[152:155], v[176:179], v[120:123]
	v_mfma_f32_16x16x32_bf16 v[116:119], v[144:147], v[184:187], v[116:119]
	v_mfma_f32_16x16x32_bf16 v[112:115], v[152:155], v[184:187], v[112:115]
	v_mfma_f32_16x16x32_bf16 v[100:103], v[144:147], v[212:215], v[100:103]
	v_mfma_f32_16x16x32_bf16 v[96:99], v[152:155], v[212:215], v[96:99]
	v_mfma_f32_16x16x32_bf16 v[84:87], v[144:147], v[232:235], v[84:87]
	v_mfma_f32_16x16x32_bf16 v[80:83], v[152:155], v[232:235], v[80:83]
	v_mfma_f32_16x16x32_bf16 v[108:111], v[156:159], v[172:175], v[108:111]
	v_mfma_f32_16x16x32_bf16 v[104:107], v[164:167], v[172:175], v[104:107]
	v_mfma_f32_16x16x32_bf16 v[92:95], v[156:159], v[180:183], v[92:95]
	v_mfma_f32_16x16x32_bf16 v[88:91], v[164:167], v[180:183], v[88:91]
	v_mfma_f32_16x16x32_bf16 v[76:79], v[156:159], v[188:191], v[76:79]
	v_mfma_f32_16x16x32_bf16 v[72:75], v[164:167], v[188:191], v[72:75]
	v_mfma_f32_16x16x32_bf16 v[68:71], v[156:159], v[216:219], v[68:71]
	v_mfma_f32_16x16x32_bf16 v[64:67], v[164:167], v[216:219], v[64:67]
	v_mfma_f32_16x16x32_bf16 v[108:111], v[160:163], v[176:179], v[108:111]
	v_mfma_f32_16x16x32_bf16 v[104:107], v[168:171], v[176:179], v[104:107]
	v_mfma_f32_16x16x32_bf16 v[92:95], v[160:163], v[184:187], v[92:95]
	v_mfma_f32_16x16x32_bf16 v[88:91], v[168:171], v[184:187], v[88:91]
	v_mfma_f32_16x16x32_bf16 v[76:79], v[160:163], v[212:215], v[76:79]
	v_mfma_f32_16x16x32_bf16 v[72:75], v[168:171], v[212:215], v[72:75]
	v_mfma_f32_16x16x32_bf16 v[68:71], v[160:163], v[232:235], v[68:71]
	v_mfma_f32_16x16x32_bf16 v[64:67], v[168:171], v[232:235], v[64:67]
	s_setprio 1
	s_barrier
	s_add_i32 s18, s73, s35
	v_lshl_add_u64 v[194:195], s[22:23], 0, v[192:193]
	s_mov_b32 m0, s18
	ds_read_b128 v[172:175], v139 offset:16384
	ds_read_b128 v[176:179], v139 offset:17408
	ds_read_b128 v[180:183], v139 offset:18432
	ds_read_b128 v[184:187], v139 offset:19456
	ds_read_b128 v[188:191], v139 offset:20480
	ds_read_b128 v[212:215], v139 offset:21504
	ds_read_b128 v[216:219], v139 offset:22528
	ds_read_b128 v[232:235], v139 offset:23552
	global_load_lds_dwordx4 v[194:195], off
	s_add_i32 m0, s18, 0x2000
	s_add_u32 s18, s22, 0xb0000
	v_lshl_add_u64 v[196:197], s[22:23], 0, v[132:133]
	s_addc_u32 s19, s23, 0
	s_add_i32 s73, s74, s35
	global_load_lds_dwordx4 v[196:197], off
	v_lshl_add_u64 v[202:203], s[18:19], 0, v[192:193]
	s_mov_b32 m0, s73
	v_lshl_add_u64 v[204:205], s[44:45], 0, v[130:131]
	global_load_lds_dwordx4 v[202:203], off
	v_lshl_add_u64 v[202:203], s[18:19], 0, v[132:133]
	s_add_i32 m0, s73, 0x2000
	s_nop 0
	global_load_lds_dwordx4 v[202:203], off
	v_lshl_add_u64 v[202:203], s[44:45], 0, v[128:129]
	s_mov_b32 m0, s38
	s_nop 0
	global_load_lds_dwordx4 v[202:203], off
	s_mov_b32 m0, s40
	s_nop 0
	global_load_lds_dwordx4 v[204:205], off
	s_waitcnt vmcnt(8)
	s_waitcnt lgkmcnt(0)
	s_barrier
; #define PG8_STAGE(bufoff, gbase, voff) do { _Pragma("unroll") for (int _i = 0; _i < 2; ++_i) \
;         __builtin_amdgcn_global_load_lds((const unsigned*)((const char*)(gbase) + (voff)[_i]), (PG8_LAS unsigned*)(lds + (bufoff) + ldsw + _i * 8192), 16, 0, 0); } while (0)
; #define PG8_LDA(dst, b, h) do { _Pragma("unroll") for (int m = 0; m < 4; ++m) _Pragma("unroll") for (int k = 0; k < 2; ++k) dst[m][k] = *(const PG8_LAS bf16x8*)(lds + PG8_SA(b, h) + aoff + m * 2048 + k * 1024); } while (0)
; #define PG8_LDB(dst, b, h) do { _Pragma("unroll") for (int n = 0; n < 2; ++n) _Pragma("unroll") for (int k = 0; k < 2; ++k) dst[n][k] = *(const PG8_LAS bf16x8*)(lds + PG8_SB(b, h) + boff + n * 2048 + k * 1024); } while (0)
; #define PG8_MMA(ai, bj, At, Bt) do { __builtin_amdgcn_s_setprio(1); _Pragma("unroll") for (int m = 0; m < 4; ++m) _Pragma("unroll") for (int n = 0; n < 2; ++n) _Pragma("unroll") for (int k = 0; k < 2; ++k) \
;         acc[ai][bj][m][n] = __builtin_amdgcn_mfma_f32_16x16x32_bf16(Bt[n][k], At[m][k], acc[ai][bj][m][n], 0, 0, 0); __builtin_amdgcn_s_setprio(0); } while (0)
; #define PG8_WAIT_V(n) asm volatile("s_waitcnt vmcnt(" #n ")" ::: "memory")
; #define PG8_WAIT_L(n) asm volatile("s_waitcnt lgkmcnt(" #n ")" ::: "memory")
; #define PG8_BAR __builtin_amdgcn_s_barrier()
; #define PG8_SCHED __builtin_amdgcn_sched_barrier(0)
; template <class Epi, class Sched, bool ALIGN_EPI = false, bool SP2 = false>
; __device__ __forceinline__ void gemm_phase(PG8_LAS unsigned char* lds, const Gemm g, const Sched& S, const Epi& E, const int tid) {
;     ...
;             PG8_WAIT_V(8); PG8_WAIT_L(0); PG8_BAR; PG8_MMA(1, 0, At, B0); PG8_MMA(1, 1, At, B1); PG8_BAR; PG8_SCHED;
;             PG8_LDB(B0, 1, 0); PG8_LDB(B1, 1, 1); PG8_SCHED; PG8_LDA(At, 1, 0); PG8_STAGE(PG8_SA(0, 1), a2 + hstep, voffA);
;             PG8_WAIT_V(8); PG8_WAIT_L(0); PG8_BAR; PG8_MMA(0, 0, At, B0); PG8_MMA(0, 1, At, B1); PG8_BAR; PG8_SCHED;
	s_setprio 0
	s_waitcnt lgkmcnt(0)
	v_mfma_f32_16x16x32_bf16 v[60:63], v[140:143], v[172:175], v[60:63]
	v_mfma_f32_16x16x32_bf16 v[56:59], v[148:151], v[172:175], v[56:59]
	v_mfma_f32_16x16x32_bf16 v[52:55], v[140:143], v[180:183], v[52:55]
	v_mfma_f32_16x16x32_bf16 v[48:51], v[148:151], v[180:183], v[48:51]
	v_mfma_f32_16x16x32_bf16 v[36:39], v[140:143], v[188:191], v[36:39]
	v_mfma_f32_16x16x32_bf16 v[32:35], v[148:151], v[188:191], v[32:35]
	v_mfma_f32_16x16x32_bf16 v[20:23], v[140:143], v[216:219], v[20:23]
	v_mfma_f32_16x16x32_bf16 v[16:19], v[148:151], v[216:219], v[16:19]
	v_mfma_f32_16x16x32_bf16 v[60:63], v[144:147], v[176:179], v[60:63]
	v_mfma_f32_16x16x32_bf16 v[56:59], v[152:155], v[176:179], v[56:59]
	v_mfma_f32_16x16x32_bf16 v[52:55], v[144:147], v[184:187], v[52:55]
	v_mfma_f32_16x16x32_bf16 v[48:51], v[152:155], v[184:187], v[48:51]
	v_mfma_f32_16x16x32_bf16 v[36:39], v[144:147], v[212:215], v[36:39]
	v_mfma_f32_16x16x32_bf16 v[32:35], v[152:155], v[212:215], v[32:35]
	v_mfma_f32_16x16x32_bf16 v[20:23], v[144:147], v[232:235], v[20:23]
	v_mfma_f32_16x16x32_bf16 v[16:19], v[152:155], v[232:235], v[16:19]
	v_mfma_f32_16x16x32_bf16 v[44:47], v[156:159], v[172:175], v[44:47]
	v_mfma_f32_16x16x32_bf16 v[40:43], v[164:167], v[172:175], v[40:43]
	v_mfma_f32_16x16x32_bf16 v[28:31], v[156:159], v[180:183], v[28:31]
	v_mfma_f32_16x16x32_bf16 v[24:27], v[164:167], v[180:183], v[24:27]
	v_mfma_f32_16x16x32_bf16 v[12:15], v[156:159], v[188:191], v[12:15]
	v_mfma_f32_16x16x32_bf16 v[8:11], v[164:167], v[188:191], v[8:11]
	v_mfma_f32_16x16x32_bf16 v[4:7], v[156:159], v[216:219], v[4:7]
	v_mfma_f32_16x16x32_bf16 v[0:3], v[164:167], v[216:219], v[0:3]
	v_mfma_f32_16x16x32_bf16 v[44:47], v[160:163], v[176:179], v[44:47]
	v_mfma_f32_16x16x32_bf16 v[40:43], v[168:171], v[176:179], v[40:43]
	v_mfma_f32_16x16x32_bf16 v[28:31], v[160:163], v[184:187], v[28:31]
	v_mfma_f32_16x16x32_bf16 v[24:27], v[168:171], v[184:187], v[24:27]
	v_mfma_f32_16x16x32_bf16 v[12:15], v[160:163], v[212:215], v[12:15]
	v_mfma_f32_16x16x32_bf16 v[8:11], v[168:171], v[212:215], v[8:11]
	v_mfma_f32_16x16x32_bf16 v[4:7], v[160:163], v[232:235], v[4:7]
	v_mfma_f32_16x16x32_bf16 v[0:3], v[168:171], v[232:235], v[0:3]
	s_setprio 1
	s_barrier
	s_add_i32 s73, 0, 0x18000
	s_add_i32 s74, 0, 0x1c000
	v_add_u32_e32 v152, s73, v138
	v_add_u32_e32 v168, s74, v138
	ds_read_b128 v[140:143], v152
	ds_read_b128 v[144:147], v152 offset:1024
	ds_read_b128 v[148:151], v152 offset:2048
	ds_read_b128 v[152:155], v152 offset:3072
	ds_read_b128 v[156:159], v168
	ds_read_b128 v[160:163], v168 offset:1024
	ds_read_b128 v[164:167], v168 offset:2048
	ds_read_b128 v[168:171], v168 offset:3072
	s_add_u32 s18, s44, 0xb0000
	s_addc_u32 s19, s45, 0
	s_mov_b32 m0, s41
	v_lshl_add_u64 v[206:207], s[18:19], 0, v[128:129]
	ds_read_b128 v[172:175], v139 offset:32768
	ds_read_b128 v[176:179], v139 offset:33792
	ds_read_b128 v[180:183], v139 offset:34816
	ds_read_b128 v[184:187], v139 offset:35840
	ds_read_b128 v[188:191], v139 offset:36864
	ds_read_b128 v[212:215], v139 offset:37888
	ds_read_b128 v[216:219], v139 offset:38912
	ds_read_b128 v[232:235], v139 offset:39936
	global_load_lds_dwordx4 v[206:207], off
	v_lshl_add_u64 v[206:207], s[18:19], 0, v[130:131]
	s_mov_b32 m0, s46
	s_nop 0
	global_load_lds_dwordx4 v[206:207], off
	s_waitcnt vmcnt(8)
	s_waitcnt lgkmcnt(0)
	s_barrier
	s_setprio 0
	s_waitcnt lgkmcnt(0)
	v_mfma_f32_16x16x32_bf16 v[124:127], v[140:143], v[172:175], v[124:127]
	v_mfma_f32_16x16x32_bf16 v[120:123], v[148:151], v[172:175], v[120:123]
	v_mfma_f32_16x16x32_bf16 v[116:119], v[140:143], v[180:183], v[116:119]
	v_mfma_f32_16x16x32_bf16 v[112:115], v[148:151], v[180:183], v[112:115]
	v_mfma_f32_16x16x32_bf16 v[100:103], v[140:143], v[188:191], v[100:103]
	v_mfma_f32_16x16x32_bf16 v[96:99], v[148:151], v[188:191], v[96:99]
	v_mfma_f32_16x16x32_bf16 v[84:87], v[140:143], v[216:219], v[84:87]
	v_mfma_f32_16x16x32_bf16 v[80:83], v[148:151], v[216:219], v[80:83]
	v_mfma_f32_16x16x32_bf16 v[124:127], v[144:147], v[176:179], v[124:127]
	v_mfma_f32_16x16x32_bf16 v[120:123], v[152:155], v[176:179], v[120:123]
	v_mfma_f32_16x16x32_bf16 v[116:119], v[144:147], v[184:187], v[116:119]
	v_mfma_f32_16x16x32_bf16 v[112:115], v[152:155], v[184:187], v[112:115]
	v_mfma_f32_16x16x32_bf16 v[100:103], v[144:147], v[212:215], v[100:103]
	v_mfma_f32_16x16x32_bf16 v[96:99], v[152:155], v[212:215], v[96:99]
	v_mfma_f32_16x16x32_bf16 v[84:87], v[144:147], v[232:235], v[84:87]
	v_mfma_f32_16x16x32_bf16 v[80:83], v[152:155], v[232:235], v[80:83]
	v_mfma_f32_16x16x32_bf16 v[108:111], v[156:159], v[172:175], v[108:111]
	v_mfma_f32_16x16x32_bf16 v[104:107], v[164:167], v[172:175], v[104:107]
	v_mfma_f32_16x16x32_bf16 v[92:95], v[156:159], v[180:183], v[92:95]
	v_mfma_f32_16x16x32_bf16 v[88:91], v[164:167], v[180:183], v[88:91]
	v_mfma_f32_16x16x32_bf16 v[76:79], v[156:159], v[188:191], v[76:79]
	v_mfma_f32_16x16x32_bf16 v[72:75], v[164:167], v[188:191], v[72:75]
	v_mfma_f32_16x16x32_bf16 v[68:71], v[156:159], v[216:219], v[68:71]
	v_mfma_f32_16x16x32_bf16 v[64:67], v[164:167], v[216:219], v[64:67]
	v_mfma_f32_16x16x32_bf16 v[108:111], v[160:163], v[176:179], v[108:111]
	v_mfma_f32_16x16x32_bf16 v[104:107], v[168:171], v[176:179], v[104:107]
	v_mfma_f32_16x16x32_bf16 v[92:95], v[160:163], v[184:187], v[92:95]
	v_mfma_f32_16x16x32_bf16 v[88:91], v[168:171], v[184:187], v[88:91]
	v_mfma_f32_16x16x32_bf16 v[76:79], v[160:163], v[212:215], v[76:79]
	v_mfma_f32_16x16x32_bf16 v[72:75], v[168:171], v[212:215], v[72:75]
	v_mfma_f32_16x16x32_bf16 v[68:71], v[160:163], v[232:235], v[68:71]
	v_mfma_f32_16x16x32_bf16 v[64:67], v[168:171], v[232:235], v[64:67]
	s_setprio 1
	s_barrier
; #define PG8_STAGE(bufoff, gbase, voff) do { _Pragma("unroll") for (int _i = 0; _i < 2; ++_i) \
;         __builtin_amdgcn_global_load_lds((const unsigned*)((const char*)(gbase) + (voff)[_i]), (PG8_LAS unsigned*)(lds + (bufoff) + ldsw + _i * 8192), 16, 0, 0); } while (0)
; #define PG8_LDA(dst, b, h) do { _Pragma("unroll") for (int m = 0; m < 4; ++m) _Pragma("unroll") for (int k = 0; k < 2; ++k) dst[m][k] = *(const PG8_LAS bf16x8*)(lds + PG8_SA(b, h) + aoff + m * 2048 + k * 1024); } while (0)
; #define PG8_MMA(ai, bj, At, Bt) do { __builtin_amdgcn_s_setprio(1); _Pragma("unroll") for (int m = 0; m < 4; ++m) _Pragma("unroll") for (int n = 0; n < 2; ++n) _Pragma("unroll") for (int k = 0; k < 2; ++k) \
;         acc[ai][bj][m][n] = __builtin_amdgcn_mfma_f32_16x16x32_bf16(Bt[n][k], At[m][k], acc[ai][bj][m][n], 0, 0, 0); __builtin_amdgcn_s_setprio(0); } while (0)
; #define PG8_WAIT_V(n) asm volatile("s_waitcnt vmcnt(" #n ")" ::: "memory")
; #define PG8_WAIT_L(n) asm volatile("s_waitcnt lgkmcnt(" #n ")" ::: "memory")
; #define PG8_BAR __builtin_amdgcn_s_barrier()
; #define PG8_SCHED __builtin_amdgcn_sched_barrier(0)
; template <class Epi, class Sched, bool ALIGN_EPI = false, bool SP2 = false>
; __device__ __forceinline__ void gemm_phase(PG8_LAS unsigned char* lds, const Gemm g, const Sched& S, const Epi& E, const int tid) {
;     ...
;         for (int t = 0; t < nt; t += 2) {
;     ...
;             PG8_LDA(At, 1, 1); PG8_STAGE(PG8_SB(1, 0), b3, voffB); PG8_STAGE(PG8_SB(1, 1), b3 + hstep, voffB); PG8_STAGE(PG8_SA(1, 0), a3, voffA);
;             PG8_WAIT_V(8); PG8_WAIT_L(0); PG8_BAR; PG8_MMA(1, 0, At, B0); PG8_MMA(1, 1, At, B1); PG8_BAR; PG8_SCHED;
	s_add_i32 s18, s73, s35
	v_lshl_add_u64 v[194:195], v[194:195], 0, s[36:37]
	s_mov_b32 m0, s18
	ds_read_b128 v[172:175], v139 offset:49152
	ds_read_b128 v[176:179], v139 offset:50176
	ds_read_b128 v[180:183], v139 offset:51200
	ds_read_b128 v[184:187], v139 offset:52224
	ds_read_b128 v[188:191], v139 offset:53248
	ds_read_b128 v[212:215], v139 offset:54272
	ds_read_b128 v[216:219], v139 offset:55296
	ds_read_b128 v[232:235], v139 offset:56320
	global_load_lds_dwordx4 v[194:195], off
	s_add_i32 m0, s18, 0x2000
	s_add_u32 s18, s22, 0xb0080
	v_lshl_add_u64 v[194:195], v[196:197], 0, s[36:37]
	s_addc_u32 s19, s23, 0
	s_add_i32 s22, s74, s35
	global_load_lds_dwordx4 v[194:195], off
	v_lshl_add_u64 v[194:195], s[18:19], 0, v[192:193]
	s_mov_b32 m0, s22
	s_nop 0
	global_load_lds_dwordx4 v[194:195], off
	v_lshl_add_u64 v[194:195], s[18:19], 0, v[132:133]
	s_add_i32 m0, s22, 0x2000
	s_nop 0
	global_load_lds_dwordx4 v[194:195], off
	v_lshl_add_u64 v[194:195], v[202:203], 0, s[36:37]
	s_mov_b32 m0, s47
	s_nop 0
	global_load_lds_dwordx4 v[194:195], off
	v_lshl_add_u64 v[194:195], v[204:205], 0, s[36:37]
	s_mov_b32 m0, s53
	s_nop 0
	global_load_lds_dwordx4 v[194:195], off
	s_waitcnt vmcnt(8)
	s_waitcnt lgkmcnt(0)
	s_barrier
	s_setprio 0
	s_waitcnt lgkmcnt(0)
	v_mfma_f32_16x16x32_bf16 v[60:63], v[140:143], v[172:175], v[60:63]
	v_mfma_f32_16x16x32_bf16 v[56:59], v[148:151], v[172:175], v[56:59]
	v_mfma_f32_16x16x32_bf16 v[52:55], v[140:143], v[180:183], v[52:55]
	v_mfma_f32_16x16x32_bf16 v[48:51], v[148:151], v[180:183], v[48:51]
	v_mfma_f32_16x16x32_bf16 v[36:39], v[140:143], v[188:191], v[36:39]
	v_mfma_f32_16x16x32_bf16 v[32:35], v[148:151], v[188:191], v[32:35]
	v_mfma_f32_16x16x32_bf16 v[20:23], v[140:143], v[216:219], v[20:23]
	v_mfma_f32_16x16x32_bf16 v[16:19], v[148:151], v[216:219], v[16:19]
	v_mfma_f32_16x16x32_bf16 v[60:63], v[144:147], v[176:179], v[60:63]
	v_mfma_f32_16x16x32_bf16 v[56:59], v[152:155], v[176:179], v[56:59]
	v_mfma_f32_16x16x32_bf16 v[52:55], v[144:147], v[184:187], v[52:55]
	v_mfma_f32_16x16x32_bf16 v[48:51], v[152:155], v[184:187], v[48:51]
	v_mfma_f32_16x16x32_bf16 v[36:39], v[144:147], v[212:215], v[36:39]
	v_mfma_f32_16x16x32_bf16 v[32:35], v[152:155], v[212:215], v[32:35]
	v_mfma_f32_16x16x32_bf16 v[20:23], v[144:147], v[232:235], v[20:23]
	v_mfma_f32_16x16x32_bf16 v[16:19], v[152:155], v[232:235], v[16:19]
	v_mfma_f32_16x16x32_bf16 v[44:47], v[156:159], v[172:175], v[44:47]
	v_mfma_f32_16x16x32_bf16 v[40:43], v[164:167], v[172:175], v[40:43]
	v_mfma_f32_16x16x32_bf16 v[28:31], v[156:159], v[180:183], v[28:31]
	v_mfma_f32_16x16x32_bf16 v[24:27], v[164:167], v[180:183], v[24:27]
	v_mfma_f32_16x16x32_bf16 v[12:15], v[156:159], v[188:191], v[12:15]
	v_mfma_f32_16x16x32_bf16 v[8:11], v[164:167], v[188:191], v[8:11]
	v_mfma_f32_16x16x32_bf16 v[4:7], v[156:159], v[216:219], v[4:7]
	v_mfma_f32_16x16x32_bf16 v[0:3], v[164:167], v[216:219], v[0:3]
	v_mfma_f32_16x16x32_bf16 v[44:47], v[160:163], v[176:179], v[44:47]
	v_mfma_f32_16x16x32_bf16 v[40:43], v[168:171], v[176:179], v[40:43]
	v_mfma_f32_16x16x32_bf16 v[28:31], v[160:163], v[184:187], v[28:31]
	v_mfma_f32_16x16x32_bf16 v[24:27], v[168:171], v[184:187], v[24:27]
	v_mfma_f32_16x16x32_bf16 v[12:15], v[160:163], v[212:215], v[12:15]
	v_mfma_f32_16x16x32_bf16 v[8:11], v[168:171], v[212:215], v[8:11]
	v_mfma_f32_16x16x32_bf16 v[4:7], v[160:163], v[232:235], v[4:7]
	v_mfma_f32_16x16x32_bf16 v[0:3], v[168:171], v[232:235], v[0:3]
	s_setprio 1
	s_barrier
	s_add_i32 s72, s72, 2
	s_add_u32 s62, s62, 0x100
	s_addc_u32 s71, s71, 0
	s_cmp_gt_u32 s72, 41
	s_mov_b64 s[18:19], s[20:21]
	s_cbranch_scc0 .LBB0_99
	s_and_b64 vcc, exec, s[14:15]
	s_cbranch_vccz .LBB0_102
	s_barrier

; #define PG8_STAGE(bufoff, gbase, voff) do { _Pragma("unroll") for (int _i = 0; _i < 2; ++_i) \
;         __builtin_amdgcn_global_load_lds((const unsigned*)((const char*)(gbase) + (voff)[_i]), (PG8_LAS unsigned*)(lds + (bufoff) + ldsw + _i * 8192), 16, 0, 0); } while (0)
; #define PG8_LDA(dst, b, h) do { _Pragma("unroll") for (int m = 0; m < 4; ++m) _Pragma("unroll") for (int k = 0; k < 2; ++k) dst[m][k] = *(const PG8_LAS bf16x8*)(lds + PG8_SA(b, h) + aoff + m * 2048 + k * 1024); } while (0)
; #define PG8_LDB(dst, b, h) do { _Pragma("unroll") for (int n = 0; n < 2; ++n) _Pragma("unroll") for (int k = 0; k < 2; ++k) dst[n][k] = *(const PG8_LAS bf16x8*)(lds + PG8_SB(b, h) + boff + n * 2048 + k * 1024); } while (0)
; #define PG8_MMA(ai, bj, At, Bt) do { __builtin_amdgcn_s_setprio(1); _Pragma("unroll") for (int m = 0; m < 4; ++m) _Pragma("unroll") for (int n = 0; n < 2; ++n) _Pragma("unroll") for (int k = 0; k < 2; ++k) \
;         acc[ai][bj][m][n] = __builtin_amdgcn_mfma_f32_16x16x32_bf16(Bt[n][k], At[m][k], acc[ai][bj][m][n], 0, 0, 0); __builtin_amdgcn_s_setprio(0); } while (0)
; #define PG8_WAIT_V(n) asm volatile("s_waitcnt vmcnt(" #n ")" ::: "memory")
; #define PG8_WAIT_L(n) asm volatile("s_waitcnt lgkmcnt(" #n ")" ::: "memory")
; #define PG8_BAR __builtin_amdgcn_s_barrier()
; #define PG8_SCHED __builtin_amdgcn_sched_barrier(0)
; template <class Epi, class Sched, bool ALIGN_EPI = false, bool SP2 = false>
; __device__ __forceinline__ void gemm_phase(PG8_LAS unsigned char* lds, const Gemm g, const Sched& S, const Epi& E, const int tid) {
;     ...
;             const bool last = (t == nt - 2);
;             const char* a1 = cA + (size_t)(t + 1) * kstep;
;             const char* a2 = last ? nA : cA + (size_t)(t + 2) * kstep; const char* b2 = last ? nB : cB + (size_t)(t + 2) * kstep;
;             const char* a3 = a2 + kstep; const char* b3 = b2 + kstep;
;             if (last && has_next) S.a_ready(nxt);
;             if constexpr (SP2) {
;             PG8_LDB(B0, 0, 0); PG8_LDB(B1, 0, 1); PG8_SCHED; PG8_LDA(At, 0, 0); PG8_STAGE(PG8_SA(1, 1), a1 + hstep, voffA);
;             PG8_WAIT_V(8); PG8_WAIT_L(0); PG8_BAR; PG8_MMA(0, 0, At, B0); PG8_MMA(0, 1, At, B1); PG8_BAR; PG8_SCHED;
;             PG8_LDA(At, 0, 1); PG8_STAGE(PG8_SB(0, 0), b2, voffB); PG8_STAGE(PG8_SB(0, 1), b2 + hstep, voffB); PG8_STAGE(PG8_SA(0, 0), a2, voffA);
.LBB0_127:
	s_add_u32 s44, s16, s22
	s_addc_u32 s45, s17, s23
	s_add_u32 s44, s44, 0x100
	s_addc_u32 s45, s45, 0
	s_waitcnt lgkmcnt(0)
	s_add_u32 s75, s19, s22
	s_addc_u32 s76, s62, s23
	s_add_i32 s77, 0, 0x10000
	s_cmpk_eq_i32 s22, 0x1500
	s_cselect_b32 s59, s21, s45
	s_cselect_b32 s58, s20, s44
	s_cselect_b32 s45, s11, s76
	s_cselect_b32 s44, s10, s75
	s_add_i32 s75, 0, 0x14000
	v_add_u32_e32 v156, s77, v142
	v_add_u32_e32 v172, s75, v142
	ds_read_b128 v[144:147], v156
	ds_read_b128 v[148:151], v156 offset:1024
	ds_read_b128 v[152:155], v156 offset:2048
	ds_read_b128 v[156:159], v156 offset:3072
	ds_read_b128 v[160:163], v172
	ds_read_b128 v[164:167], v172 offset:1024
	ds_read_b128 v[168:171], v172 offset:2048
	ds_read_b128 v[172:175], v172 offset:3072
	v_lshl_add_u64 v[194:195], v[138:139], 0, s[22:23]
	s_add_i32 m0, s47, 0xc000
	ds_read_b128 v[176:179], v143
	ds_read_b128 v[180:183], v143 offset:1024
	ds_read_b128 v[184:187], v143 offset:2048
	ds_read_b128 v[188:191], v143 offset:3072
	ds_read_b128 v[212:215], v143 offset:4096
	ds_read_b128 v[216:219], v143 offset:5120
	ds_read_b128 v[232:235], v143 offset:6144
	ds_read_b128 v[236:239], v143 offset:7168
	global_load_lds_dwordx4 v[194:195], off
	v_lshl_add_u64 v[194:195], v[140:141], 0, s[22:23]
	s_add_i32 m0, s47, 0xe000
	s_nop 0
	global_load_lds_dwordx4 v[194:195], off
	s_waitcnt vmcnt(8)
	s_waitcnt lgkmcnt(0)
	s_barrier
	s_setprio 0
	s_waitcnt lgkmcnt(0)
	v_mfma_f32_16x16x32_bf16 v[124:127], v[144:147], v[176:179], v[124:127]
	v_mfma_f32_16x16x32_bf16 v[120:123], v[152:155], v[176:179], v[120:123]
	v_mfma_f32_16x16x32_bf16 v[108:111], v[144:147], v[184:187], v[108:111]
	v_mfma_f32_16x16x32_bf16 v[104:107], v[152:155], v[184:187], v[104:107]
	v_mfma_f32_16x16x32_bf16 v[92:95], v[144:147], v[212:215], v[92:95]
	v_mfma_f32_16x16x32_bf16 v[88:91], v[152:155], v[212:215], v[88:91]
	v_mfma_f32_16x16x32_bf16 v[76:79], v[144:147], v[232:235], v[76:79]
	v_mfma_f32_16x16x32_bf16 v[72:75], v[152:155], v[232:235], v[72:75]
	v_mfma_f32_16x16x32_bf16 v[124:127], v[148:151], v[180:183], v[124:127]
	v_mfma_f32_16x16x32_bf16 v[120:123], v[156:159], v[180:183], v[120:123]
	v_mfma_f32_16x16x32_bf16 v[108:111], v[148:151], v[188:191], v[108:111]
	v_mfma_f32_16x16x32_bf16 v[104:107], v[156:159], v[188:191], v[104:107]
	v_mfma_f32_16x16x32_bf16 v[92:95], v[148:151], v[216:219], v[92:95]
	v_mfma_f32_16x16x32_bf16 v[88:91], v[156:159], v[216:219], v[88:91]
	v_mfma_f32_16x16x32_bf16 v[76:79], v[148:151], v[236:239], v[76:79]
	v_mfma_f32_16x16x32_bf16 v[72:75], v[156:159], v[236:239], v[72:75]
	v_mfma_f32_16x16x32_bf16 v[116:119], v[160:163], v[176:179], v[116:119]
	v_mfma_f32_16x16x32_bf16 v[112:115], v[168:171], v[176:179], v[112:115]
	v_mfma_f32_16x16x32_bf16 v[100:103], v[160:163], v[184:187], v[100:103]
	v_mfma_f32_16x16x32_bf16 v[96:99], v[168:171], v[184:187], v[96:99]
	v_mfma_f32_16x16x32_bf16 v[84:87], v[160:163], v[212:215], v[84:87]
	v_mfma_f32_16x16x32_bf16 v[80:83], v[168:171], v[212:215], v[80:83]
	v_mfma_f32_16x16x32_bf16 v[68:71], v[160:163], v[232:235], v[68:71]
	v_mfma_f32_16x16x32_bf16 v[64:67], v[168:171], v[232:235], v[64:67]
	v_mfma_f32_16x16x32_bf16 v[116:119], v[164:167], v[180:183], v[116:119]
	v_mfma_f32_16x16x32_bf16 v[112:115], v[172:175], v[180:183], v[112:115]
	v_mfma_f32_16x16x32_bf16 v[100:103], v[164:167], v[188:191], v[100:103]
	v_mfma_f32_16x16x32_bf16 v[96:99], v[172:175], v[188:191], v[96:99]
	v_mfma_f32_16x16x32_bf16 v[84:87], v[164:167], v[216:219], v[84:87]
	v_mfma_f32_16x16x32_bf16 v[80:83], v[172:175], v[216:219], v[80:83]
	v_mfma_f32_16x16x32_bf16 v[68:71], v[164:167], v[236:239], v[68:71]
	v_mfma_f32_16x16x32_bf16 v[64:67], v[172:175], v[236:239], v[64:67]
	s_setprio 1
	s_barrier
	s_add_i32 s76, s77, s46
	v_lshl_add_u64 v[194:195], s[44:45], 0, v[192:193]
	s_mov_b32 m0, s76
	ds_read_b128 v[176:179], v143 offset:16384
	ds_read_b128 v[180:183], v143 offset:17408
	ds_read_b128 v[184:187], v143 offset:18432
	ds_read_b128 v[188:191], v143 offset:19456
	ds_read_b128 v[212:215], v143 offset:20480
	ds_read_b128 v[216:219], v143 offset:21504
	ds_read_b128 v[232:235], v143 offset:22528
	ds_read_b128 v[236:239], v143 offset:23552
	global_load_lds_dwordx4 v[194:195], off
	s_add_i32 m0, s76, 0x2000
	s_add_u32 s76, s44, 0xb0000
	v_lshl_add_u64 v[196:197], s[44:45], 0, v[132:133]
	s_addc_u32 s77, s45, 0
	s_add_i32 s75, s75, s46
	global_load_lds_dwordx4 v[196:197], off
	v_lshl_add_u64 v[202:203], s[76:77], 0, v[192:193]
	s_mov_b32 m0, s75
	v_lshl_add_u64 v[204:205], s[58:59], 0, v[130:131]
	global_load_lds_dwordx4 v[202:203], off
	v_lshl_add_u64 v[202:203], s[76:77], 0, v[132:133]
	s_add_i32 m0, s75, 0x2000
	s_nop 0
	global_load_lds_dwordx4 v[202:203], off
	v_lshl_add_u64 v[202:203], s[58:59], 0, v[128:129]
	s_mov_b32 m0, s47
	s_nop 0
	global_load_lds_dwordx4 v[202:203], off
	s_mov_b32 m0, s53
	s_nop 0
	global_load_lds_dwordx4 v[204:205], off
	s_waitcnt vmcnt(8)
	s_waitcnt lgkmcnt(0)
	s_barrier
; #define PG8_STAGE(bufoff, gbase, voff) do { _Pragma("unroll") for (int _i = 0; _i < 2; ++_i) \
;         __builtin_amdgcn_global_load_lds((const unsigned*)((const char*)(gbase) + (voff)[_i]), (PG8_LAS unsigned*)(lds + (bufoff) + ldsw + _i * 8192), 16, 0, 0); } while (0)
; #define PG8_LDA(dst, b, h) do { _Pragma("unroll") for (int m = 0; m < 4; ++m) _Pragma("unroll") for (int k = 0; k < 2; ++k) dst[m][k] = *(const PG8_LAS bf16x8*)(lds + PG8_SA(b, h) + aoff + m * 2048 + k * 1024); } while (0)
; #define PG8_LDB(dst, b, h) do { _Pragma("unroll") for (int n = 0; n < 2; ++n) _Pragma("unroll") for (int k = 0; k < 2; ++k) dst[n][k] = *(const PG8_LAS bf16x8*)(lds + PG8_SB(b, h) + boff + n * 2048 + k * 1024); } while (0)
; #define PG8_MMA(ai, bj, At, Bt) do { __builtin_amdgcn_s_setprio(1); _Pragma("unroll") for (int m = 0; m < 4; ++m) _Pragma("unroll") for (int n = 0; n < 2; ++n) _Pragma("unroll") for (int k = 0; k < 2; ++k) \
;         acc[ai][bj][m][n] = __builtin_amdgcn_mfma_f32_16x16x32_bf16(Bt[n][k], At[m][k], acc[ai][bj][m][n], 0, 0, 0); __builtin_amdgcn_s_setprio(0); } while (0)
; #define PG8_WAIT_V(n) asm volatile("s_waitcnt vmcnt(" #n ")" ::: "memory")
; #define PG8_WAIT_L(n) asm volatile("s_waitcnt lgkmcnt(" #n ")" ::: "memory")
; #define PG8_BAR __builtin_amdgcn_s_barrier()
; #define PG8_SCHED __builtin_amdgcn_sched_barrier(0)
; template <class Epi, class Sched, bool ALIGN_EPI = false, bool SP2 = false>
; __device__ __forceinline__ void gemm_phase(PG8_LAS unsigned char* lds, const Gemm g, const Sched& S, const Epi& E, const int tid) {
;     ...
;             PG8_WAIT_V(8); PG8_WAIT_L(0); PG8_BAR; PG8_MMA(1, 0, At, B0); PG8_MMA(1, 1, At, B1); PG8_BAR; PG8_SCHED;
;             PG8_LDB(B0, 1, 0); PG8_LDB(B1, 1, 1); PG8_SCHED; PG8_LDA(At, 1, 0); PG8_STAGE(PG8_SA(0, 1), a2 + hstep, voffA);
;             PG8_WAIT_V(8); PG8_WAIT_L(0); PG8_BAR; PG8_MMA(0, 0, At, B0); PG8_MMA(0, 1, At, B1); PG8_BAR; PG8_SCHED;
	s_setprio 0
	s_waitcnt lgkmcnt(0)
	v_mfma_f32_16x16x32_bf16 v[60:63], v[144:147], v[176:179], v[60:63]
	v_mfma_f32_16x16x32_bf16 v[56:59], v[152:155], v[176:179], v[56:59]
	v_mfma_f32_16x16x32_bf16 v[44:47], v[144:147], v[184:187], v[44:47]
	v_mfma_f32_16x16x32_bf16 v[40:43], v[152:155], v[184:187], v[40:43]
	v_mfma_f32_16x16x32_bf16 v[28:31], v[144:147], v[212:215], v[28:31]
	v_mfma_f32_16x16x32_bf16 v[24:27], v[152:155], v[212:215], v[24:27]
	v_mfma_f32_16x16x32_bf16 v[12:15], v[144:147], v[232:235], v[12:15]
	v_mfma_f32_16x16x32_bf16 v[8:11], v[152:155], v[232:235], v[8:11]
	v_mfma_f32_16x16x32_bf16 v[60:63], v[148:151], v[180:183], v[60:63]
	v_mfma_f32_16x16x32_bf16 v[56:59], v[156:159], v[180:183], v[56:59]
	v_mfma_f32_16x16x32_bf16 v[44:47], v[148:151], v[188:191], v[44:47]
	v_mfma_f32_16x16x32_bf16 v[40:43], v[156:159], v[188:191], v[40:43]
	v_mfma_f32_16x16x32_bf16 v[28:31], v[148:151], v[216:219], v[28:31]
	v_mfma_f32_16x16x32_bf16 v[24:27], v[156:159], v[216:219], v[24:27]
	v_mfma_f32_16x16x32_bf16 v[12:15], v[148:151], v[236:239], v[12:15]
	v_mfma_f32_16x16x32_bf16 v[8:11], v[156:159], v[236:239], v[8:11]
	v_mfma_f32_16x16x32_bf16 v[52:55], v[160:163], v[176:179], v[52:55]
	v_mfma_f32_16x16x32_bf16 v[48:51], v[168:171], v[176:179], v[48:51]
	v_mfma_f32_16x16x32_bf16 v[36:39], v[160:163], v[184:187], v[36:39]
	v_mfma_f32_16x16x32_bf16 v[32:35], v[168:171], v[184:187], v[32:35]
	v_mfma_f32_16x16x32_bf16 v[20:23], v[160:163], v[212:215], v[20:23]
	v_mfma_f32_16x16x32_bf16 v[16:19], v[168:171], v[212:215], v[16:19]
	v_mfma_f32_16x16x32_bf16 v[4:7], v[160:163], v[232:235], v[4:7]
	v_mfma_f32_16x16x32_bf16 v[0:3], v[168:171], v[232:235], v[0:3]
	v_mfma_f32_16x16x32_bf16 v[52:55], v[164:167], v[180:183], v[52:55]
	v_mfma_f32_16x16x32_bf16 v[48:51], v[172:175], v[180:183], v[48:51]
	v_mfma_f32_16x16x32_bf16 v[36:39], v[164:167], v[188:191], v[36:39]
	v_mfma_f32_16x16x32_bf16 v[32:35], v[172:175], v[188:191], v[32:35]
	v_mfma_f32_16x16x32_bf16 v[20:23], v[164:167], v[216:219], v[20:23]
	v_mfma_f32_16x16x32_bf16 v[16:19], v[172:175], v[216:219], v[16:19]
	v_mfma_f32_16x16x32_bf16 v[4:7], v[164:167], v[236:239], v[4:7]
	v_mfma_f32_16x16x32_bf16 v[0:3], v[172:175], v[236:239], v[0:3]
	s_setprio 1
	s_barrier
	s_add_i32 s75, 0, 0x18000
	s_add_i32 s76, 0, 0x1c000
	v_add_u32_e32 v156, s75, v142
	v_add_u32_e32 v172, s76, v142
	ds_read_b128 v[144:147], v156
	ds_read_b128 v[148:151], v156 offset:1024
	ds_read_b128 v[152:155], v156 offset:2048
	ds_read_b128 v[156:159], v156 offset:3072
	ds_read_b128 v[160:163], v172
	ds_read_b128 v[164:167], v172 offset:1024
	ds_read_b128 v[168:171], v172 offset:2048
	ds_read_b128 v[172:175], v172 offset:3072
	s_add_u32 s58, s58, 0xb0000
	s_addc_u32 s59, s59, 0
	s_mov_b32 m0, s54
	v_lshl_add_u64 v[206:207], s[58:59], 0, v[128:129]
	ds_read_b128 v[176:179], v143 offset:32768
	ds_read_b128 v[180:183], v143 offset:33792
	ds_read_b128 v[184:187], v143 offset:34816
	ds_read_b128 v[188:191], v143 offset:35840
	ds_read_b128 v[212:215], v143 offset:36864
	ds_read_b128 v[216:219], v143 offset:37888
	ds_read_b128 v[232:235], v143 offset:38912
	ds_read_b128 v[236:239], v143 offset:39936
	global_load_lds_dwordx4 v[206:207], off
	v_lshl_add_u64 v[206:207], s[58:59], 0, v[130:131]
	s_mov_b32 m0, s55
	s_nop 0
	global_load_lds_dwordx4 v[206:207], off
	s_waitcnt vmcnt(8)
	s_waitcnt lgkmcnt(0)
	s_barrier
	s_setprio 0
	s_waitcnt lgkmcnt(0)
	v_mfma_f32_16x16x32_bf16 v[124:127], v[144:147], v[176:179], v[124:127]
	v_mfma_f32_16x16x32_bf16 v[120:123], v[152:155], v[176:179], v[120:123]
	v_mfma_f32_16x16x32_bf16 v[108:111], v[144:147], v[184:187], v[108:111]
	v_mfma_f32_16x16x32_bf16 v[104:107], v[152:155], v[184:187], v[104:107]
	v_mfma_f32_16x16x32_bf16 v[92:95], v[144:147], v[212:215], v[92:95]
	v_mfma_f32_16x16x32_bf16 v[88:91], v[152:155], v[212:215], v[88:91]
	v_mfma_f32_16x16x32_bf16 v[76:79], v[144:147], v[232:235], v[76:79]
	v_mfma_f32_16x16x32_bf16 v[72:75], v[152:155], v[232:235], v[72:75]
	v_mfma_f32_16x16x32_bf16 v[124:127], v[148:151], v[180:183], v[124:127]
	v_mfma_f32_16x16x32_bf16 v[120:123], v[156:159], v[180:183], v[120:123]
	v_mfma_f32_16x16x32_bf16 v[108:111], v[148:151], v[188:191], v[108:111]
	v_mfma_f32_16x16x32_bf16 v[104:107], v[156:159], v[188:191], v[104:107]
	v_mfma_f32_16x16x32_bf16 v[92:95], v[148:151], v[216:219], v[92:95]
	v_mfma_f32_16x16x32_bf16 v[88:91], v[156:159], v[216:219], v[88:91]
	v_mfma_f32_16x16x32_bf16 v[76:79], v[148:151], v[236:239], v[76:79]
	v_mfma_f32_16x16x32_bf16 v[72:75], v[156:159], v[236:239], v[72:75]
	v_mfma_f32_16x16x32_bf16 v[116:119], v[160:163], v[176:179], v[116:119]
	v_mfma_f32_16x16x32_bf16 v[112:115], v[168:171], v[176:179], v[112:115]
	v_mfma_f32_16x16x32_bf16 v[100:103], v[160:163], v[184:187], v[100:103]
	v_mfma_f32_16x16x32_bf16 v[96:99], v[168:171], v[184:187], v[96:99]
	v_mfma_f32_16x16x32_bf16 v[84:87], v[160:163], v[212:215], v[84:87]
	v_mfma_f32_16x16x32_bf16 v[80:83], v[168:171], v[212:215], v[80:83]
	v_mfma_f32_16x16x32_bf16 v[68:71], v[160:163], v[232:235], v[68:71]
	v_mfma_f32_16x16x32_bf16 v[64:67], v[168:171], v[232:235], v[64:67]
	v_mfma_f32_16x16x32_bf16 v[116:119], v[164:167], v[180:183], v[116:119]
	v_mfma_f32_16x16x32_bf16 v[112:115], v[172:175], v[180:183], v[112:115]
	v_mfma_f32_16x16x32_bf16 v[100:103], v[164:167], v[188:191], v[100:103]
	v_mfma_f32_16x16x32_bf16 v[96:99], v[172:175], v[188:191], v[96:99]
	v_mfma_f32_16x16x32_bf16 v[84:87], v[164:167], v[216:219], v[84:87]
	v_mfma_f32_16x16x32_bf16 v[80:83], v[172:175], v[216:219], v[80:83]
	v_mfma_f32_16x16x32_bf16 v[68:71], v[164:167], v[236:239], v[68:71]
	v_mfma_f32_16x16x32_bf16 v[64:67], v[172:175], v[236:239], v[64:67]
	s_setprio 1
	s_barrier
; #define PG8_STAGE(bufoff, gbase, voff) do { _Pragma("unroll") for (int _i = 0; _i < 2; ++_i) \
;         __builtin_amdgcn_global_load_lds((const unsigned*)((const char*)(gbase) + (voff)[_i]), (PG8_LAS unsigned*)(lds + (bufoff) + ldsw + _i * 8192), 16, 0, 0); } while (0)
; #define PG8_LDA(dst, b, h) do { _Pragma("unroll") for (int m = 0; m < 4; ++m) _Pragma("unroll") for (int k = 0; k < 2; ++k) dst[m][k] = *(const PG8_LAS bf16x8*)(lds + PG8_SA(b, h) + aoff + m * 2048 + k * 1024); } while (0)
; #define PG8_MMA(ai, bj, At, Bt) do { __builtin_amdgcn_s_setprio(1); _Pragma("unroll") for (int m = 0; m < 4; ++m) _Pragma("unroll") for (int n = 0; n < 2; ++n) _Pragma("unroll") for (int k = 0; k < 2; ++k) \
;         acc[ai][bj][m][n] = __builtin_amdgcn_mfma_f32_16x16x32_bf16(Bt[n][k], At[m][k], acc[ai][bj][m][n], 0, 0, 0); __builtin_amdgcn_s_setprio(0); } while (0)
; #define PG8_WAIT_V(n) asm volatile("s_waitcnt vmcnt(" #n ")" ::: "memory")
; #define PG8_WAIT_L(n) asm volatile("s_waitcnt lgkmcnt(" #n ")" ::: "memory")
; #define PG8_BAR __builtin_amdgcn_s_barrier()
; #define PG8_SCHED __builtin_amdgcn_sched_barrier(0)
; template <class Epi, class Sched, bool ALIGN_EPI = false, bool SP2 = false>
; __device__ __forceinline__ void gemm_phase(PG8_LAS unsigned char* lds, const Gemm g, const Sched& S, const Epi& E, const int tid) {
;     ...
;             PG8_LDA(At, 1, 1); PG8_STAGE(PG8_SB(1, 0), b3, voffB); PG8_STAGE(PG8_SB(1, 1), b3 + hstep, voffB); PG8_STAGE(PG8_SA(1, 0), a3, voffA);
;             PG8_WAIT_V(8); PG8_WAIT_L(0); PG8_BAR; PG8_MMA(1, 0, At, B0); PG8_MMA(1, 1, At, B1); PG8_BAR; PG8_SCHED;
;     ...
; #pragma unroll
;         for (int a = 0; a < 2; ++a)
; #pragma unroll
;             for (int b = 0; b < 2; ++b)
; #pragma unroll
;                 for (int m = 0; m < 4; ++m)
; #pragma unroll
;                     for (int n = 0; n < 2; ++n) acc[a][b][m][n] = (f32x4){0.f, 0.f, 0.f, 0.f};
	s_add_i32 s58, s75, s46
	v_lshl_add_u64 v[194:195], v[194:195], 0, s[36:37]
	s_mov_b32 m0, s58
	ds_read_b128 v[176:179], v143 offset:49152
	ds_read_b128 v[180:183], v143 offset:50176
	ds_read_b128 v[184:187], v143 offset:51200
	ds_read_b128 v[188:191], v143 offset:52224
	ds_read_b128 v[212:215], v143 offset:53248
	ds_read_b128 v[216:219], v143 offset:54272
	ds_read_b128 v[232:235], v143 offset:55296
	ds_read_b128 v[236:239], v143 offset:56320
	global_load_lds_dwordx4 v[194:195], off
	s_add_i32 m0, s58, 0x2000
	s_add_u32 s44, s44, 0xb0080
	v_lshl_add_u64 v[194:195], v[196:197], 0, s[36:37]
	s_addc_u32 s45, s45, 0
	s_add_i32 s58, s76, s46
	global_load_lds_dwordx4 v[194:195], off
	v_lshl_add_u64 v[194:195], s[44:45], 0, v[192:193]
	s_mov_b32 m0, s58
	s_nop 0
	global_load_lds_dwordx4 v[194:195], off
	v_lshl_add_u64 v[194:195], s[44:45], 0, v[132:133]
	s_add_i32 m0, s58, 0x2000
	s_nop 0
	global_load_lds_dwordx4 v[194:195], off
	v_lshl_add_u64 v[194:195], v[202:203], 0, s[36:37]
	s_mov_b32 m0, s60
	s_nop 0
	global_load_lds_dwordx4 v[194:195], off
	v_lshl_add_u64 v[194:195], v[204:205], 0, s[36:37]
	s_mov_b32 m0, s70
	s_nop 0
	global_load_lds_dwordx4 v[194:195], off
	s_waitcnt vmcnt(8)
	s_waitcnt lgkmcnt(0)
	s_barrier
	s_setprio 0
	s_waitcnt lgkmcnt(0)
	v_mfma_f32_16x16x32_bf16 v[60:63], v[144:147], v[176:179], v[60:63]
	v_mfma_f32_16x16x32_bf16 v[56:59], v[152:155], v[176:179], v[56:59]
	v_mfma_f32_16x16x32_bf16 v[44:47], v[144:147], v[184:187], v[44:47]
	v_mfma_f32_16x16x32_bf16 v[40:43], v[152:155], v[184:187], v[40:43]
	v_mfma_f32_16x16x32_bf16 v[28:31], v[144:147], v[212:215], v[28:31]
	v_mfma_f32_16x16x32_bf16 v[24:27], v[152:155], v[212:215], v[24:27]
	v_mfma_f32_16x16x32_bf16 v[12:15], v[144:147], v[232:235], v[12:15]
	v_mfma_f32_16x16x32_bf16 v[8:11], v[152:155], v[232:235], v[8:11]
	v_mfma_f32_16x16x32_bf16 v[60:63], v[148:151], v[180:183], v[60:63]
	v_mfma_f32_16x16x32_bf16 v[56:59], v[156:159], v[180:183], v[56:59]
	v_mfma_f32_16x16x32_bf16 v[44:47], v[148:151], v[188:191], v[44:47]
	v_mfma_f32_16x16x32_bf16 v[40:43], v[156:159], v[188:191], v[40:43]
	v_mfma_f32_16x16x32_bf16 v[28:31], v[148:151], v[216:219], v[28:31]
	v_mfma_f32_16x16x32_bf16 v[24:27], v[156:159], v[216:219], v[24:27]
	v_mfma_f32_16x16x32_bf16 v[12:15], v[148:151], v[236:239], v[12:15]
	v_mfma_f32_16x16x32_bf16 v[8:11], v[156:159], v[236:239], v[8:11]
	v_mfma_f32_16x16x32_bf16 v[52:55], v[160:163], v[176:179], v[52:55]
	v_mfma_f32_16x16x32_bf16 v[48:51], v[168:171], v[176:179], v[48:51]
	v_mfma_f32_16x16x32_bf16 v[36:39], v[160:163], v[184:187], v[36:39]
	v_mfma_f32_16x16x32_bf16 v[32:35], v[168:171], v[184:187], v[32:35]
	v_mfma_f32_16x16x32_bf16 v[20:23], v[160:163], v[212:215], v[20:23]
	v_mfma_f32_16x16x32_bf16 v[16:19], v[168:171], v[212:215], v[16:19]
	v_mfma_f32_16x16x32_bf16 v[4:7], v[160:163], v[232:235], v[4:7]
	v_mfma_f32_16x16x32_bf16 v[0:3], v[168:171], v[232:235], v[0:3]
	v_mfma_f32_16x16x32_bf16 v[52:55], v[164:167], v[180:183], v[52:55]
	v_mfma_f32_16x16x32_bf16 v[48:51], v[172:175], v[180:183], v[48:51]
	v_mfma_f32_16x16x32_bf16 v[36:39], v[164:167], v[188:191], v[36:39]
	v_mfma_f32_16x16x32_bf16 v[32:35], v[172:175], v[188:191], v[32:35]
	v_mfma_f32_16x16x32_bf16 v[20:23], v[164:167], v[216:219], v[20:23]
	v_mfma_f32_16x16x32_bf16 v[16:19], v[172:175], v[216:219], v[16:19]
	v_mfma_f32_16x16x32_bf16 v[4:7], v[164:167], v[236:239], v[4:7]
	v_mfma_f32_16x16x32_bf16 v[0:3], v[172:175], v[236:239], v[0:3]
	s_setprio 1
	s_barrier
	s_add_i32 s74, s74, 2
	s_add_u32 s22, s22, 0x100
	s_addc_u32 s23, s23, 0
	s_cmp_gt_u32 s74, 41
	s_cbranch_scc0 .LBB0_127
	s_add_u32 s22, s19, 0xffffff00
	s_addc_u32 s23, s62, -1
	s_and_b64 vcc, exec, s[8:9]
	s_cbranch_vccnz .LBB0_130
	v_mov_b32_e32 v0, 0
	s_mov_b32 s14, s72
	s_mov_b32 s1, s73
	s_mov_b64 s[16:17], s[20:21]
	s_mov_b32 s71, s18
	v_mov_b32_e32 v1, v0
	v_mov_b32_e32 v2, v0
	v_mov_b32_e32 v3, v0
	v_mov_b32_e32 v4, v0
	v_mov_b32_e32 v5, v0
	v_mov_b32_e32 v6, v0
	v_mov_b32_e32 v7, v0
	v_mov_b32_e32 v16, v0
	v_mov_b32_e32 v17, v0
	v_mov_b32_e32 v18, v0
	v_mov_b32_e32 v19, v0
	v_mov_b32_e32 v20, v0
	v_mov_b32_e32 v21, v0
	v_mov_b32_e32 v22, v0
	v_mov_b32_e32 v23, v0
	v_mov_b32_e32 v32, v0
	v_mov_b32_e32 v33, v0
	v_mov_b32_e32 v34, v0
	v_mov_b32_e32 v35, v0
	v_mov_b32_e32 v36, v0
	v_mov_b32_e32 v37, v0
	v_mov_b32_e32 v38, v0
	v_mov_b32_e32 v39, v0
	v_mov_b32_e32 v48, v0
	v_mov_b32_e32 v49, v0
	v_mov_b32_e32 v50, v0
	v_mov_b32_e32 v51, v0
	v_mov_b32_e32 v52, v0
	v_mov_b32_e32 v53, v0
	v_mov_b32_e32 v54, v0
	v_mov_b32_e32 v55, v0
	v_mov_b32_e32 v8, v0
	v_mov_b32_e32 v9, v0
	v_mov_b32_e32 v10, v0
	v_mov_b32_e32 v11, v0
	v_mov_b32_e32 v12, v0
	v_mov_b32_e32 v13, v0
	v_mov_b32_e32 v14, v0
	v_mov_b32_e32 v15, v0
	v_mov_b32_e32 v24, v0
	v_mov_b32_e32 v25, v0
	v_mov_b32_e32 v26, v0
	v_mov_b32_e32 v27, v0
	v_mov_b32_e32 v28, v0
	v_mov_b32_e32 v29, v0
	v_mov_b32_e32 v30, v0
	v_mov_b32_e32 v31, v0
	v_mov_b32_e32 v40, v0
	v_mov_b32_e32 v41, v0
	v_mov_b32_e32 v42, v0
	v_mov_b32_e32 v43, v0
	v_mov_b32_e32 v44, v0
	v_mov_b32_e32 v45, v0
	v_mov_b32_e32 v46, v0
	v_mov_b32_e32 v47, v0
	v_mov_b32_e32 v56, v0
	v_mov_b32_e32 v57, v0
	v_mov_b32_e32 v58, v0
	v_mov_b32_e32 v59, v0
	v_mov_b32_e32 v60, v0
	v_mov_b32_e32 v61, v0
	v_mov_b32_e32 v62, v0
	v_mov_b32_e32 v63, v0
	v_mov_b32_e32 v64, v0
	v_mov_b32_e32 v65, v0
	v_mov_b32_e32 v66, v0
	v_mov_b32_e32 v67, v0
	v_mov_b32_e32 v68, v0
	v_mov_b32_e32 v69, v0
	v_mov_b32_e32 v70, v0
	v_mov_b32_e32 v71, v0
	v_mov_b32_e32 v80, v0
	v_mov_b32_e32 v81, v0
	v_mov_b32_e32 v82, v0
	v_mov_b32_e32 v83, v0
	v_mov_b32_e32 v84, v0
	v_mov_b32_e32 v85, v0
	v_mov_b32_e32 v86, v0
	v_mov_b32_e32 v87, v0
	v_mov_b32_e32 v96, v0
	v_mov_b32_e32 v97, v0
	v_mov_b32_e32 v98, v0
	v_mov_b32_e32 v99, v0
	v_mov_b32_e32 v100, v0
	v_mov_b32_e32 v101, v0
	v_mov_b32_e32 v102, v0
	v_mov_b32_e32 v103, v0
	v_mov_b32_e32 v112, v0
	v_mov_b32_e32 v113, v0
	v_mov_b32_e32 v114, v0
	v_mov_b32_e32 v115, v0
	v_mov_b32_e32 v116, v0
	v_mov_b32_e32 v117, v0
	v_mov_b32_e32 v118, v0
	v_mov_b32_e32 v119, v0
	v_mov_b32_e32 v72, v0
	v_mov_b32_e32 v73, v0
	v_mov_b32_e32 v74, v0
	v_mov_b32_e32 v75, v0
	v_mov_b32_e32 v76, v0
	v_mov_b32_e32 v77, v0
	v_mov_b32_e32 v78, v0
	v_mov_b32_e32 v79, v0
	v_mov_b32_e32 v88, v0
	v_mov_b32_e32 v89, v0
	v_mov_b32_e32 v90, v0
	v_mov_b32_e32 v91, v0
	v_mov_b32_e32 v92, v0
	v_mov_b32_e32 v93, v0
	v_mov_b32_e32 v94, v0
	v_mov_b32_e32 v95, v0
	v_mov_b32_e32 v104, v0
	v_mov_b32_e32 v105, v0
	v_mov_b32_e32 v106, v0
	v_mov_b32_e32 v107, v0
	v_mov_b32_e32 v108, v0
	v_mov_b32_e32 v109, v0
	v_mov_b32_e32 v110, v0
	v_mov_b32_e32 v111, v0
	v_mov_b32_e32 v120, v0
	v_mov_b32_e32 v121, v0
	v_mov_b32_e32 v122, v0
	v_mov_b32_e32 v123, v0
	v_mov_b32_e32 v124, v0
	v_mov_b32_e32 v125, v0
	v_mov_b32_e32 v126, v0
	v_mov_b32_e32 v127, v0
	s_load_dword s75, s[96:97], 0x0
	s_andn2_b64 vcc, exec, s[6:7]
	s_cbranch_vccnz .LBB0_131
	s_branch .LBB0_189

; #define PG8_STAGE(bufoff, gbase, voff) do { _Pragma("unroll") for (int _i = 0; _i < 2; ++_i) \
;         __builtin_amdgcn_global_load_lds((const unsigned*)((const char*)(gbase) + (voff)[_i]), (PG8_LAS unsigned*)(lds + (bufoff) + ldsw + _i * 8192), 16, 0, 0); } while (0)
; #define PG8_LDA(dst, b, h) do { _Pragma("unroll") for (int m = 0; m < 4; ++m) _Pragma("unroll") for (int k = 0; k < 2; ++k) dst[m][k] = *(const PG8_LAS bf16x8*)(lds + PG8_SA(b, h) + aoff + m * 2048 + k * 1024); } while (0)
; #define PG8_LDB(dst, b, h) do { _Pragma("unroll") for (int n = 0; n < 2; ++n) _Pragma("unroll") for (int k = 0; k < 2; ++k) dst[n][k] = *(const PG8_LAS bf16x8*)(lds + PG8_SB(b, h) + boff + n * 2048 + k * 1024); } while (0)
; #define PG8_MMA(ai, bj, At, Bt) do { __builtin_amdgcn_s_setprio(1); _Pragma("unroll") for (int m = 0; m < 4; ++m) _Pragma("unroll") for (int n = 0; n < 2; ++n) _Pragma("unroll") for (int k = 0; k < 2; ++k) \
;         acc[ai][bj][m][n] = __builtin_amdgcn_mfma_f32_16x16x32_bf16(Bt[n][k], At[m][k], acc[ai][bj][m][n], 0, 0, 0); __builtin_amdgcn_s_setprio(0); } while (0)
; #define PG8_WAIT_V(n) asm volatile("s_waitcnt vmcnt(" #n ")" ::: "memory")
; #define PG8_WAIT_L(n) asm volatile("s_waitcnt lgkmcnt(" #n ")" ::: "memory")
; #define PG8_BAR __builtin_amdgcn_s_barrier()
; #define PG8_SCHED __builtin_amdgcn_sched_barrier(0)
; template <class Epi, class Sched, bool ALIGN_EPI = false, bool SP2 = false>
; __device__ __forceinline__ void gemm_phase(PG8_LAS unsigned char* lds, const Gemm g, const Sched& S, const Epi& E, const int tid) {
;     ...
;             const bool last = (t == nt - 2);
;             const char* a1 = cA + (size_t)(t + 1) * kstep;
;             const char* a2 = last ? nA : cA + (size_t)(t + 2) * kstep; const char* b2 = last ? nB : cB + (size_t)(t + 2) * kstep;
;             const char* a3 = a2 + kstep; const char* b3 = b2 + kstep;
;             if (last && has_next) S.a_ready(nxt);
;             if constexpr (SP2) {
;             PG8_LDB(B0, 0, 0); PG8_LDB(B1, 0, 1); PG8_SCHED; PG8_LDA(At, 0, 0); PG8_STAGE(PG8_SA(1, 1), a1 + hstep, voffA);
;             PG8_WAIT_V(8); PG8_WAIT_L(0); PG8_BAR; PG8_MMA(0, 0, At, B0); PG8_MMA(0, 1, At, B1); PG8_BAR; PG8_SCHED;
;             PG8_LDA(At, 0, 1); PG8_STAGE(PG8_SB(0, 0), b2, voffB); PG8_STAGE(PG8_SB(0, 1), b2 + hstep, voffB); PG8_STAGE(PG8_SA(0, 0), a2, voffA);
.LBB0_143:
	s_add_u32 s58, s44, 0xfffc0080
	s_addc_u32 s59, s45, -1
	s_add_i32 s72, 0, 0x10000
	s_cmp_eq_u32 s71, 12
	s_cselect_b32 s79, s17, s59
	s_cselect_b32 s78, s55, s58
	v_add_u32_e32 v138, s72, v140
	s_cselect_b32 s59, s15, s70
	s_cselect_b32 s58, s60, s62
	s_add_i32 s74, 0, 0x14000
	ds_read_b128 v[142:145], v138
	ds_read_b128 v[146:149], v138 offset:1024
	ds_read_b128 v[150:153], v138 offset:2048
	ds_read_b128 v[154:157], v138 offset:3072
	v_add_u32_e32 v138, s74, v140
	ds_read_b128 v[158:161], v138
	ds_read_b128 v[162:165], v138 offset:1024
	ds_read_b128 v[166:169], v138 offset:2048
	ds_read_b128 v[170:173], v138 offset:3072
	v_lshl_add_u64 v[138:139], s[44:45], 0, v[134:135]
	s_add_i32 m0, s38, 0xc000
	ds_read_b128 v[174:177], v141
	ds_read_b128 v[178:181], v141 offset:1024
	ds_read_b128 v[182:185], v141 offset:2048
	ds_read_b128 v[186:189], v141 offset:3072
	ds_read_b128 v[212:215], v141 offset:4096
	ds_read_b128 v[216:219], v141 offset:5120
	ds_read_b128 v[232:235], v141 offset:6144
	ds_read_b128 v[236:239], v141 offset:7168
	global_load_lds_dwordx4 v[138:139], off
	v_lshl_add_u64 v[138:139], s[44:45], 0, v[136:137]
	s_add_i32 m0, s38, 0xe000
	s_nop 0
	global_load_lds_dwordx4 v[138:139], off
	s_waitcnt vmcnt(8)
	s_waitcnt lgkmcnt(0)
	s_barrier
	s_setprio 0
	s_waitcnt lgkmcnt(0)
	v_mfma_f32_16x16x32_bf16 v[124:127], v[142:145], v[174:177], v[124:127]
	v_mfma_f32_16x16x32_bf16 v[116:119], v[150:153], v[174:177], v[116:119]
	v_mfma_f32_16x16x32_bf16 v[108:111], v[142:145], v[182:185], v[108:111]
	v_mfma_f32_16x16x32_bf16 v[100:103], v[150:153], v[182:185], v[100:103]
	v_mfma_f32_16x16x32_bf16 v[92:95], v[142:145], v[212:215], v[92:95]
	v_mfma_f32_16x16x32_bf16 v[84:87], v[150:153], v[212:215], v[84:87]
	v_mfma_f32_16x16x32_bf16 v[76:79], v[142:145], v[232:235], v[76:79]
	v_mfma_f32_16x16x32_bf16 v[68:71], v[150:153], v[232:235], v[68:71]
	v_mfma_f32_16x16x32_bf16 v[124:127], v[146:149], v[178:181], v[124:127]
	v_mfma_f32_16x16x32_bf16 v[116:119], v[154:157], v[178:181], v[116:119]
	v_mfma_f32_16x16x32_bf16 v[108:111], v[146:149], v[186:189], v[108:111]
	v_mfma_f32_16x16x32_bf16 v[100:103], v[154:157], v[186:189], v[100:103]
	v_mfma_f32_16x16x32_bf16 v[92:95], v[146:149], v[216:219], v[92:95]
	v_mfma_f32_16x16x32_bf16 v[84:87], v[154:157], v[216:219], v[84:87]
	v_mfma_f32_16x16x32_bf16 v[76:79], v[146:149], v[236:239], v[76:79]
	v_mfma_f32_16x16x32_bf16 v[68:71], v[154:157], v[236:239], v[68:71]
	v_mfma_f32_16x16x32_bf16 v[120:123], v[158:161], v[174:177], v[120:123]
	v_mfma_f32_16x16x32_bf16 v[112:115], v[166:169], v[174:177], v[112:115]
	v_mfma_f32_16x16x32_bf16 v[104:107], v[158:161], v[182:185], v[104:107]
	v_mfma_f32_16x16x32_bf16 v[96:99], v[166:169], v[182:185], v[96:99]
	v_mfma_f32_16x16x32_bf16 v[88:91], v[158:161], v[212:215], v[88:91]
	v_mfma_f32_16x16x32_bf16 v[80:83], v[166:169], v[212:215], v[80:83]
	v_mfma_f32_16x16x32_bf16 v[72:75], v[158:161], v[232:235], v[72:75]
	v_mfma_f32_16x16x32_bf16 v[64:67], v[166:169], v[232:235], v[64:67]
	v_mfma_f32_16x16x32_bf16 v[120:123], v[162:165], v[178:181], v[120:123]
	v_mfma_f32_16x16x32_bf16 v[112:115], v[170:173], v[178:181], v[112:115]
	v_mfma_f32_16x16x32_bf16 v[104:107], v[162:165], v[186:189], v[104:107]
	v_mfma_f32_16x16x32_bf16 v[96:99], v[170:173], v[186:189], v[96:99]
	v_mfma_f32_16x16x32_bf16 v[88:91], v[162:165], v[216:219], v[88:91]
	v_mfma_f32_16x16x32_bf16 v[80:83], v[170:173], v[216:219], v[80:83]
	v_mfma_f32_16x16x32_bf16 v[72:75], v[162:165], v[236:239], v[72:75]
	v_mfma_f32_16x16x32_bf16 v[64:67], v[170:173], v[236:239], v[64:67]
	s_setprio 1
	s_barrier
	s_add_i32 s72, s72, s34
	v_lshl_add_u64 v[138:139], s[58:59], 0, v[192:193]
	s_mov_b32 m0, s72
	ds_read_b128 v[174:177], v141 offset:16384
	ds_read_b128 v[178:181], v141 offset:17408
	ds_read_b128 v[182:185], v141 offset:18432
	ds_read_b128 v[186:189], v141 offset:19456
	ds_read_b128 v[212:215], v141 offset:20480
	ds_read_b128 v[216:219], v141 offset:21504
	ds_read_b128 v[232:235], v141 offset:22528
	ds_read_b128 v[236:239], v141 offset:23552
	global_load_lds_dwordx4 v[138:139], off
	s_add_i32 m0, s72, 0x2000
	s_add_u32 s72, s58, 0x40000
	v_lshl_add_u64 v[190:191], s[58:59], 0, v[128:129]
	s_addc_u32 s73, s59, 0
	s_add_i32 s74, s74, s34
	global_load_lds_dwordx4 v[190:191], off
	v_lshl_add_u64 v[194:195], s[72:73], 0, v[192:193]
	s_mov_b32 m0, s74
	v_lshl_add_u64 v[196:197], s[78:79], 0, v[130:131]
	global_load_lds_dwordx4 v[194:195], off
	v_lshl_add_u64 v[194:195], s[72:73], 0, v[128:129]
	s_add_i32 m0, s74, 0x2000
	s_nop 0
	global_load_lds_dwordx4 v[194:195], off
	v_lshl_add_u64 v[194:195], s[78:79], 0, v[132:133]
	s_mov_b32 m0, s38
	s_nop 0
	global_load_lds_dwordx4 v[194:195], off
	s_mov_b32 m0, s40
	s_nop 0
	global_load_lds_dwordx4 v[196:197], off
	s_waitcnt vmcnt(8)
	s_waitcnt lgkmcnt(0)
	s_barrier
; #define PG8_STAGE(bufoff, gbase, voff) do { _Pragma("unroll") for (int _i = 0; _i < 2; ++_i) \
;         __builtin_amdgcn_global_load_lds((const unsigned*)((const char*)(gbase) + (voff)[_i]), (PG8_LAS unsigned*)(lds + (bufoff) + ldsw + _i * 8192), 16, 0, 0); } while (0)
; #define PG8_LDA(dst, b, h) do { _Pragma("unroll") for (int m = 0; m < 4; ++m) _Pragma("unroll") for (int k = 0; k < 2; ++k) dst[m][k] = *(const PG8_LAS bf16x8*)(lds + PG8_SA(b, h) + aoff + m * 2048 + k * 1024); } while (0)
; #define PG8_LDB(dst, b, h) do { _Pragma("unroll") for (int n = 0; n < 2; ++n) _Pragma("unroll") for (int k = 0; k < 2; ++k) dst[n][k] = *(const PG8_LAS bf16x8*)(lds + PG8_SB(b, h) + boff + n * 2048 + k * 1024); } while (0)
; #define PG8_MMA(ai, bj, At, Bt) do { __builtin_amdgcn_s_setprio(1); _Pragma("unroll") for (int m = 0; m < 4; ++m) _Pragma("unroll") for (int n = 0; n < 2; ++n) _Pragma("unroll") for (int k = 0; k < 2; ++k) \
;         acc[ai][bj][m][n] = __builtin_amdgcn_mfma_f32_16x16x32_bf16(Bt[n][k], At[m][k], acc[ai][bj][m][n], 0, 0, 0); __builtin_amdgcn_s_setprio(0); } while (0)
; #define PG8_WAIT_V(n) asm volatile("s_waitcnt vmcnt(" #n ")" ::: "memory")
; #define PG8_WAIT_L(n) asm volatile("s_waitcnt lgkmcnt(" #n ")" ::: "memory")
; #define PG8_BAR __builtin_amdgcn_s_barrier()
; #define PG8_SCHED __builtin_amdgcn_sched_barrier(0)
; template <class Epi, class Sched, bool ALIGN_EPI = false, bool SP2 = false>
; __device__ __forceinline__ void gemm_phase(PG8_LAS unsigned char* lds, const Gemm g, const Sched& S, const Epi& E, const int tid) {
;     ...
;             PG8_WAIT_V(8); PG8_WAIT_L(0); PG8_BAR; PG8_MMA(0, 0, At, B0); PG8_MMA(0, 1, At, B1); PG8_BAR; PG8_SCHED;
;             PG8_LDA(At, 0, 1); PG8_STAGE(PG8_SB(0, 0), b2, voffB); PG8_STAGE(PG8_SB(0, 1), b2 + hstep, voffB); PG8_STAGE(PG8_SA(0, 0), a2, voffA);
;             PG8_WAIT_V(8); PG8_WAIT_L(0); PG8_BAR; PG8_MMA(1, 0, At, B0); PG8_MMA(1, 1, At, B1); PG8_BAR; PG8_SCHED;
;             PG8_LDB(B0, 1, 0); PG8_LDB(B1, 1, 1); PG8_SCHED; PG8_LDA(At, 1, 0); PG8_STAGE(PG8_SA(0, 1), a2 + hstep, voffA);
;             PG8_WAIT_V(8); PG8_WAIT_L(0); PG8_BAR; PG8_MMA(0, 0, At, B0); PG8_MMA(0, 1, At, B1); PG8_BAR; PG8_SCHED;
	s_setprio 0
	s_waitcnt lgkmcnt(0)
	v_mfma_f32_16x16x32_bf16 v[60:63], v[142:145], v[174:177], v[60:63]
	v_mfma_f32_16x16x32_bf16 v[52:55], v[150:153], v[174:177], v[52:55]
	v_mfma_f32_16x16x32_bf16 v[44:47], v[142:145], v[182:185], v[44:47]
	v_mfma_f32_16x16x32_bf16 v[36:39], v[150:153], v[182:185], v[36:39]
	v_mfma_f32_16x16x32_bf16 v[28:31], v[142:145], v[212:215], v[28:31]
	v_mfma_f32_16x16x32_bf16 v[20:23], v[150:153], v[212:215], v[20:23]
	v_mfma_f32_16x16x32_bf16 v[12:15], v[142:145], v[232:235], v[12:15]
	v_mfma_f32_16x16x32_bf16 v[4:7], v[150:153], v[232:235], v[4:7]
	v_mfma_f32_16x16x32_bf16 v[60:63], v[146:149], v[178:181], v[60:63]
	v_mfma_f32_16x16x32_bf16 v[52:55], v[154:157], v[178:181], v[52:55]
	v_mfma_f32_16x16x32_bf16 v[44:47], v[146:149], v[186:189], v[44:47]
	v_mfma_f32_16x16x32_bf16 v[36:39], v[154:157], v[186:189], v[36:39]
	v_mfma_f32_16x16x32_bf16 v[28:31], v[146:149], v[216:219], v[28:31]
	v_mfma_f32_16x16x32_bf16 v[20:23], v[154:157], v[216:219], v[20:23]
	v_mfma_f32_16x16x32_bf16 v[12:15], v[146:149], v[236:239], v[12:15]
	v_mfma_f32_16x16x32_bf16 v[4:7], v[154:157], v[236:239], v[4:7]
	v_mfma_f32_16x16x32_bf16 v[56:59], v[158:161], v[174:177], v[56:59]
	v_mfma_f32_16x16x32_bf16 v[48:51], v[166:169], v[174:177], v[48:51]
	v_mfma_f32_16x16x32_bf16 v[40:43], v[158:161], v[182:185], v[40:43]
	v_mfma_f32_16x16x32_bf16 v[32:35], v[166:169], v[182:185], v[32:35]
	v_mfma_f32_16x16x32_bf16 v[24:27], v[158:161], v[212:215], v[24:27]
	v_mfma_f32_16x16x32_bf16 v[16:19], v[166:169], v[212:215], v[16:19]
	v_mfma_f32_16x16x32_bf16 v[8:11], v[158:161], v[232:235], v[8:11]
	v_mfma_f32_16x16x32_bf16 v[0:3], v[166:169], v[232:235], v[0:3]
	v_mfma_f32_16x16x32_bf16 v[56:59], v[162:165], v[178:181], v[56:59]
	v_mfma_f32_16x16x32_bf16 v[48:51], v[170:173], v[178:181], v[48:51]
	v_mfma_f32_16x16x32_bf16 v[40:43], v[162:165], v[186:189], v[40:43]
	v_mfma_f32_16x16x32_bf16 v[32:35], v[170:173], v[186:189], v[32:35]
	v_mfma_f32_16x16x32_bf16 v[24:27], v[162:165], v[216:219], v[24:27]
	v_mfma_f32_16x16x32_bf16 v[16:19], v[170:173], v[216:219], v[16:19]
	v_mfma_f32_16x16x32_bf16 v[8:11], v[162:165], v[236:239], v[8:11]
	v_mfma_f32_16x16x32_bf16 v[0:3], v[170:173], v[236:239], v[0:3]
	s_setprio 1
	s_barrier
	s_add_i32 s74, 0, 0x18000
	s_add_i32 s75, 0, 0x1c000
	v_add_u32_e32 v154, s74, v140
	v_add_u32_e32 v170, s75, v140
	ds_read_b128 v[142:145], v154
	ds_read_b128 v[146:149], v154 offset:1024
	ds_read_b128 v[150:153], v154 offset:2048
	ds_read_b128 v[154:157], v154 offset:3072
	ds_read_b128 v[158:161], v170
	ds_read_b128 v[162:165], v170 offset:1024
	ds_read_b128 v[166:169], v170 offset:2048
	ds_read_b128 v[170:173], v170 offset:3072
	s_add_u32 s72, s78, 0x40000
	s_addc_u32 s73, s79, 0
	s_mov_b32 m0, s41
	v_lshl_add_u64 v[202:203], s[72:73], 0, v[132:133]
	ds_read_b128 v[174:177], v141 offset:32768
	ds_read_b128 v[178:181], v141 offset:33792
	ds_read_b128 v[182:185], v141 offset:34816
	ds_read_b128 v[186:189], v141 offset:35840
	ds_read_b128 v[212:215], v141 offset:36864
	ds_read_b128 v[216:219], v141 offset:37888
	ds_read_b128 v[232:235], v141 offset:38912
	ds_read_b128 v[236:239], v141 offset:39936
	global_load_lds_dwordx4 v[202:203], off
	v_lshl_add_u64 v[202:203], s[72:73], 0, v[130:131]
	s_mov_b32 m0, s46
	s_nop 0
	global_load_lds_dwordx4 v[202:203], off
	s_waitcnt vmcnt(8)
	s_waitcnt lgkmcnt(0)
	s_barrier
	s_setprio 0
	s_waitcnt lgkmcnt(0)
	v_mfma_f32_16x16x32_bf16 v[124:127], v[142:145], v[174:177], v[124:127]
	v_mfma_f32_16x16x32_bf16 v[116:119], v[150:153], v[174:177], v[116:119]
	v_mfma_f32_16x16x32_bf16 v[108:111], v[142:145], v[182:185], v[108:111]
	v_mfma_f32_16x16x32_bf16 v[100:103], v[150:153], v[182:185], v[100:103]
	v_mfma_f32_16x16x32_bf16 v[92:95], v[142:145], v[212:215], v[92:95]
	v_mfma_f32_16x16x32_bf16 v[84:87], v[150:153], v[212:215], v[84:87]
	v_mfma_f32_16x16x32_bf16 v[76:79], v[142:145], v[232:235], v[76:79]
	v_mfma_f32_16x16x32_bf16 v[68:71], v[150:153], v[232:235], v[68:71]
	v_mfma_f32_16x16x32_bf16 v[124:127], v[146:149], v[178:181], v[124:127]
	v_mfma_f32_16x16x32_bf16 v[116:119], v[154:157], v[178:181], v[116:119]
	v_mfma_f32_16x16x32_bf16 v[108:111], v[146:149], v[186:189], v[108:111]
	v_mfma_f32_16x16x32_bf16 v[100:103], v[154:157], v[186:189], v[100:103]
	v_mfma_f32_16x16x32_bf16 v[92:95], v[146:149], v[216:219], v[92:95]
	v_mfma_f32_16x16x32_bf16 v[84:87], v[154:157], v[216:219], v[84:87]
	v_mfma_f32_16x16x32_bf16 v[76:79], v[146:149], v[236:239], v[76:79]
	v_mfma_f32_16x16x32_bf16 v[68:71], v[154:157], v[236:239], v[68:71]
	v_mfma_f32_16x16x32_bf16 v[120:123], v[158:161], v[174:177], v[120:123]
	v_mfma_f32_16x16x32_bf16 v[112:115], v[166:169], v[174:177], v[112:115]
	v_mfma_f32_16x16x32_bf16 v[104:107], v[158:161], v[182:185], v[104:107]
	v_mfma_f32_16x16x32_bf16 v[96:99], v[166:169], v[182:185], v[96:99]
	v_mfma_f32_16x16x32_bf16 v[88:91], v[158:161], v[212:215], v[88:91]
	v_mfma_f32_16x16x32_bf16 v[80:83], v[166:169], v[212:215], v[80:83]
	v_mfma_f32_16x16x32_bf16 v[72:75], v[158:161], v[232:235], v[72:75]
	v_mfma_f32_16x16x32_bf16 v[64:67], v[166:169], v[232:235], v[64:67]
	v_mfma_f32_16x16x32_bf16 v[120:123], v[162:165], v[178:181], v[120:123]
	v_mfma_f32_16x16x32_bf16 v[112:115], v[170:173], v[178:181], v[112:115]
	v_mfma_f32_16x16x32_bf16 v[104:107], v[162:165], v[186:189], v[104:107]
	v_mfma_f32_16x16x32_bf16 v[96:99], v[170:173], v[186:189], v[96:99]
	v_mfma_f32_16x16x32_bf16 v[88:91], v[162:165], v[216:219], v[88:91]
	v_mfma_f32_16x16x32_bf16 v[80:83], v[170:173], v[216:219], v[80:83]
	v_mfma_f32_16x16x32_bf16 v[72:75], v[162:165], v[236:239], v[72:75]
	v_mfma_f32_16x16x32_bf16 v[64:67], v[170:173], v[236:239], v[64:67]
	s_setprio 1
	s_barrier
; #define PG8_STAGE(bufoff, gbase, voff) do { _Pragma("unroll") for (int _i = 0; _i < 2; ++_i) \
;         __builtin_amdgcn_global_load_lds((const unsigned*)((const char*)(gbase) + (voff)[_i]), (PG8_LAS unsigned*)(lds + (bufoff) + ldsw + _i * 8192), 16, 0, 0); } while (0)
; #define PG8_LDA(dst, b, h) do { _Pragma("unroll") for (int m = 0; m < 4; ++m) _Pragma("unroll") for (int k = 0; k < 2; ++k) dst[m][k] = *(const PG8_LAS bf16x8*)(lds + PG8_SA(b, h) + aoff + m * 2048 + k * 1024); } while (0)
; #define PG8_MMA(ai, bj, At, Bt) do { __builtin_amdgcn_s_setprio(1); _Pragma("unroll") for (int m = 0; m < 4; ++m) _Pragma("unroll") for (int n = 0; n < 2; ++n) _Pragma("unroll") for (int k = 0; k < 2; ++k) \
;         acc[ai][bj][m][n] = __builtin_amdgcn_mfma_f32_16x16x32_bf16(Bt[n][k], At[m][k], acc[ai][bj][m][n], 0, 0, 0); __builtin_amdgcn_s_setprio(0); } while (0)
; #define PG8_WAIT_V(n) asm volatile("s_waitcnt vmcnt(" #n ")" ::: "memory")
; #define PG8_WAIT_L(n) asm volatile("s_waitcnt lgkmcnt(" #n ")" ::: "memory")
; #define PG8_BAR __builtin_amdgcn_s_barrier()
; #define PG8_SCHED __builtin_amdgcn_sched_barrier(0)
; template <class Epi, class Sched, bool ALIGN_EPI = false, bool SP2 = false>
; __device__ __forceinline__ void gemm_phase(PG8_LAS unsigned char* lds, const Gemm g, const Sched& S, const Epi& E, const int tid) {
;     ...
;         for (int t = 0; t < nt; t += 2) {
;             const bool last = (t == nt - 2);
;     ...
;             PG8_LDA(At, 1, 1); PG8_STAGE(PG8_SB(1, 0), b3, voffB); PG8_STAGE(PG8_SB(1, 1), b3 + hstep, voffB); PG8_STAGE(PG8_SA(1, 0), a3, voffA);
;             PG8_WAIT_V(8); PG8_WAIT_L(0); PG8_BAR; PG8_MMA(1, 0, At, B0); PG8_MMA(1, 1, At, B1); PG8_BAR; PG8_SCHED;
;     ...
;         if constexpr (ALIGN_EPI) { if (wr == 0) PG8_BAR; }
	s_add_i32 s72, s74, s34
	v_lshl_add_u64 v[138:139], v[138:139], 0, s[36:37]
	s_mov_b32 m0, s72
	ds_read_b128 v[174:177], v141 offset:49152
	ds_read_b128 v[178:181], v141 offset:50176
	ds_read_b128 v[182:185], v141 offset:51200
	ds_read_b128 v[186:189], v141 offset:52224
	ds_read_b128 v[212:215], v141 offset:53248
	ds_read_b128 v[216:219], v141 offset:54272
	ds_read_b128 v[232:235], v141 offset:55296
	ds_read_b128 v[236:239], v141 offset:56320
	global_load_lds_dwordx4 v[138:139], off
	s_add_i32 m0, s72, 0x2000
	s_add_u32 s58, s58, 0x40080
	v_lshl_add_u64 v[138:139], v[190:191], 0, s[36:37]
	s_addc_u32 s59, s59, 0
	s_add_i32 s72, s75, s34
	global_load_lds_dwordx4 v[138:139], off
	v_lshl_add_u64 v[138:139], s[58:59], 0, v[192:193]
	s_mov_b32 m0, s72
	s_nop 0
	global_load_lds_dwordx4 v[138:139], off
	v_lshl_add_u64 v[138:139], s[58:59], 0, v[128:129]
	s_add_i32 m0, s72, 0x2000
	s_nop 0
	global_load_lds_dwordx4 v[138:139], off
	v_lshl_add_u64 v[138:139], v[194:195], 0, s[36:37]
	s_mov_b32 m0, s47
	s_nop 0
	global_load_lds_dwordx4 v[138:139], off
	v_lshl_add_u64 v[138:139], v[196:197], 0, s[36:37]
	s_mov_b32 m0, s52
	s_nop 0
	global_load_lds_dwordx4 v[138:139], off
	s_waitcnt vmcnt(8)
	s_waitcnt lgkmcnt(0)
	s_barrier
	s_setprio 0
	s_waitcnt lgkmcnt(0)
	v_mfma_f32_16x16x32_bf16 v[60:63], v[142:145], v[174:177], v[60:63]
	v_mfma_f32_16x16x32_bf16 v[52:55], v[150:153], v[174:177], v[52:55]
	v_mfma_f32_16x16x32_bf16 v[44:47], v[142:145], v[182:185], v[44:47]
	v_mfma_f32_16x16x32_bf16 v[36:39], v[150:153], v[182:185], v[36:39]
	v_mfma_f32_16x16x32_bf16 v[28:31], v[142:145], v[212:215], v[28:31]
	v_mfma_f32_16x16x32_bf16 v[20:23], v[150:153], v[212:215], v[20:23]
	v_mfma_f32_16x16x32_bf16 v[12:15], v[142:145], v[232:235], v[12:15]
	v_mfma_f32_16x16x32_bf16 v[4:7], v[150:153], v[232:235], v[4:7]
	v_mfma_f32_16x16x32_bf16 v[60:63], v[146:149], v[178:181], v[60:63]
	v_mfma_f32_16x16x32_bf16 v[52:55], v[154:157], v[178:181], v[52:55]
	v_mfma_f32_16x16x32_bf16 v[44:47], v[146:149], v[186:189], v[44:47]
	v_mfma_f32_16x16x32_bf16 v[36:39], v[154:157], v[186:189], v[36:39]
	v_mfma_f32_16x16x32_bf16 v[28:31], v[146:149], v[216:219], v[28:31]
	v_mfma_f32_16x16x32_bf16 v[20:23], v[154:157], v[216:219], v[20:23]
	v_mfma_f32_16x16x32_bf16 v[12:15], v[146:149], v[236:239], v[12:15]
	v_mfma_f32_16x16x32_bf16 v[4:7], v[154:157], v[236:239], v[4:7]
	v_mfma_f32_16x16x32_bf16 v[56:59], v[158:161], v[174:177], v[56:59]
	v_mfma_f32_16x16x32_bf16 v[48:51], v[166:169], v[174:177], v[48:51]
	v_mfma_f32_16x16x32_bf16 v[40:43], v[158:161], v[182:185], v[40:43]
	v_mfma_f32_16x16x32_bf16 v[32:35], v[166:169], v[182:185], v[32:35]
	v_mfma_f32_16x16x32_bf16 v[24:27], v[158:161], v[212:215], v[24:27]
	v_mfma_f32_16x16x32_bf16 v[16:19], v[166:169], v[212:215], v[16:19]
	v_mfma_f32_16x16x32_bf16 v[8:11], v[158:161], v[232:235], v[8:11]
	v_mfma_f32_16x16x32_bf16 v[0:3], v[166:169], v[232:235], v[0:3]
	v_mfma_f32_16x16x32_bf16 v[56:59], v[162:165], v[178:181], v[56:59]
	v_mfma_f32_16x16x32_bf16 v[48:51], v[170:173], v[178:181], v[48:51]
	v_mfma_f32_16x16x32_bf16 v[40:43], v[162:165], v[186:189], v[40:43]
	v_mfma_f32_16x16x32_bf16 v[32:35], v[170:173], v[186:189], v[32:35]
	v_mfma_f32_16x16x32_bf16 v[24:27], v[162:165], v[216:219], v[24:27]
	v_mfma_f32_16x16x32_bf16 v[16:19], v[170:173], v[216:219], v[16:19]
	v_mfma_f32_16x16x32_bf16 v[8:11], v[162:165], v[236:239], v[8:11]
	v_mfma_f32_16x16x32_bf16 v[0:3], v[170:173], v[236:239], v[0:3]
	s_setprio 1
	s_barrier
	s_add_i32 s71, s71, 2
	s_add_u32 s44, s44, 0x100
	s_addc_u32 s45, s45, 0
	s_add_u32 s62, s62, 0x100
	s_addc_u32 s70, s70, 0
	s_cmp_gt_u32 s71, 13
	s_cbranch_scc0 .LBB0_143
	s_and_b64 vcc, exec, s[10:11]
	s_cbranch_vccz .LBB0_146
	s_barrier

; #define PG8_STAGE(bufoff, gbase, voff) do { _Pragma("unroll") for (int _i = 0; _i < 2; ++_i) \
;         __builtin_amdgcn_global_load_lds((const unsigned*)((const char*)(gbase) + (voff)[_i]), (PG8_LAS unsigned*)(lds + (bufoff) + ldsw + _i * 8192), 16, 0, 0); } while (0)
; #define PG8_LDA(dst, b, h) do { _Pragma("unroll") for (int m = 0; m < 4; ++m) _Pragma("unroll") for (int k = 0; k < 2; ++k) dst[m][k] = *(const PG8_LAS bf16x8*)(lds + PG8_SA(b, h) + aoff + m * 2048 + k * 1024); } while (0)
; #define PG8_LDB(dst, b, h) do { _Pragma("unroll") for (int n = 0; n < 2; ++n) _Pragma("unroll") for (int k = 0; k < 2; ++k) dst[n][k] = *(const PG8_LAS bf16x8*)(lds + PG8_SB(b, h) + boff + n * 2048 + k * 1024); } while (0)
; #define PG8_MMA(ai, bj, At, Bt) do { __builtin_amdgcn_s_setprio(1); _Pragma("unroll") for (int m = 0; m < 4; ++m) _Pragma("unroll") for (int n = 0; n < 2; ++n) _Pragma("unroll") for (int k = 0; k < 2; ++k) \
;         acc[ai][bj][m][n] = __builtin_amdgcn_mfma_f32_16x16x32_bf16(Bt[n][k], At[m][k], acc[ai][bj][m][n], 0, 0, 0); __builtin_amdgcn_s_setprio(0); } while (0)
; #define PG8_WAIT_V(n) asm volatile("s_waitcnt vmcnt(" #n ")" ::: "memory")
; #define PG8_WAIT_L(n) asm volatile("s_waitcnt lgkmcnt(" #n ")" ::: "memory")
; #define PG8_BAR __builtin_amdgcn_s_barrier()
; #define PG8_SCHED __builtin_amdgcn_sched_barrier(0)
; template <class Epi, class Sched, bool ALIGN_EPI = false, bool SP2 = false>
; __device__ __forceinline__ void gemm_phase(PG8_LAS unsigned char* lds, const Gemm g, const Sched& S, const Epi& E, const int tid) {
;     ...
;             const bool last = (t == nt - 2);
;             const char* a1 = cA + (size_t)(t + 1) * kstep;
;             const char* a2 = last ? nA : cA + (size_t)(t + 2) * kstep; const char* b2 = last ? nB : cB + (size_t)(t + 2) * kstep;
;             const char* a3 = a2 + kstep; const char* b3 = b2 + kstep;
;             if (last && has_next) S.a_ready(nxt);
;             if constexpr (SP2) {
;             PG8_LDB(B0, 0, 0); PG8_LDB(B1, 0, 1); PG8_SCHED; PG8_LDA(At, 0, 0); PG8_STAGE(PG8_SA(1, 1), a1 + hstep, voffA);
;             PG8_WAIT_V(8); PG8_WAIT_L(0); PG8_BAR; PG8_MMA(0, 0, At, B0); PG8_MMA(0, 1, At, B1); PG8_BAR; PG8_SCHED;
;             PG8_LDA(At, 0, 1); PG8_STAGE(PG8_SB(0, 0), b2, voffB); PG8_STAGE(PG8_SB(0, 1), b2 + hstep, voffB); PG8_STAGE(PG8_SA(0, 0), a2, voffA);
.LBB0_183:
	s_add_u32 s28, s22, 0xfffc0080
	s_addc_u32 s29, s23, -1
	s_add_i32 s71, 0, 0x10000
	s_cmp_eq_u32 s70, 12
	s_cselect_b32 s45, s17, s29
	s_cselect_b32 s44, s58, s28
	s_cselect_b32 s29, s13, s62
	s_cselect_b32 s28, s59, s60
	s_add_i32 s74, 0, 0x14000
	v_add_u32_e32 v154, s71, v140
	v_add_u32_e32 v170, s74, v140
	ds_read_b128 v[142:145], v154
	ds_read_b128 v[146:149], v154 offset:1024
	ds_read_b128 v[150:153], v154 offset:2048
	ds_read_b128 v[154:157], v154 offset:3072
	ds_read_b128 v[158:161], v170
	ds_read_b128 v[162:165], v170 offset:1024
	ds_read_b128 v[166:169], v170 offset:2048
	ds_read_b128 v[170:173], v170 offset:3072
	v_lshl_add_u64 v[190:191], s[22:23], 0, v[136:137]
	s_add_i32 m0, s15, 0xc000
	ds_read_b128 v[174:177], v141
	ds_read_b128 v[178:181], v141 offset:1024
	ds_read_b128 v[182:185], v141 offset:2048
	ds_read_b128 v[186:189], v141 offset:3072
	ds_read_b128 v[212:215], v141 offset:4096
	ds_read_b128 v[216:219], v141 offset:5120
	ds_read_b128 v[232:235], v141 offset:6144
	ds_read_b128 v[236:239], v141 offset:7168
	global_load_lds_dwordx4 v[190:191], off
	v_lshl_add_u64 v[190:191], s[22:23], 0, v[138:139]
	s_add_i32 m0, s15, 0xe000
	s_nop 0
	global_load_lds_dwordx4 v[190:191], off
	s_waitcnt vmcnt(8)
	s_waitcnt lgkmcnt(0)
	s_barrier
	s_setprio 0
	s_waitcnt lgkmcnt(0)
	v_mfma_f32_16x16x32_bf16 v[124:127], v[142:145], v[174:177], v[124:127]
	v_mfma_f32_16x16x32_bf16 v[120:123], v[150:153], v[174:177], v[120:123]
	v_mfma_f32_16x16x32_bf16 v[116:119], v[142:145], v[182:185], v[116:119]
	v_mfma_f32_16x16x32_bf16 v[112:115], v[150:153], v[182:185], v[112:115]
	v_mfma_f32_16x16x32_bf16 v[100:103], v[142:145], v[212:215], v[100:103]
	v_mfma_f32_16x16x32_bf16 v[96:99], v[150:153], v[212:215], v[96:99]
	v_mfma_f32_16x16x32_bf16 v[84:87], v[142:145], v[232:235], v[84:87]
	v_mfma_f32_16x16x32_bf16 v[80:83], v[150:153], v[232:235], v[80:83]
	v_mfma_f32_16x16x32_bf16 v[124:127], v[146:149], v[178:181], v[124:127]
	v_mfma_f32_16x16x32_bf16 v[120:123], v[154:157], v[178:181], v[120:123]
	v_mfma_f32_16x16x32_bf16 v[116:119], v[146:149], v[186:189], v[116:119]
	v_mfma_f32_16x16x32_bf16 v[112:115], v[154:157], v[186:189], v[112:115]
	v_mfma_f32_16x16x32_bf16 v[100:103], v[146:149], v[216:219], v[100:103]
	v_mfma_f32_16x16x32_bf16 v[96:99], v[154:157], v[216:219], v[96:99]
	v_mfma_f32_16x16x32_bf16 v[84:87], v[146:149], v[236:239], v[84:87]
	v_mfma_f32_16x16x32_bf16 v[80:83], v[154:157], v[236:239], v[80:83]
	v_mfma_f32_16x16x32_bf16 v[108:111], v[158:161], v[174:177], v[108:111]
	v_mfma_f32_16x16x32_bf16 v[104:107], v[166:169], v[174:177], v[104:107]
	v_mfma_f32_16x16x32_bf16 v[92:95], v[158:161], v[182:185], v[92:95]
	v_mfma_f32_16x16x32_bf16 v[88:91], v[166:169], v[182:185], v[88:91]
	v_mfma_f32_16x16x32_bf16 v[76:79], v[158:161], v[212:215], v[76:79]
	v_mfma_f32_16x16x32_bf16 v[72:75], v[166:169], v[212:215], v[72:75]
	v_mfma_f32_16x16x32_bf16 v[68:71], v[158:161], v[232:235], v[68:71]
	v_mfma_f32_16x16x32_bf16 v[64:67], v[166:169], v[232:235], v[64:67]
	v_mfma_f32_16x16x32_bf16 v[108:111], v[162:165], v[178:181], v[108:111]
	v_mfma_f32_16x16x32_bf16 v[104:107], v[170:173], v[178:181], v[104:107]
	v_mfma_f32_16x16x32_bf16 v[92:95], v[162:165], v[186:189], v[92:95]
	v_mfma_f32_16x16x32_bf16 v[88:91], v[170:173], v[186:189], v[88:91]
	v_mfma_f32_16x16x32_bf16 v[76:79], v[162:165], v[216:219], v[76:79]
	v_mfma_f32_16x16x32_bf16 v[72:75], v[170:173], v[216:219], v[72:75]
	v_mfma_f32_16x16x32_bf16 v[68:71], v[162:165], v[236:239], v[68:71]
	v_mfma_f32_16x16x32_bf16 v[64:67], v[170:173], v[236:239], v[64:67]
	s_setprio 1
	s_barrier
	s_add_i32 s71, s71, s38
	v_lshl_add_u64 v[190:191], s[28:29], 0, v[192:193]
	s_mov_b32 m0, s71
	ds_read_b128 v[174:177], v141 offset:16384
	ds_read_b128 v[178:181], v141 offset:17408
	ds_read_b128 v[182:185], v141 offset:18432
	ds_read_b128 v[186:189], v141 offset:19456
	ds_read_b128 v[212:215], v141 offset:20480
	ds_read_b128 v[216:219], v141 offset:21504
	ds_read_b128 v[232:235], v141 offset:22528
	ds_read_b128 v[236:239], v141 offset:23552
	global_load_lds_dwordx4 v[190:191], off
	s_add_i32 m0, s71, 0x2000
	s_add_u32 s72, s28, 0x40000
	v_lshl_add_u64 v[194:195], s[28:29], 0, v[132:133]
	s_addc_u32 s73, s29, 0
	s_add_i32 s71, s74, s38
	global_load_lds_dwordx4 v[194:195], off
	v_lshl_add_u64 v[196:197], s[72:73], 0, v[192:193]
	s_mov_b32 m0, s71
	v_lshl_add_u64 v[202:203], s[44:45], 0, v[130:131]
	global_load_lds_dwordx4 v[196:197], off
	v_lshl_add_u64 v[196:197], s[72:73], 0, v[132:133]
	s_add_i32 m0, s71, 0x2000
	s_nop 0
	global_load_lds_dwordx4 v[196:197], off
	v_lshl_add_u64 v[196:197], s[44:45], 0, v[128:129]
	s_mov_b32 m0, s15
	s_nop 0
	global_load_lds_dwordx4 v[196:197], off
	s_mov_b32 m0, s40
	s_nop 0
	global_load_lds_dwordx4 v[202:203], off
	s_waitcnt vmcnt(8)
	s_waitcnt lgkmcnt(0)
	s_barrier
; #define PG8_STAGE(bufoff, gbase, voff) do { _Pragma("unroll") for (int _i = 0; _i < 2; ++_i) \
;         __builtin_amdgcn_global_load_lds((const unsigned*)((const char*)(gbase) + (voff)[_i]), (PG8_LAS unsigned*)(lds + (bufoff) + ldsw + _i * 8192), 16, 0, 0); } while (0)
; #define PG8_LDA(dst, b, h) do { _Pragma("unroll") for (int m = 0; m < 4; ++m) _Pragma("unroll") for (int k = 0; k < 2; ++k) dst[m][k] = *(const PG8_LAS bf16x8*)(lds + PG8_SA(b, h) + aoff + m * 2048 + k * 1024); } while (0)
; #define PG8_LDB(dst, b, h) do { _Pragma("unroll") for (int n = 0; n < 2; ++n) _Pragma("unroll") for (int k = 0; k < 2; ++k) dst[n][k] = *(const PG8_LAS bf16x8*)(lds + PG8_SB(b, h) + boff + n * 2048 + k * 1024); } while (0)
; #define PG8_MMA(ai, bj, At, Bt) do { __builtin_amdgcn_s_setprio(1); _Pragma("unroll") for (int m = 0; m < 4; ++m) _Pragma("unroll") for (int n = 0; n < 2; ++n) _Pragma("unroll") for (int k = 0; k < 2; ++k) \
;         acc[ai][bj][m][n] = __builtin_amdgcn_mfma_f32_16x16x32_bf16(Bt[n][k], At[m][k], acc[ai][bj][m][n], 0, 0, 0); __builtin_amdgcn_s_setprio(0); } while (0)
; #define PG8_WAIT_V(n) asm volatile("s_waitcnt vmcnt(" #n ")" ::: "memory")
; #define PG8_WAIT_L(n) asm volatile("s_waitcnt lgkmcnt(" #n ")" ::: "memory")
; #define PG8_BAR __builtin_amdgcn_s_barrier()
; #define PG8_SCHED __builtin_amdgcn_sched_barrier(0)
; template <class Epi, class Sched, bool ALIGN_EPI = false, bool SP2 = false>
; __device__ __forceinline__ void gemm_phase(PG8_LAS unsigned char* lds, const Gemm g, const Sched& S, const Epi& E, const int tid) {
;     ...
;             PG8_WAIT_V(8); PG8_WAIT_L(0); PG8_BAR; PG8_MMA(1, 0, At, B0); PG8_MMA(1, 1, At, B1); PG8_BAR; PG8_SCHED;
;             PG8_LDB(B0, 1, 0); PG8_LDB(B1, 1, 1); PG8_SCHED; PG8_LDA(At, 1, 0); PG8_STAGE(PG8_SA(0, 1), a2 + hstep, voffA);
;             PG8_WAIT_V(8); PG8_WAIT_L(0); PG8_BAR; PG8_MMA(0, 0, At, B0); PG8_MMA(0, 1, At, B1); PG8_BAR; PG8_SCHED;
	s_setprio 0
	s_waitcnt lgkmcnt(0)
	v_mfma_f32_16x16x32_bf16 v[60:63], v[142:145], v[174:177], v[60:63]
	v_mfma_f32_16x16x32_bf16 v[56:59], v[150:153], v[174:177], v[56:59]
	v_mfma_f32_16x16x32_bf16 v[52:55], v[142:145], v[182:185], v[52:55]
	v_mfma_f32_16x16x32_bf16 v[48:51], v[150:153], v[182:185], v[48:51]
	v_mfma_f32_16x16x32_bf16 v[36:39], v[142:145], v[212:215], v[36:39]
	v_mfma_f32_16x16x32_bf16 v[32:35], v[150:153], v[212:215], v[32:35]
	v_mfma_f32_16x16x32_bf16 v[20:23], v[142:145], v[232:235], v[20:23]
	v_mfma_f32_16x16x32_bf16 v[16:19], v[150:153], v[232:235], v[16:19]
	v_mfma_f32_16x16x32_bf16 v[60:63], v[146:149], v[178:181], v[60:63]
	v_mfma_f32_16x16x32_bf16 v[56:59], v[154:157], v[178:181], v[56:59]
	v_mfma_f32_16x16x32_bf16 v[52:55], v[146:149], v[186:189], v[52:55]
	v_mfma_f32_16x16x32_bf16 v[48:51], v[154:157], v[186:189], v[48:51]
	v_mfma_f32_16x16x32_bf16 v[36:39], v[146:149], v[216:219], v[36:39]
	v_mfma_f32_16x16x32_bf16 v[32:35], v[154:157], v[216:219], v[32:35]
	v_mfma_f32_16x16x32_bf16 v[20:23], v[146:149], v[236:239], v[20:23]
	v_mfma_f32_16x16x32_bf16 v[16:19], v[154:157], v[236:239], v[16:19]
	v_mfma_f32_16x16x32_bf16 v[44:47], v[158:161], v[174:177], v[44:47]
	v_mfma_f32_16x16x32_bf16 v[40:43], v[166:169], v[174:177], v[40:43]
	v_mfma_f32_16x16x32_bf16 v[28:31], v[158:161], v[182:185], v[28:31]
	v_mfma_f32_16x16x32_bf16 v[24:27], v[166:169], v[182:185], v[24:27]
	v_mfma_f32_16x16x32_bf16 v[12:15], v[158:161], v[212:215], v[12:15]
	v_mfma_f32_16x16x32_bf16 v[8:11], v[166:169], v[212:215], v[8:11]
	v_mfma_f32_16x16x32_bf16 v[4:7], v[158:161], v[232:235], v[4:7]
	v_mfma_f32_16x16x32_bf16 v[0:3], v[166:169], v[232:235], v[0:3]
	v_mfma_f32_16x16x32_bf16 v[44:47], v[162:165], v[178:181], v[44:47]
	v_mfma_f32_16x16x32_bf16 v[40:43], v[170:173], v[178:181], v[40:43]
	v_mfma_f32_16x16x32_bf16 v[28:31], v[162:165], v[186:189], v[28:31]
	v_mfma_f32_16x16x32_bf16 v[24:27], v[170:173], v[186:189], v[24:27]
	v_mfma_f32_16x16x32_bf16 v[12:15], v[162:165], v[216:219], v[12:15]
	v_mfma_f32_16x16x32_bf16 v[8:11], v[170:173], v[216:219], v[8:11]
	v_mfma_f32_16x16x32_bf16 v[4:7], v[162:165], v[236:239], v[4:7]
	v_mfma_f32_16x16x32_bf16 v[0:3], v[170:173], v[236:239], v[0:3]
	s_setprio 1
	s_barrier
	s_add_i32 s71, 0, 0x18000
	s_add_i32 s72, 0, 0x1c000
	v_add_u32_e32 v154, s71, v140
	v_add_u32_e32 v170, s72, v140
	ds_read_b128 v[142:145], v154
	ds_read_b128 v[146:149], v154 offset:1024
	ds_read_b128 v[150:153], v154 offset:2048
	ds_read_b128 v[154:157], v154 offset:3072
	ds_read_b128 v[158:161], v170
	ds_read_b128 v[162:165], v170 offset:1024
	ds_read_b128 v[166:169], v170 offset:2048
	ds_read_b128 v[170:173], v170 offset:3072
	s_add_u32 s44, s44, 0x40000
	s_addc_u32 s45, s45, 0
	s_mov_b32 m0, s41
	v_lshl_add_u64 v[204:205], s[44:45], 0, v[128:129]
	ds_read_b128 v[174:177], v141 offset:32768
	ds_read_b128 v[178:181], v141 offset:33792
	ds_read_b128 v[182:185], v141 offset:34816
	ds_read_b128 v[186:189], v141 offset:35840
	ds_read_b128 v[212:215], v141 offset:36864
	ds_read_b128 v[216:219], v141 offset:37888
	ds_read_b128 v[232:235], v141 offset:38912
	ds_read_b128 v[236:239], v141 offset:39936
	global_load_lds_dwordx4 v[204:205], off
	v_lshl_add_u64 v[204:205], s[44:45], 0, v[130:131]
	s_mov_b32 m0, s46
	s_nop 0
	global_load_lds_dwordx4 v[204:205], off
	s_waitcnt vmcnt(8)
	s_waitcnt lgkmcnt(0)
	s_barrier
	s_setprio 0
	s_waitcnt lgkmcnt(0)
	v_mfma_f32_16x16x32_bf16 v[124:127], v[142:145], v[174:177], v[124:127]
	v_mfma_f32_16x16x32_bf16 v[120:123], v[150:153], v[174:177], v[120:123]
	v_mfma_f32_16x16x32_bf16 v[116:119], v[142:145], v[182:185], v[116:119]
	v_mfma_f32_16x16x32_bf16 v[112:115], v[150:153], v[182:185], v[112:115]
	v_mfma_f32_16x16x32_bf16 v[100:103], v[142:145], v[212:215], v[100:103]
	v_mfma_f32_16x16x32_bf16 v[96:99], v[150:153], v[212:215], v[96:99]
	v_mfma_f32_16x16x32_bf16 v[84:87], v[142:145], v[232:235], v[84:87]
	v_mfma_f32_16x16x32_bf16 v[80:83], v[150:153], v[232:235], v[80:83]
	v_mfma_f32_16x16x32_bf16 v[124:127], v[146:149], v[178:181], v[124:127]
	v_mfma_f32_16x16x32_bf16 v[120:123], v[154:157], v[178:181], v[120:123]
	v_mfma_f32_16x16x32_bf16 v[116:119], v[146:149], v[186:189], v[116:119]
	v_mfma_f32_16x16x32_bf16 v[112:115], v[154:157], v[186:189], v[112:115]
	v_mfma_f32_16x16x32_bf16 v[100:103], v[146:149], v[216:219], v[100:103]
	v_mfma_f32_16x16x32_bf16 v[96:99], v[154:157], v[216:219], v[96:99]
	v_mfma_f32_16x16x32_bf16 v[84:87], v[146:149], v[236:239], v[84:87]
	v_mfma_f32_16x16x32_bf16 v[80:83], v[154:157], v[236:239], v[80:83]
	v_mfma_f32_16x16x32_bf16 v[108:111], v[158:161], v[174:177], v[108:111]
	v_mfma_f32_16x16x32_bf16 v[104:107], v[166:169], v[174:177], v[104:107]
	v_mfma_f32_16x16x32_bf16 v[92:95], v[158:161], v[182:185], v[92:95]
	v_mfma_f32_16x16x32_bf16 v[88:91], v[166:169], v[182:185], v[88:91]
	v_mfma_f32_16x16x32_bf16 v[76:79], v[158:161], v[212:215], v[76:79]
	v_mfma_f32_16x16x32_bf16 v[72:75], v[166:169], v[212:215], v[72:75]
	v_mfma_f32_16x16x32_bf16 v[68:71], v[158:161], v[232:235], v[68:71]
	v_mfma_f32_16x16x32_bf16 v[64:67], v[166:169], v[232:235], v[64:67]
	v_mfma_f32_16x16x32_bf16 v[108:111], v[162:165], v[178:181], v[108:111]
	v_mfma_f32_16x16x32_bf16 v[104:107], v[170:173], v[178:181], v[104:107]
	v_mfma_f32_16x16x32_bf16 v[92:95], v[162:165], v[186:189], v[92:95]
	v_mfma_f32_16x16x32_bf16 v[88:91], v[170:173], v[186:189], v[88:91]
	v_mfma_f32_16x16x32_bf16 v[76:79], v[162:165], v[216:219], v[76:79]
	v_mfma_f32_16x16x32_bf16 v[72:75], v[170:173], v[216:219], v[72:75]
	v_mfma_f32_16x16x32_bf16 v[68:71], v[162:165], v[236:239], v[68:71]
	v_mfma_f32_16x16x32_bf16 v[64:67], v[170:173], v[236:239], v[64:67]
	s_setprio 1
	s_barrier
; #define PG8_STAGE(bufoff, gbase, voff) do { _Pragma("unroll") for (int _i = 0; _i < 2; ++_i) \
;         __builtin_amdgcn_global_load_lds((const unsigned*)((const char*)(gbase) + (voff)[_i]), (PG8_LAS unsigned*)(lds + (bufoff) + ldsw + _i * 8192), 16, 0, 0); } while (0)
; #define PG8_LDA(dst, b, h) do { _Pragma("unroll") for (int m = 0; m < 4; ++m) _Pragma("unroll") for (int k = 0; k < 2; ++k) dst[m][k] = *(const PG8_LAS bf16x8*)(lds + PG8_SA(b, h) + aoff + m * 2048 + k * 1024); } while (0)
; #define PG8_MMA(ai, bj, At, Bt) do { __builtin_amdgcn_s_setprio(1); _Pragma("unroll") for (int m = 0; m < 4; ++m) _Pragma("unroll") for (int n = 0; n < 2; ++n) _Pragma("unroll") for (int k = 0; k < 2; ++k) \
;         acc[ai][bj][m][n] = __builtin_amdgcn_mfma_f32_16x16x32_bf16(Bt[n][k], At[m][k], acc[ai][bj][m][n], 0, 0, 0); __builtin_amdgcn_s_setprio(0); } while (0)
; #define PG8_WAIT_V(n) asm volatile("s_waitcnt vmcnt(" #n ")" ::: "memory")
; #define PG8_WAIT_L(n) asm volatile("s_waitcnt lgkmcnt(" #n ")" ::: "memory")
; #define PG8_BAR __builtin_amdgcn_s_barrier()
; #define PG8_SCHED __builtin_amdgcn_sched_barrier(0)
; template <class Epi, class Sched, bool ALIGN_EPI = false, bool SP2 = false>
; __device__ __forceinline__ void gemm_phase(PG8_LAS unsigned char* lds, const Gemm g, const Sched& S, const Epi& E, const int tid) {
;     ...
;         for (int t = 0; t < nt; t += 2) {
;     ...
;             PG8_LDA(At, 1, 1); PG8_STAGE(PG8_SB(1, 0), b3, voffB); PG8_STAGE(PG8_SB(1, 1), b3 + hstep, voffB); PG8_STAGE(PG8_SA(1, 0), a3, voffA);
;             PG8_WAIT_V(8); PG8_WAIT_L(0); PG8_BAR; PG8_MMA(1, 0, At, B0); PG8_MMA(1, 1, At, B1); PG8_BAR; PG8_SCHED;
;     ...
;         if constexpr (ALIGN_EPI) { if (wr == 0) PG8_BAR; }
	s_add_i32 s44, s71, s38
	v_lshl_add_u64 v[190:191], v[190:191], 0, s[36:37]
	s_mov_b32 m0, s44
	ds_read_b128 v[174:177], v141 offset:49152
	ds_read_b128 v[178:181], v141 offset:50176
	ds_read_b128 v[182:185], v141 offset:51200
	ds_read_b128 v[186:189], v141 offset:52224
	ds_read_b128 v[212:215], v141 offset:53248
	ds_read_b128 v[216:219], v141 offset:54272
	ds_read_b128 v[232:235], v141 offset:55296
	ds_read_b128 v[236:239], v141 offset:56320
	global_load_lds_dwordx4 v[190:191], off
	s_add_i32 m0, s44, 0x2000
	s_add_u32 s28, s28, 0x40080
	v_lshl_add_u64 v[190:191], v[194:195], 0, s[36:37]
	s_addc_u32 s29, s29, 0
	s_add_i32 s44, s72, s38
	global_load_lds_dwordx4 v[190:191], off
	v_lshl_add_u64 v[190:191], s[28:29], 0, v[192:193]
	s_mov_b32 m0, s44
	s_nop 0
	global_load_lds_dwordx4 v[190:191], off
	v_lshl_add_u64 v[190:191], s[28:29], 0, v[132:133]
	s_add_i32 m0, s44, 0x2000
	s_nop 0
	global_load_lds_dwordx4 v[190:191], off
	v_lshl_add_u64 v[190:191], v[196:197], 0, s[36:37]
	s_mov_b32 m0, s47
	s_nop 0
	global_load_lds_dwordx4 v[190:191], off
	v_lshl_add_u64 v[190:191], v[202:203], 0, s[36:37]
	s_mov_b32 m0, s52
	s_nop 0
	global_load_lds_dwordx4 v[190:191], off
	s_waitcnt vmcnt(8)
	s_waitcnt lgkmcnt(0)
	s_barrier
	s_setprio 0
	s_waitcnt lgkmcnt(0)
	v_mfma_f32_16x16x32_bf16 v[60:63], v[142:145], v[174:177], v[60:63]
	v_mfma_f32_16x16x32_bf16 v[56:59], v[150:153], v[174:177], v[56:59]
	v_mfma_f32_16x16x32_bf16 v[52:55], v[142:145], v[182:185], v[52:55]
	v_mfma_f32_16x16x32_bf16 v[48:51], v[150:153], v[182:185], v[48:51]
	v_mfma_f32_16x16x32_bf16 v[36:39], v[142:145], v[212:215], v[36:39]
	v_mfma_f32_16x16x32_bf16 v[32:35], v[150:153], v[212:215], v[32:35]
	v_mfma_f32_16x16x32_bf16 v[20:23], v[142:145], v[232:235], v[20:23]
	v_mfma_f32_16x16x32_bf16 v[16:19], v[150:153], v[232:235], v[16:19]
	v_mfma_f32_16x16x32_bf16 v[60:63], v[146:149], v[178:181], v[60:63]
	v_mfma_f32_16x16x32_bf16 v[56:59], v[154:157], v[178:181], v[56:59]
	v_mfma_f32_16x16x32_bf16 v[52:55], v[146:149], v[186:189], v[52:55]
	v_mfma_f32_16x16x32_bf16 v[48:51], v[154:157], v[186:189], v[48:51]
	v_mfma_f32_16x16x32_bf16 v[36:39], v[146:149], v[216:219], v[36:39]
	v_mfma_f32_16x16x32_bf16 v[32:35], v[154:157], v[216:219], v[32:35]
	v_mfma_f32_16x16x32_bf16 v[20:23], v[146:149], v[236:239], v[20:23]
	v_mfma_f32_16x16x32_bf16 v[16:19], v[154:157], v[236:239], v[16:19]
	v_mfma_f32_16x16x32_bf16 v[44:47], v[158:161], v[174:177], v[44:47]
	v_mfma_f32_16x16x32_bf16 v[40:43], v[166:169], v[174:177], v[40:43]
	v_mfma_f32_16x16x32_bf16 v[28:31], v[158:161], v[182:185], v[28:31]
	v_mfma_f32_16x16x32_bf16 v[24:27], v[166:169], v[182:185], v[24:27]
	v_mfma_f32_16x16x32_bf16 v[12:15], v[158:161], v[212:215], v[12:15]
	v_mfma_f32_16x16x32_bf16 v[8:11], v[166:169], v[212:215], v[8:11]
	v_mfma_f32_16x16x32_bf16 v[4:7], v[158:161], v[232:235], v[4:7]
	v_mfma_f32_16x16x32_bf16 v[0:3], v[166:169], v[232:235], v[0:3]
	v_mfma_f32_16x16x32_bf16 v[44:47], v[162:165], v[178:181], v[44:47]
	v_mfma_f32_16x16x32_bf16 v[40:43], v[170:173], v[178:181], v[40:43]
	v_mfma_f32_16x16x32_bf16 v[28:31], v[162:165], v[186:189], v[28:31]
	v_mfma_f32_16x16x32_bf16 v[24:27], v[170:173], v[186:189], v[24:27]
	v_mfma_f32_16x16x32_bf16 v[12:15], v[162:165], v[216:219], v[12:15]
	v_mfma_f32_16x16x32_bf16 v[8:11], v[170:173], v[216:219], v[8:11]
	v_mfma_f32_16x16x32_bf16 v[4:7], v[162:165], v[236:239], v[4:7]
	v_mfma_f32_16x16x32_bf16 v[0:3], v[170:173], v[236:239], v[0:3]
	s_setprio 1
	s_barrier
	s_add_i32 s70, s70, 2
	s_add_u32 s22, s22, 0x100
	s_addc_u32 s23, s23, 0
	s_add_u32 s60, s60, 0x100
	s_addc_u32 s62, s62, 0
	s_cmp_gt_u32 s70, 13
	s_cbranch_scc0 .LBB0_183
	s_and_b64 vcc, exec, s[10:11]
	s_cbranch_vccz .LBB0_186
	s_barrier

; #define PG8_STAGE(bufoff, gbase, voff) do { _Pragma("unroll") for (int _i = 0; _i < 2; ++_i) \
;         __builtin_amdgcn_global_load_lds((const unsigned*)((const char*)(gbase) + (voff)[_i]), (PG8_LAS unsigned*)(lds + (bufoff) + ldsw + _i * 8192), 16, 0, 0); } while (0)
; #define PG8_LDA(dst, b, h) do { _Pragma("unroll") for (int m = 0; m < 4; ++m) _Pragma("unroll") for (int k = 0; k < 2; ++k) dst[m][k] = *(const PG8_LAS bf16x8*)(lds + PG8_SA(b, h) + aoff + m * 2048 + k * 1024); } while (0)
; #define PG8_LDB(dst, b, h) do { _Pragma("unroll") for (int n = 0; n < 2; ++n) _Pragma("unroll") for (int k = 0; k < 2; ++k) dst[n][k] = *(const PG8_LAS bf16x8*)(lds + PG8_SB(b, h) + boff + n * 2048 + k * 1024); } while (0)
; #define PG8_MMA(ai, bj, At, Bt) do { __builtin_amdgcn_s_setprio(1); _Pragma("unroll") for (int m = 0; m < 4; ++m) _Pragma("unroll") for (int n = 0; n < 2; ++n) _Pragma("unroll") for (int k = 0; k < 2; ++k) \
;         acc[ai][bj][m][n] = __builtin_amdgcn_mfma_f32_16x16x32_bf16(Bt[n][k], At[m][k], acc[ai][bj][m][n], 0, 0, 0); __builtin_amdgcn_s_setprio(0); } while (0)
; #define PG8_WAIT_V(n) asm volatile("s_waitcnt vmcnt(" #n ")" ::: "memory")
; #define PG8_WAIT_L(n) asm volatile("s_waitcnt lgkmcnt(" #n ")" ::: "memory")
; #define PG8_BAR __builtin_amdgcn_s_barrier()
; template <class Epi, class Sched, bool ALIGN_EPI = false, bool SP2 = false>
; __device__ __forceinline__ void gemm_phase(PG8_LAS unsigned char* lds, const Gemm g, const Sched& S, const Epi& E, const int tid) {
;     ...
;         for (int t = 0; t < nt; t += 2) {
;             const bool last = (t == nt - 2);
;             const char* a1 = cA + (size_t)(t + 1) * kstep;
;             const char* a2 = last ? nA : cA + (size_t)(t + 2) * kstep; const char* b2 = last ? nB : cB + (size_t)(t + 2) * kstep;
;             const char* a3 = a2 + kstep; const char* b3 = b2 + kstep;
;             if (last && has_next) S.a_ready(nxt);
;             if constexpr (SP2) {
;             PG8_LDB(B0, 0, 0); PG8_LDB(B1, 0, 1); PG8_SCHED; PG8_LDA(At, 0, 0); PG8_STAGE(PG8_SA(1, 1), a1 + hstep, voffA);
;             PG8_WAIT_V(8); PG8_WAIT_L(0); PG8_BAR; PG8_MMA(0, 0, At, B0); PG8_MMA(0, 1, At, B1); PG8_BAR; PG8_SCHED;
;             PG8_LDA(At, 0, 1); PG8_STAGE(PG8_SB(0, 0), b2, voffB); PG8_STAGE(PG8_SB(0, 1), b2 + hstep, voffB); PG8_STAGE(PG8_SA(0, 0), a2, voffA);
.LBB0_239:
	s_add_u32 s58, s10, s44
	s_addc_u32 s59, s11, s45
	s_add_u32 s58, s58, 0x100
	s_addc_u32 s59, s59, 0
	s_add_u32 s73, s19, s44
	s_addc_u32 s74, s62, s45
	s_waitcnt lgkmcnt(0)
	s_add_i32 s75, 0, 0x10000
	s_cmpk_eq_i32 s44, 0x700
	s_cselect_b32 s79, s15, s59
	s_cselect_b32 s78, s70, s58
	s_cselect_b32 s59, s13, s74
	s_cselect_b32 s58, s71, s73
	s_add_i32 s73, 0, 0x14000
	v_add_u32_e32 v156, s75, v142
	v_add_u32_e32 v172, s73, v142
	ds_read_b128 v[144:147], v156
	ds_read_b128 v[148:151], v156 offset:1024
	ds_read_b128 v[152:155], v156 offset:2048
	ds_read_b128 v[156:159], v156 offset:3072
	ds_read_b128 v[160:163], v172
	ds_read_b128 v[164:167], v172 offset:1024
	ds_read_b128 v[168:171], v172 offset:2048
	ds_read_b128 v[172:175], v172 offset:3072
	v_lshl_add_u64 v[194:195], v[138:139], 0, s[44:45]
	s_add_i32 m0, s46, 0xc000
	ds_read_b128 v[176:179], v143
	ds_read_b128 v[180:183], v143 offset:1024
	ds_read_b128 v[184:187], v143 offset:2048
	ds_read_b128 v[188:191], v143 offset:3072
	ds_read_b128 v[212:215], v143 offset:4096
	ds_read_b128 v[216:219], v143 offset:5120
	ds_read_b128 v[234:237], v143 offset:6144
	ds_read_b128 v[238:241], v143 offset:7168
	global_load_lds_dwordx4 v[194:195], off
	v_lshl_add_u64 v[194:195], v[140:141], 0, s[44:45]
	s_add_i32 m0, s46, 0xe000
	s_nop 0
	global_load_lds_dwordx4 v[194:195], off
	s_waitcnt vmcnt(8)
	s_waitcnt lgkmcnt(0)
	s_barrier
	s_setprio 0
	s_waitcnt lgkmcnt(0)
	v_mfma_f32_16x16x32_bf16 v[76:79], v[144:147], v[176:179], v[76:79]
	v_mfma_f32_16x16x32_bf16 v[72:75], v[152:155], v[176:179], v[72:75]
	v_mfma_f32_16x16x32_bf16 v[100:103], v[144:147], v[184:187], v[100:103]
	v_mfma_f32_16x16x32_bf16 v[96:99], v[152:155], v[184:187], v[96:99]
	v_mfma_f32_16x16x32_bf16 v[124:127], v[144:147], v[212:215], v[124:127]
	v_mfma_f32_16x16x32_bf16 v[120:123], v[152:155], v[212:215], v[120:123]
	v_mfma_f32_16x16x32_bf16 v[92:95], v[144:147], v[234:237], v[92:95]
	v_mfma_f32_16x16x32_bf16 v[84:87], v[152:155], v[234:237], v[84:87]
	v_mfma_f32_16x16x32_bf16 v[76:79], v[148:151], v[180:183], v[76:79]
	v_mfma_f32_16x16x32_bf16 v[72:75], v[156:159], v[180:183], v[72:75]
	v_mfma_f32_16x16x32_bf16 v[100:103], v[148:151], v[188:191], v[100:103]
	v_mfma_f32_16x16x32_bf16 v[96:99], v[156:159], v[188:191], v[96:99]
	v_mfma_f32_16x16x32_bf16 v[124:127], v[148:151], v[216:219], v[124:127]
	v_mfma_f32_16x16x32_bf16 v[120:123], v[156:159], v[216:219], v[120:123]
	v_mfma_f32_16x16x32_bf16 v[92:95], v[148:151], v[238:241], v[92:95]
	v_mfma_f32_16x16x32_bf16 v[84:87], v[156:159], v[238:241], v[84:87]
	v_mfma_f32_16x16x32_bf16 v[80:83], v[160:163], v[176:179], v[80:83]
	v_mfma_f32_16x16x32_bf16 v[88:91], v[168:171], v[176:179], v[88:91]
	v_mfma_f32_16x16x32_bf16 v[108:111], v[160:163], v[184:187], v[108:111]
	v_mfma_f32_16x16x32_bf16 v[116:119], v[168:171], v[184:187], v[116:119]
	v_mfma_f32_16x16x32_bf16 v[112:115], v[160:163], v[212:215], v[112:115]
	v_mfma_f32_16x16x32_bf16 v[104:107], v[168:171], v[212:215], v[104:107]
	v_mfma_f32_16x16x32_bf16 v[68:71], v[160:163], v[234:237], v[68:71]
	v_mfma_f32_16x16x32_bf16 v[64:67], v[168:171], v[234:237], v[64:67]
	v_mfma_f32_16x16x32_bf16 v[80:83], v[164:167], v[180:183], v[80:83]
	v_mfma_f32_16x16x32_bf16 v[88:91], v[172:175], v[180:183], v[88:91]
	v_mfma_f32_16x16x32_bf16 v[108:111], v[164:167], v[188:191], v[108:111]
	v_mfma_f32_16x16x32_bf16 v[116:119], v[172:175], v[188:191], v[116:119]
	v_mfma_f32_16x16x32_bf16 v[112:115], v[164:167], v[216:219], v[112:115]
	v_mfma_f32_16x16x32_bf16 v[104:107], v[172:175], v[216:219], v[104:107]
	v_mfma_f32_16x16x32_bf16 v[68:71], v[164:167], v[238:241], v[68:71]
	v_mfma_f32_16x16x32_bf16 v[64:67], v[172:175], v[238:241], v[64:67]
	s_setprio 1
	s_barrier
	s_add_i32 s74, s75, s41
	v_lshl_add_u64 v[194:195], s[58:59], 0, v[192:193]
	s_mov_b32 m0, s74
	ds_read_b128 v[176:179], v143 offset:16384
	ds_read_b128 v[180:183], v143 offset:17408
	ds_read_b128 v[184:187], v143 offset:18432
	ds_read_b128 v[188:191], v143 offset:19456
	ds_read_b128 v[212:215], v143 offset:20480
	ds_read_b128 v[216:219], v143 offset:21504
	ds_read_b128 v[234:237], v143 offset:22528
	ds_read_b128 v[238:241], v143 offset:23552
	global_load_lds_dwordx4 v[194:195], off
	s_add_i32 m0, s74, 0x2000
	s_add_u32 s74, s58, 0x40000
	v_lshl_add_u64 v[196:197], s[58:59], 0, v[132:133]
	s_addc_u32 s75, s59, 0
	s_add_i32 s73, s73, s41
	global_load_lds_dwordx4 v[196:197], off
	v_lshl_add_u64 v[202:203], s[74:75], 0, v[192:193]
	s_mov_b32 m0, s73
	v_lshl_add_u64 v[204:205], s[78:79], 0, v[130:131]
	global_load_lds_dwordx4 v[202:203], off
	v_lshl_add_u64 v[202:203], s[74:75], 0, v[132:133]
	s_add_i32 m0, s73, 0x2000
	s_nop 0
	global_load_lds_dwordx4 v[202:203], off
	v_lshl_add_u64 v[202:203], s[78:79], 0, v[128:129]
	s_mov_b32 m0, s46
	s_nop 0
	global_load_lds_dwordx4 v[202:203], off
	s_mov_b32 m0, s47
	s_nop 0
	global_load_lds_dwordx4 v[204:205], off
	s_waitcnt vmcnt(8)
	s_waitcnt lgkmcnt(0)
	s_barrier
; #define PG8_STAGE(bufoff, gbase, voff) do { _Pragma("unroll") for (int _i = 0; _i < 2; ++_i) \
;         __builtin_amdgcn_global_load_lds((const unsigned*)((const char*)(gbase) + (voff)[_i]), (PG8_LAS unsigned*)(lds + (bufoff) + ldsw + _i * 8192), 16, 0, 0); } while (0)
; #define PG8_LDA(dst, b, h) do { _Pragma("unroll") for (int m = 0; m < 4; ++m) _Pragma("unroll") for (int k = 0; k < 2; ++k) dst[m][k] = *(const PG8_LAS bf16x8*)(lds + PG8_SA(b, h) + aoff + m * 2048 + k * 1024); } while (0)
; #define PG8_LDB(dst, b, h) do { _Pragma("unroll") for (int n = 0; n < 2; ++n) _Pragma("unroll") for (int k = 0; k < 2; ++k) dst[n][k] = *(const PG8_LAS bf16x8*)(lds + PG8_SB(b, h) + boff + n * 2048 + k * 1024); } while (0)
; #define PG8_MMA(ai, bj, At, Bt) do { __builtin_amdgcn_s_setprio(1); _Pragma("unroll") for (int m = 0; m < 4; ++m) _Pragma("unroll") for (int n = 0; n < 2; ++n) _Pragma("unroll") for (int k = 0; k < 2; ++k) \
;         acc[ai][bj][m][n] = __builtin_amdgcn_mfma_f32_16x16x32_bf16(Bt[n][k], At[m][k], acc[ai][bj][m][n], 0, 0, 0); __builtin_amdgcn_s_setprio(0); } while (0)
; #define PG8_WAIT_V(n) asm volatile("s_waitcnt vmcnt(" #n ")" ::: "memory")
; #define PG8_WAIT_L(n) asm volatile("s_waitcnt lgkmcnt(" #n ")" ::: "memory")
; #define PG8_BAR __builtin_amdgcn_s_barrier()
; #define PG8_SCHED __builtin_amdgcn_sched_barrier(0)
; template <class Epi, class Sched, bool ALIGN_EPI = false, bool SP2 = false>
; __device__ __forceinline__ void gemm_phase(PG8_LAS unsigned char* lds, const Gemm g, const Sched& S, const Epi& E, const int tid) {
;     ...
;             PG8_WAIT_V(8); PG8_WAIT_L(0); PG8_BAR; PG8_MMA(1, 0, At, B0); PG8_MMA(1, 1, At, B1); PG8_BAR; PG8_SCHED;
;             PG8_LDB(B0, 1, 0); PG8_LDB(B1, 1, 1); PG8_SCHED; PG8_LDA(At, 1, 0); PG8_STAGE(PG8_SA(0, 1), a2 + hstep, voffA);
;             PG8_WAIT_V(8); PG8_WAIT_L(0); PG8_BAR; PG8_MMA(0, 0, At, B0); PG8_MMA(0, 1, At, B1); PG8_BAR; PG8_SCHED;
	s_setprio 0
	s_waitcnt lgkmcnt(0)
	v_mfma_f32_16x16x32_bf16 v[60:63], v[144:147], v[176:179], v[60:63]
	v_mfma_f32_16x16x32_bf16 v[56:59], v[152:155], v[176:179], v[56:59]
	v_mfma_f32_16x16x32_bf16 v[44:47], v[144:147], v[184:187], v[44:47]
	v_mfma_f32_16x16x32_bf16 v[40:43], v[152:155], v[184:187], v[40:43]
	v_mfma_f32_16x16x32_bf16 v[28:31], v[144:147], v[212:215], v[28:31]
	v_mfma_f32_16x16x32_bf16 v[24:27], v[152:155], v[212:215], v[24:27]
	v_mfma_f32_16x16x32_bf16 v[12:15], v[144:147], v[234:237], v[12:15]
	v_mfma_f32_16x16x32_bf16 v[8:11], v[152:155], v[234:237], v[8:11]
	v_mfma_f32_16x16x32_bf16 v[60:63], v[148:151], v[180:183], v[60:63]
	v_mfma_f32_16x16x32_bf16 v[56:59], v[156:159], v[180:183], v[56:59]
	v_mfma_f32_16x16x32_bf16 v[44:47], v[148:151], v[188:191], v[44:47]
	v_mfma_f32_16x16x32_bf16 v[40:43], v[156:159], v[188:191], v[40:43]
	v_mfma_f32_16x16x32_bf16 v[28:31], v[148:151], v[216:219], v[28:31]
	v_mfma_f32_16x16x32_bf16 v[24:27], v[156:159], v[216:219], v[24:27]
	v_mfma_f32_16x16x32_bf16 v[12:15], v[148:151], v[238:241], v[12:15]
	v_mfma_f32_16x16x32_bf16 v[8:11], v[156:159], v[238:241], v[8:11]
	v_mfma_f32_16x16x32_bf16 v[52:55], v[160:163], v[176:179], v[52:55]
	v_mfma_f32_16x16x32_bf16 v[48:51], v[168:171], v[176:179], v[48:51]
	v_mfma_f32_16x16x32_bf16 v[36:39], v[160:163], v[184:187], v[36:39]
	v_mfma_f32_16x16x32_bf16 v[32:35], v[168:171], v[184:187], v[32:35]
	v_mfma_f32_16x16x32_bf16 v[20:23], v[160:163], v[212:215], v[20:23]
	v_mfma_f32_16x16x32_bf16 v[16:19], v[168:171], v[212:215], v[16:19]
	v_mfma_f32_16x16x32_bf16 v[4:7], v[160:163], v[234:237], v[4:7]
	v_mfma_f32_16x16x32_bf16 v[0:3], v[168:171], v[234:237], v[0:3]
	v_mfma_f32_16x16x32_bf16 v[52:55], v[164:167], v[180:183], v[52:55]
	v_mfma_f32_16x16x32_bf16 v[48:51], v[172:175], v[180:183], v[48:51]
	v_mfma_f32_16x16x32_bf16 v[36:39], v[164:167], v[188:191], v[36:39]
	v_mfma_f32_16x16x32_bf16 v[32:35], v[172:175], v[188:191], v[32:35]
	v_mfma_f32_16x16x32_bf16 v[20:23], v[164:167], v[216:219], v[20:23]
	v_mfma_f32_16x16x32_bf16 v[16:19], v[172:175], v[216:219], v[16:19]
	v_mfma_f32_16x16x32_bf16 v[4:7], v[164:167], v[238:241], v[4:7]
	v_mfma_f32_16x16x32_bf16 v[0:3], v[172:175], v[238:241], v[0:3]
	s_setprio 1
	s_barrier
	s_add_i32 s73, 0, 0x18000
	s_add_i32 s76, 0, 0x1c000
	v_add_u32_e32 v156, s73, v142
	v_add_u32_e32 v172, s76, v142
	ds_read_b128 v[144:147], v156
	ds_read_b128 v[148:151], v156 offset:1024
	ds_read_b128 v[152:155], v156 offset:2048
	ds_read_b128 v[156:159], v156 offset:3072
	ds_read_b128 v[160:163], v172
	ds_read_b128 v[164:167], v172 offset:1024
	ds_read_b128 v[168:171], v172 offset:2048
	ds_read_b128 v[172:175], v172 offset:3072
	s_add_u32 s74, s78, 0x40000
	s_addc_u32 s75, s79, 0
	s_mov_b32 m0, s52
	v_lshl_add_u64 v[206:207], s[74:75], 0, v[128:129]
	ds_read_b128 v[176:179], v143 offset:32768
	ds_read_b128 v[180:183], v143 offset:33792
	ds_read_b128 v[184:187], v143 offset:34816
	ds_read_b128 v[188:191], v143 offset:35840
	ds_read_b128 v[212:215], v143 offset:36864
	ds_read_b128 v[216:219], v143 offset:37888
	ds_read_b128 v[234:237], v143 offset:38912
	ds_read_b128 v[238:241], v143 offset:39936
	global_load_lds_dwordx4 v[206:207], off
	v_lshl_add_u64 v[206:207], s[74:75], 0, v[130:131]
	s_mov_b32 m0, s53
	s_nop 0
	global_load_lds_dwordx4 v[206:207], off
	s_waitcnt vmcnt(8)
	s_waitcnt lgkmcnt(0)
	s_barrier
	s_setprio 0
	s_waitcnt lgkmcnt(0)
	v_mfma_f32_16x16x32_bf16 v[76:79], v[144:147], v[176:179], v[76:79]
	v_mfma_f32_16x16x32_bf16 v[72:75], v[152:155], v[176:179], v[72:75]
	v_mfma_f32_16x16x32_bf16 v[100:103], v[144:147], v[184:187], v[100:103]
	v_mfma_f32_16x16x32_bf16 v[96:99], v[152:155], v[184:187], v[96:99]
	v_mfma_f32_16x16x32_bf16 v[124:127], v[144:147], v[212:215], v[124:127]
	v_mfma_f32_16x16x32_bf16 v[120:123], v[152:155], v[212:215], v[120:123]
	v_mfma_f32_16x16x32_bf16 v[92:95], v[144:147], v[234:237], v[92:95]
	v_mfma_f32_16x16x32_bf16 v[84:87], v[152:155], v[234:237], v[84:87]
	v_mfma_f32_16x16x32_bf16 v[76:79], v[148:151], v[180:183], v[76:79]
	v_mfma_f32_16x16x32_bf16 v[72:75], v[156:159], v[180:183], v[72:75]
	v_mfma_f32_16x16x32_bf16 v[100:103], v[148:151], v[188:191], v[100:103]
	v_mfma_f32_16x16x32_bf16 v[96:99], v[156:159], v[188:191], v[96:99]
	v_mfma_f32_16x16x32_bf16 v[124:127], v[148:151], v[216:219], v[124:127]
	v_mfma_f32_16x16x32_bf16 v[120:123], v[156:159], v[216:219], v[120:123]
	v_mfma_f32_16x16x32_bf16 v[92:95], v[148:151], v[238:241], v[92:95]
	v_mfma_f32_16x16x32_bf16 v[84:87], v[156:159], v[238:241], v[84:87]
	v_mfma_f32_16x16x32_bf16 v[80:83], v[160:163], v[176:179], v[80:83]
	v_mfma_f32_16x16x32_bf16 v[88:91], v[168:171], v[176:179], v[88:91]
	v_mfma_f32_16x16x32_bf16 v[108:111], v[160:163], v[184:187], v[108:111]
	v_mfma_f32_16x16x32_bf16 v[116:119], v[168:171], v[184:187], v[116:119]
	v_mfma_f32_16x16x32_bf16 v[112:115], v[160:163], v[212:215], v[112:115]
	v_mfma_f32_16x16x32_bf16 v[104:107], v[168:171], v[212:215], v[104:107]
	v_mfma_f32_16x16x32_bf16 v[68:71], v[160:163], v[234:237], v[68:71]
	v_mfma_f32_16x16x32_bf16 v[64:67], v[168:171], v[234:237], v[64:67]
	v_mfma_f32_16x16x32_bf16 v[80:83], v[164:167], v[180:183], v[80:83]
	v_mfma_f32_16x16x32_bf16 v[88:91], v[172:175], v[180:183], v[88:91]
	v_mfma_f32_16x16x32_bf16 v[108:111], v[164:167], v[188:191], v[108:111]
	v_mfma_f32_16x16x32_bf16 v[116:119], v[172:175], v[188:191], v[116:119]
	v_mfma_f32_16x16x32_bf16 v[112:115], v[164:167], v[216:219], v[112:115]
	v_mfma_f32_16x16x32_bf16 v[104:107], v[172:175], v[216:219], v[104:107]
	v_mfma_f32_16x16x32_bf16 v[68:71], v[164:167], v[238:241], v[68:71]
	v_mfma_f32_16x16x32_bf16 v[64:67], v[172:175], v[238:241], v[64:67]
	s_setprio 1
	s_barrier
; #define PG8_STAGE(bufoff, gbase, voff) do { _Pragma("unroll") for (int _i = 0; _i < 2; ++_i) \
;         __builtin_amdgcn_global_load_lds((const unsigned*)((const char*)(gbase) + (voff)[_i]), (PG8_LAS unsigned*)(lds + (bufoff) + ldsw + _i * 8192), 16, 0, 0); } while (0)
; #define PG8_LDA(dst, b, h) do { _Pragma("unroll") for (int m = 0; m < 4; ++m) _Pragma("unroll") for (int k = 0; k < 2; ++k) dst[m][k] = *(const PG8_LAS bf16x8*)(lds + PG8_SA(b, h) + aoff + m * 2048 + k * 1024); } while (0)
; #define PG8_MMA(ai, bj, At, Bt) do { __builtin_amdgcn_s_setprio(1); _Pragma("unroll") for (int m = 0; m < 4; ++m) _Pragma("unroll") for (int n = 0; n < 2; ++n) _Pragma("unroll") for (int k = 0; k < 2; ++k) \
;         acc[ai][bj][m][n] = __builtin_amdgcn_mfma_f32_16x16x32_bf16(Bt[n][k], At[m][k], acc[ai][bj][m][n], 0, 0, 0); __builtin_amdgcn_s_setprio(0); } while (0)
; #define PG8_WAIT_V(n) asm volatile("s_waitcnt vmcnt(" #n ")" ::: "memory")
; #define PG8_WAIT_L(n) asm volatile("s_waitcnt lgkmcnt(" #n ")" ::: "memory")
; #define PG8_BAR __builtin_amdgcn_s_barrier()
; #define PG8_SCHED __builtin_amdgcn_sched_barrier(0)
; template <class Epi, class Sched, bool ALIGN_EPI = false, bool SP2 = false>
; __device__ __forceinline__ void gemm_phase(PG8_LAS unsigned char* lds, const Gemm g, const Sched& S, const Epi& E, const int tid) {
;     ...
;             PG8_LDA(At, 1, 1); PG8_STAGE(PG8_SB(1, 0), b3, voffB); PG8_STAGE(PG8_SB(1, 1), b3 + hstep, voffB); PG8_STAGE(PG8_SA(1, 0), a3, voffA);
;             PG8_WAIT_V(8); PG8_WAIT_L(0); PG8_BAR; PG8_MMA(1, 0, At, B0); PG8_MMA(1, 1, At, B1); PG8_BAR; PG8_SCHED;
;     ...
;         if (!has_next) break;
; #pragma unroll
;         for (int a = 0; a < 2; ++a)
; #pragma unroll
;             for (int b = 0; b < 2; ++b)
; #pragma unroll
;                 for (int m = 0; m < 4; ++m)
; #pragma unroll
;                     for (int n = 0; n < 2; ++n) acc[a][b][m][n] = (f32x4){0.f, 0.f, 0.f, 0.f};
;         cur = nxt; cA = nA; cB = nB; ++ui;
	s_add_i32 s73, s73, s41
	v_lshl_add_u64 v[194:195], v[194:195], 0, s[36:37]
	s_mov_b32 m0, s73
	ds_read_b128 v[176:179], v143 offset:49152
	ds_read_b128 v[180:183], v143 offset:50176
	ds_read_b128 v[184:187], v143 offset:51200
	ds_read_b128 v[188:191], v143 offset:52224
	ds_read_b128 v[212:215], v143 offset:53248
	ds_read_b128 v[216:219], v143 offset:54272
	ds_read_b128 v[234:237], v143 offset:55296
	ds_read_b128 v[238:241], v143 offset:56320
	global_load_lds_dwordx4 v[194:195], off
	s_add_i32 m0, s73, 0x2000
	s_add_u32 s58, s58, 0x40080
	v_lshl_add_u64 v[194:195], v[196:197], 0, s[36:37]
	s_addc_u32 s59, s59, 0
	s_add_i32 s73, s76, s41
	global_load_lds_dwordx4 v[194:195], off
	v_lshl_add_u64 v[194:195], s[58:59], 0, v[192:193]
	s_mov_b32 m0, s73
	s_nop 0
	global_load_lds_dwordx4 v[194:195], off
	v_lshl_add_u64 v[194:195], s[58:59], 0, v[132:133]
	s_add_i32 m0, s73, 0x2000
	s_nop 0
	global_load_lds_dwordx4 v[194:195], off
	v_lshl_add_u64 v[194:195], v[202:203], 0, s[36:37]
	s_mov_b32 m0, s54
	s_nop 0
	global_load_lds_dwordx4 v[194:195], off
	v_lshl_add_u64 v[194:195], v[204:205], 0, s[36:37]
	s_mov_b32 m0, s55
	s_nop 0
	global_load_lds_dwordx4 v[194:195], off
	s_waitcnt vmcnt(8)
	s_waitcnt lgkmcnt(0)
	s_barrier
	s_setprio 0
	s_waitcnt lgkmcnt(0)
	v_mfma_f32_16x16x32_bf16 v[60:63], v[144:147], v[176:179], v[60:63]
	v_mfma_f32_16x16x32_bf16 v[56:59], v[152:155], v[176:179], v[56:59]
	v_mfma_f32_16x16x32_bf16 v[44:47], v[144:147], v[184:187], v[44:47]
	v_mfma_f32_16x16x32_bf16 v[40:43], v[152:155], v[184:187], v[40:43]
	v_mfma_f32_16x16x32_bf16 v[28:31], v[144:147], v[212:215], v[28:31]
	v_mfma_f32_16x16x32_bf16 v[24:27], v[152:155], v[212:215], v[24:27]
	v_mfma_f32_16x16x32_bf16 v[12:15], v[144:147], v[234:237], v[12:15]
	v_mfma_f32_16x16x32_bf16 v[8:11], v[152:155], v[234:237], v[8:11]
	v_mfma_f32_16x16x32_bf16 v[60:63], v[148:151], v[180:183], v[60:63]
	v_mfma_f32_16x16x32_bf16 v[56:59], v[156:159], v[180:183], v[56:59]
	v_mfma_f32_16x16x32_bf16 v[44:47], v[148:151], v[188:191], v[44:47]
	v_mfma_f32_16x16x32_bf16 v[40:43], v[156:159], v[188:191], v[40:43]
	v_mfma_f32_16x16x32_bf16 v[28:31], v[148:151], v[216:219], v[28:31]
	v_mfma_f32_16x16x32_bf16 v[24:27], v[156:159], v[216:219], v[24:27]
	v_mfma_f32_16x16x32_bf16 v[12:15], v[148:151], v[238:241], v[12:15]
	v_mfma_f32_16x16x32_bf16 v[8:11], v[156:159], v[238:241], v[8:11]
	v_mfma_f32_16x16x32_bf16 v[52:55], v[160:163], v[176:179], v[52:55]
	v_mfma_f32_16x16x32_bf16 v[48:51], v[168:171], v[176:179], v[48:51]
	v_mfma_f32_16x16x32_bf16 v[36:39], v[160:163], v[184:187], v[36:39]
	v_mfma_f32_16x16x32_bf16 v[32:35], v[168:171], v[184:187], v[32:35]
	v_mfma_f32_16x16x32_bf16 v[20:23], v[160:163], v[212:215], v[20:23]
	v_mfma_f32_16x16x32_bf16 v[16:19], v[168:171], v[212:215], v[16:19]
	v_mfma_f32_16x16x32_bf16 v[4:7], v[160:163], v[234:237], v[4:7]
	v_mfma_f32_16x16x32_bf16 v[0:3], v[168:171], v[234:237], v[0:3]
	v_mfma_f32_16x16x32_bf16 v[52:55], v[164:167], v[180:183], v[52:55]
	v_mfma_f32_16x16x32_bf16 v[48:51], v[172:175], v[180:183], v[48:51]
	v_mfma_f32_16x16x32_bf16 v[36:39], v[164:167], v[188:191], v[36:39]
	v_mfma_f32_16x16x32_bf16 v[32:35], v[172:175], v[188:191], v[32:35]
	v_mfma_f32_16x16x32_bf16 v[20:23], v[164:167], v[216:219], v[20:23]
	v_mfma_f32_16x16x32_bf16 v[16:19], v[172:175], v[216:219], v[16:19]
	v_mfma_f32_16x16x32_bf16 v[4:7], v[164:167], v[238:241], v[4:7]
	v_mfma_f32_16x16x32_bf16 v[0:3], v[172:175], v[238:241], v[0:3]
	s_setprio 1
	s_barrier
	s_add_i32 s72, s72, 2
	s_add_u32 s44, s44, 0x100
	s_addc_u32 s45, s45, 0
	s_cmp_gt_u32 s72, 13
	s_cbranch_scc0 .LBB0_239
	s_add_u32 s44, s19, 0xffffff00
	s_addc_u32 s45, s62, -1
	s_andn2_b64 vcc, exec, s[8:9]
	s_cbranch_vccnz .LBB0_242
	v_mov_b32_e32 v0, 0
	s_mov_b32 s22, s12
	s_mov_b32 s20, s14
	s_mov_b64 s[10:11], s[28:29]
	s_mov_b32 s60, s18
	v_mov_b32_e32 v1, v0
	v_mov_b32_e32 v2, v0
	v_mov_b32_e32 v3, v0
	v_mov_b32_e32 v4, v0
	v_mov_b32_e32 v5, v0
	v_mov_b32_e32 v6, v0
	v_mov_b32_e32 v7, v0
	v_mov_b32_e32 v16, v0
	v_mov_b32_e32 v17, v0
	v_mov_b32_e32 v18, v0
	v_mov_b32_e32 v19, v0
	v_mov_b32_e32 v20, v0
	v_mov_b32_e32 v21, v0
	v_mov_b32_e32 v22, v0
	v_mov_b32_e32 v23, v0
	v_mov_b32_e32 v32, v0
	v_mov_b32_e32 v33, v0
	v_mov_b32_e32 v34, v0
	v_mov_b32_e32 v35, v0
	v_mov_b32_e32 v36, v0
	v_mov_b32_e32 v37, v0
	v_mov_b32_e32 v38, v0
	v_mov_b32_e32 v39, v0
	v_mov_b32_e32 v48, v0
	v_mov_b32_e32 v49, v0
	v_mov_b32_e32 v50, v0
	v_mov_b32_e32 v51, v0
	v_mov_b32_e32 v52, v0
	v_mov_b32_e32 v53, v0
	v_mov_b32_e32 v54, v0
	v_mov_b32_e32 v55, v0
	v_mov_b32_e32 v8, v0
	v_mov_b32_e32 v9, v0
	v_mov_b32_e32 v10, v0
	v_mov_b32_e32 v11, v0
	v_mov_b32_e32 v12, v0
	v_mov_b32_e32 v13, v0
	v_mov_b32_e32 v14, v0
	v_mov_b32_e32 v15, v0
	v_mov_b32_e32 v24, v0
	v_mov_b32_e32 v25, v0
	v_mov_b32_e32 v26, v0
	v_mov_b32_e32 v27, v0
	v_mov_b32_e32 v28, v0
	v_mov_b32_e32 v29, v0
	v_mov_b32_e32 v30, v0
	v_mov_b32_e32 v31, v0
	v_mov_b32_e32 v40, v0
	v_mov_b32_e32 v41, v0
	v_mov_b32_e32 v42, v0
	v_mov_b32_e32 v43, v0
	v_mov_b32_e32 v44, v0
	v_mov_b32_e32 v45, v0
	v_mov_b32_e32 v46, v0
	v_mov_b32_e32 v47, v0
	v_mov_b32_e32 v56, v0
	v_mov_b32_e32 v57, v0
	v_mov_b32_e32 v58, v0
	v_mov_b32_e32 v59, v0
	v_mov_b32_e32 v60, v0
	v_mov_b32_e32 v61, v0
	v_mov_b32_e32 v62, v0
	v_mov_b32_e32 v63, v0
	v_mov_b32_e32 v64, v0
	v_mov_b32_e32 v65, v0
	v_mov_b32_e32 v66, v0
	v_mov_b32_e32 v67, v0
	v_mov_b32_e32 v68, v0
	v_mov_b32_e32 v69, v0
	v_mov_b32_e32 v70, v0
	v_mov_b32_e32 v71, v0
	v_mov_b32_e32 v104, v0
	v_mov_b32_e32 v105, v0
	v_mov_b32_e32 v106, v0
	v_mov_b32_e32 v107, v0
	v_mov_b32_e32 v112, v0
	v_mov_b32_e32 v113, v0
	v_mov_b32_e32 v114, v0
	v_mov_b32_e32 v115, v0
	v_mov_b32_e32 v116, v0
	v_mov_b32_e32 v117, v0
	v_mov_b32_e32 v118, v0
	v_mov_b32_e32 v119, v0
	v_mov_b32_e32 v108, v0
	v_mov_b32_e32 v109, v0
	v_mov_b32_e32 v110, v0
	v_mov_b32_e32 v111, v0
	v_mov_b32_e32 v88, v0
	v_mov_b32_e32 v89, v0
	v_mov_b32_e32 v90, v0
	v_mov_b32_e32 v91, v0
	v_mov_b32_e32 v80, v0
	v_mov_b32_e32 v81, v0
	v_mov_b32_e32 v82, v0
	v_mov_b32_e32 v83, v0
	v_mov_b32_e32 v84, v0
	v_mov_b32_e32 v85, v0
	v_mov_b32_e32 v86, v0
	v_mov_b32_e32 v87, v0
	v_mov_b32_e32 v92, v0
	v_mov_b32_e32 v93, v0
	v_mov_b32_e32 v94, v0
	v_mov_b32_e32 v95, v0
	v_mov_b32_e32 v120, v0
	v_mov_b32_e32 v121, v0
	v_mov_b32_e32 v122, v0
	v_mov_b32_e32 v123, v0
	v_mov_b32_e32 v124, v0
	v_mov_b32_e32 v125, v0
	v_mov_b32_e32 v126, v0
	v_mov_b32_e32 v127, v0
	v_mov_b32_e32 v96, v0
	v_mov_b32_e32 v97, v0
	v_mov_b32_e32 v98, v0
	v_mov_b32_e32 v99, v0
	v_mov_b32_e32 v100, v0
	v_mov_b32_e32 v101, v0
	v_mov_b32_e32 v102, v0
	v_mov_b32_e32 v103, v0
	v_mov_b32_e32 v72, v0
	v_mov_b32_e32 v73, v0
	v_mov_b32_e32 v74, v0
	v_mov_b32_e32 v75, v0
	v_mov_b32_e32 v76, v0
	v_mov_b32_e32 v77, v0
	v_mov_b32_e32 v78, v0
	v_mov_b32_e32 v79, v0
	s_load_dword s75, s[96:97], 0x0
	s_mov_b64 s[72:73], 0x20000
	s_andn2_b64 vcc, exec, s[6:7]
	s_cbranch_vccnz .LBB0_243
	s_branch .LBB0_244

; #define PG8_STAGE(bufoff, gbase, voff) do { _Pragma("unroll") for (int _i = 0; _i < 2; ++_i) \
;         __builtin_amdgcn_global_load_lds((const unsigned*)((const char*)(gbase) + (voff)[_i]), (PG8_LAS unsigned*)(lds + (bufoff) + ldsw + _i * 8192), 16, 0, 0); } while (0)
; #define PG8_LDA(dst, b, h) do { _Pragma("unroll") for (int m = 0; m < 4; ++m) _Pragma("unroll") for (int k = 0; k < 2; ++k) dst[m][k] = *(const PG8_LAS bf16x8*)(lds + PG8_SA(b, h) + aoff + m * 2048 + k * 1024); } while (0)
; #define PG8_LDB(dst, b, h) do { _Pragma("unroll") for (int n = 0; n < 2; ++n) _Pragma("unroll") for (int k = 0; k < 2; ++k) dst[n][k] = *(const PG8_LAS bf16x8*)(lds + PG8_SB(b, h) + boff + n * 2048 + k * 1024); } while (0)
; #define PG8_MMA(ai, bj, At, Bt) do { __builtin_amdgcn_s_setprio(1); _Pragma("unroll") for (int m = 0; m < 4; ++m) _Pragma("unroll") for (int n = 0; n < 2; ++n) _Pragma("unroll") for (int k = 0; k < 2; ++k) \
;         acc[ai][bj][m][n] = __builtin_amdgcn_mfma_f32_16x16x32_bf16(Bt[n][k], At[m][k], acc[ai][bj][m][n], 0, 0, 0); __builtin_amdgcn_s_setprio(0); } while (0)
; #define PG8_WAIT_V(n) asm volatile("s_waitcnt vmcnt(" #n ")" ::: "memory")
; #define PG8_WAIT_L(n) asm volatile("s_waitcnt lgkmcnt(" #n ")" ::: "memory")
; #define PG8_BAR __builtin_amdgcn_s_barrier()
; #define PG8_SCHED __builtin_amdgcn_sched_barrier(0)
; template <class Epi, class Sched, bool ALIGN_EPI = false, bool SP2 = false>
; __device__ __forceinline__ void gemm_phase(PG8_LAS unsigned char* lds, const Gemm g, const Sched& S, const Epi& E, const int tid) {
;     ...
;             const bool last = (t == nt - 2);
;             const char* a1 = cA + (size_t)(t + 1) * kstep;
;             const char* a2 = last ? nA : cA + (size_t)(t + 2) * kstep; const char* b2 = last ? nB : cB + (size_t)(t + 2) * kstep;
;             const char* a3 = a2 + kstep; const char* b3 = b2 + kstep;
;             if (last && has_next) S.a_ready(nxt);
;             if constexpr (SP2) {
;             PG8_LDB(B0, 0, 0); PG8_LDB(B1, 0, 1); PG8_SCHED; PG8_LDA(At, 0, 0); PG8_STAGE(PG8_SA(1, 1), a1 + hstep, voffA);
;             PG8_WAIT_V(8); PG8_WAIT_L(0); PG8_BAR; PG8_MMA(0, 0, At, B0); PG8_MMA(0, 1, At, B1); PG8_BAR; PG8_SCHED;
;             PG8_LDA(At, 0, 1); PG8_STAGE(PG8_SB(0, 0), b2, voffB); PG8_STAGE(PG8_SB(0, 1), b2 + hstep, voffB); PG8_STAGE(PG8_SA(0, 0), a2, voffA);
.LBB0_324:
	s_add_u32 s28, s22, 0xfffc0080
	s_addc_u32 s29, s23, -1
	s_add_i32 s35, 0, 0x10000
	s_cmp_eq_u32 s34, 12
	s_cselect_b32 s45, s1, s29
	s_cselect_b32 s44, s2, s28
	s_cselect_b32 s29, s13, s26
	s_cselect_b32 s28, s15, s21
	s_add_i32 s38, 0, 0x14000
	v_add_u32_e32 v152, s35, v142
	v_add_u32_e32 v168, s38, v142
	ds_read_b128 v[138:141], v152
	ds_read_b128 v[144:147], v152 offset:1024
	ds_read_b128 v[148:151], v152 offset:2048
	ds_read_b128 v[152:155], v152 offset:3072
	ds_read_b128 v[156:159], v168
	ds_read_b128 v[160:163], v168 offset:1024
	ds_read_b128 v[164:167], v168 offset:2048
	ds_read_b128 v[168:171], v168 offset:3072
	v_lshl_add_u64 v[194:195], s[22:23], 0, v[134:135]
	s_add_i32 m0, s80, 0xc000
	ds_read_b128 v[172:175], v143
	ds_read_b128 v[176:179], v143 offset:1024
	ds_read_b128 v[180:183], v143 offset:2048
	ds_read_b128 v[184:187], v143 offset:3072
	ds_read_b128 v[188:191], v143 offset:4096
	ds_read_b128 v[212:215], v143 offset:5120
	ds_read_b128 v[216:219], v143 offset:6144
	ds_read_b128 v[232:235], v143 offset:7168
	global_load_lds_dwordx4 v[194:195], off
	v_lshl_add_u64 v[194:195], s[22:23], 0, v[136:137]
	s_add_i32 m0, s80, 0xe000
	s_nop 0
	global_load_lds_dwordx4 v[194:195], off
	s_waitcnt vmcnt(8)
	s_waitcnt lgkmcnt(0)
	s_barrier
	s_setprio 0
	s_waitcnt lgkmcnt(0)
	v_mfma_f32_16x16x32_bf16 v[124:127], v[138:141], v[172:175], v[124:127]
	v_mfma_f32_16x16x32_bf16 v[120:123], v[148:151], v[172:175], v[120:123]
	v_mfma_f32_16x16x32_bf16 v[108:111], v[138:141], v[180:183], v[108:111]
	v_mfma_f32_16x16x32_bf16 v[104:107], v[148:151], v[180:183], v[104:107]
	v_mfma_f32_16x16x32_bf16 v[92:95], v[138:141], v[188:191], v[92:95]
	v_mfma_f32_16x16x32_bf16 v[88:91], v[148:151], v[188:191], v[88:91]
	v_mfma_f32_16x16x32_bf16 v[76:79], v[138:141], v[216:219], v[76:79]
	v_mfma_f32_16x16x32_bf16 v[72:75], v[148:151], v[216:219], v[72:75]
	v_mfma_f32_16x16x32_bf16 v[124:127], v[144:147], v[176:179], v[124:127]
	v_mfma_f32_16x16x32_bf16 v[120:123], v[152:155], v[176:179], v[120:123]
	v_mfma_f32_16x16x32_bf16 v[108:111], v[144:147], v[184:187], v[108:111]
	v_mfma_f32_16x16x32_bf16 v[104:107], v[152:155], v[184:187], v[104:107]
	v_mfma_f32_16x16x32_bf16 v[92:95], v[144:147], v[212:215], v[92:95]
	v_mfma_f32_16x16x32_bf16 v[88:91], v[152:155], v[212:215], v[88:91]
	v_mfma_f32_16x16x32_bf16 v[76:79], v[144:147], v[232:235], v[76:79]
	v_mfma_f32_16x16x32_bf16 v[72:75], v[152:155], v[232:235], v[72:75]
	v_mfma_f32_16x16x32_bf16 v[116:119], v[156:159], v[172:175], v[116:119]
	v_mfma_f32_16x16x32_bf16 v[112:115], v[164:167], v[172:175], v[112:115]
	v_mfma_f32_16x16x32_bf16 v[100:103], v[156:159], v[180:183], v[100:103]
	v_mfma_f32_16x16x32_bf16 v[96:99], v[164:167], v[180:183], v[96:99]
	v_mfma_f32_16x16x32_bf16 v[84:87], v[156:159], v[188:191], v[84:87]
	v_mfma_f32_16x16x32_bf16 v[80:83], v[164:167], v[188:191], v[80:83]
	v_mfma_f32_16x16x32_bf16 v[68:71], v[156:159], v[216:219], v[68:71]
	v_mfma_f32_16x16x32_bf16 v[64:67], v[164:167], v[216:219], v[64:67]
	v_mfma_f32_16x16x32_bf16 v[116:119], v[160:163], v[176:179], v[116:119]
	v_mfma_f32_16x16x32_bf16 v[112:115], v[168:171], v[176:179], v[112:115]
	v_mfma_f32_16x16x32_bf16 v[100:103], v[160:163], v[184:187], v[100:103]
	v_mfma_f32_16x16x32_bf16 v[96:99], v[168:171], v[184:187], v[96:99]
	v_mfma_f32_16x16x32_bf16 v[84:87], v[160:163], v[212:215], v[84:87]
	v_mfma_f32_16x16x32_bf16 v[80:83], v[168:171], v[212:215], v[80:83]
	v_mfma_f32_16x16x32_bf16 v[68:71], v[160:163], v[232:235], v[68:71]
	v_mfma_f32_16x16x32_bf16 v[64:67], v[168:171], v[232:235], v[64:67]
	s_setprio 1
	s_barrier
	s_add_i32 s35, s35, s79
	v_lshl_add_u64 v[194:195], s[28:29], 0, v[192:193]
	s_mov_b32 m0, s35
	ds_read_b128 v[172:175], v143 offset:16384
	ds_read_b128 v[176:179], v143 offset:17408
	ds_read_b128 v[180:183], v143 offset:18432
	ds_read_b128 v[184:187], v143 offset:19456
	ds_read_b128 v[188:191], v143 offset:20480
	ds_read_b128 v[212:215], v143 offset:21504
	ds_read_b128 v[216:219], v143 offset:22528
	ds_read_b128 v[232:235], v143 offset:23552
	global_load_lds_dwordx4 v[194:195], off
	s_add_i32 m0, s35, 0x2000
	s_add_u32 s40, s28, 0x40000
	v_lshl_add_u64 v[196:197], s[28:29], 0, v[132:133]
	s_addc_u32 s41, s29, 0
	s_add_i32 s35, s38, s79
	global_load_lds_dwordx4 v[196:197], off
	v_lshl_add_u64 v[202:203], s[40:41], 0, v[192:193]
	s_mov_b32 m0, s35
	v_lshl_add_u64 v[204:205], s[44:45], 0, v[130:131]
	global_load_lds_dwordx4 v[202:203], off
	v_lshl_add_u64 v[202:203], s[40:41], 0, v[132:133]
	s_add_i32 m0, s35, 0x2000
	s_nop 0
	global_load_lds_dwordx4 v[202:203], off
	v_lshl_add_u64 v[202:203], s[44:45], 0, v[128:129]
	s_mov_b32 m0, s80
	s_nop 0
	global_load_lds_dwordx4 v[202:203], off
	s_mov_b32 m0, s81
	s_nop 0
	global_load_lds_dwordx4 v[204:205], off
	s_waitcnt vmcnt(8)
	s_waitcnt lgkmcnt(0)
	s_barrier
; #define PG8_STAGE(bufoff, gbase, voff) do { _Pragma("unroll") for (int _i = 0; _i < 2; ++_i) \
;         __builtin_amdgcn_global_load_lds((const unsigned*)((const char*)(gbase) + (voff)[_i]), (PG8_LAS unsigned*)(lds + (bufoff) + ldsw + _i * 8192), 16, 0, 0); } while (0)
; #define PG8_LDA(dst, b, h) do { _Pragma("unroll") for (int m = 0; m < 4; ++m) _Pragma("unroll") for (int k = 0; k < 2; ++k) dst[m][k] = *(const PG8_LAS bf16x8*)(lds + PG8_SA(b, h) + aoff + m * 2048 + k * 1024); } while (0)
; #define PG8_LDB(dst, b, h) do { _Pragma("unroll") for (int n = 0; n < 2; ++n) _Pragma("unroll") for (int k = 0; k < 2; ++k) dst[n][k] = *(const PG8_LAS bf16x8*)(lds + PG8_SB(b, h) + boff + n * 2048 + k * 1024); } while (0)
; #define PG8_MMA(ai, bj, At, Bt) do { __builtin_amdgcn_s_setprio(1); _Pragma("unroll") for (int m = 0; m < 4; ++m) _Pragma("unroll") for (int n = 0; n < 2; ++n) _Pragma("unroll") for (int k = 0; k < 2; ++k) \
;         acc[ai][bj][m][n] = __builtin_amdgcn_mfma_f32_16x16x32_bf16(Bt[n][k], At[m][k], acc[ai][bj][m][n], 0, 0, 0); __builtin_amdgcn_s_setprio(0); } while (0)
; #define PG8_WAIT_V(n) asm volatile("s_waitcnt vmcnt(" #n ")" ::: "memory")
; #define PG8_WAIT_L(n) asm volatile("s_waitcnt lgkmcnt(" #n ")" ::: "memory")
; #define PG8_BAR __builtin_amdgcn_s_barrier()
; #define PG8_SCHED __builtin_amdgcn_sched_barrier(0)
; template <class Epi, class Sched, bool ALIGN_EPI = false, bool SP2 = false>
; __device__ __forceinline__ void gemm_phase(PG8_LAS unsigned char* lds, const Gemm g, const Sched& S, const Epi& E, const int tid) {
;     ...
;             PG8_WAIT_V(8); PG8_WAIT_L(0); PG8_BAR; PG8_MMA(1, 0, At, B0); PG8_MMA(1, 1, At, B1); PG8_BAR; PG8_SCHED;
;             PG8_LDB(B0, 1, 0); PG8_LDB(B1, 1, 1); PG8_SCHED; PG8_LDA(At, 1, 0); PG8_STAGE(PG8_SA(0, 1), a2 + hstep, voffA);
;             PG8_WAIT_V(8); PG8_WAIT_L(0); PG8_BAR; PG8_MMA(0, 0, At, B0); PG8_MMA(0, 1, At, B1); PG8_BAR; PG8_SCHED;
	s_setprio 0
	s_waitcnt lgkmcnt(0)
	v_mfma_f32_16x16x32_bf16 v[60:63], v[138:141], v[172:175], v[60:63]
	v_mfma_f32_16x16x32_bf16 v[56:59], v[148:151], v[172:175], v[56:59]
	v_mfma_f32_16x16x32_bf16 v[44:47], v[138:141], v[180:183], v[44:47]
	v_mfma_f32_16x16x32_bf16 v[40:43], v[148:151], v[180:183], v[40:43]
	v_mfma_f32_16x16x32_bf16 v[28:31], v[138:141], v[188:191], v[28:31]
	v_mfma_f32_16x16x32_bf16 v[24:27], v[148:151], v[188:191], v[24:27]
	v_mfma_f32_16x16x32_bf16 v[12:15], v[138:141], v[216:219], v[12:15]
	v_mfma_f32_16x16x32_bf16 v[8:11], v[148:151], v[216:219], v[8:11]
	v_mfma_f32_16x16x32_bf16 v[60:63], v[144:147], v[176:179], v[60:63]
	v_mfma_f32_16x16x32_bf16 v[56:59], v[152:155], v[176:179], v[56:59]
	v_mfma_f32_16x16x32_bf16 v[44:47], v[144:147], v[184:187], v[44:47]
	v_mfma_f32_16x16x32_bf16 v[40:43], v[152:155], v[184:187], v[40:43]
	v_mfma_f32_16x16x32_bf16 v[28:31], v[144:147], v[212:215], v[28:31]
	v_mfma_f32_16x16x32_bf16 v[24:27], v[152:155], v[212:215], v[24:27]
	v_mfma_f32_16x16x32_bf16 v[12:15], v[144:147], v[232:235], v[12:15]
	v_mfma_f32_16x16x32_bf16 v[8:11], v[152:155], v[232:235], v[8:11]
	v_mfma_f32_16x16x32_bf16 v[52:55], v[156:159], v[172:175], v[52:55]
	v_mfma_f32_16x16x32_bf16 v[48:51], v[164:167], v[172:175], v[48:51]
	v_mfma_f32_16x16x32_bf16 v[36:39], v[156:159], v[180:183], v[36:39]
	v_mfma_f32_16x16x32_bf16 v[32:35], v[164:167], v[180:183], v[32:35]
	v_mfma_f32_16x16x32_bf16 v[20:23], v[156:159], v[188:191], v[20:23]
	v_mfma_f32_16x16x32_bf16 v[16:19], v[164:167], v[188:191], v[16:19]
	v_mfma_f32_16x16x32_bf16 v[4:7], v[156:159], v[216:219], v[4:7]
	v_mfma_f32_16x16x32_bf16 v[0:3], v[164:167], v[216:219], v[0:3]
	v_mfma_f32_16x16x32_bf16 v[52:55], v[160:163], v[176:179], v[52:55]
	v_mfma_f32_16x16x32_bf16 v[48:51], v[168:171], v[176:179], v[48:51]
	v_mfma_f32_16x16x32_bf16 v[36:39], v[160:163], v[184:187], v[36:39]
	v_mfma_f32_16x16x32_bf16 v[32:35], v[168:171], v[184:187], v[32:35]
	v_mfma_f32_16x16x32_bf16 v[20:23], v[160:163], v[212:215], v[20:23]
	v_mfma_f32_16x16x32_bf16 v[16:19], v[168:171], v[212:215], v[16:19]
	v_mfma_f32_16x16x32_bf16 v[4:7], v[160:163], v[232:235], v[4:7]
	v_mfma_f32_16x16x32_bf16 v[0:3], v[168:171], v[232:235], v[0:3]
	s_setprio 1
	s_barrier
	s_add_i32 s35, 0, 0x18000
	s_add_i32 s38, 0, 0x1c000
	v_add_u32_e32 v152, s35, v142
	v_add_u32_e32 v168, s38, v142
	ds_read_b128 v[138:141], v152
	ds_read_b128 v[144:147], v152 offset:1024
	ds_read_b128 v[148:151], v152 offset:2048
	ds_read_b128 v[152:155], v152 offset:3072
	ds_read_b128 v[156:159], v168
	ds_read_b128 v[160:163], v168 offset:1024
	ds_read_b128 v[164:167], v168 offset:2048
	ds_read_b128 v[168:171], v168 offset:3072
	s_add_u32 s40, s44, 0x40000
	s_addc_u32 s41, s45, 0
	s_mov_b32 m0, s82
	v_lshl_add_u64 v[206:207], s[40:41], 0, v[128:129]
	ds_read_b128 v[172:175], v143 offset:32768
	ds_read_b128 v[176:179], v143 offset:33792
	ds_read_b128 v[180:183], v143 offset:34816
	ds_read_b128 v[184:187], v143 offset:35840
	ds_read_b128 v[188:191], v143 offset:36864
	ds_read_b128 v[212:215], v143 offset:37888
	ds_read_b128 v[216:219], v143 offset:38912
	ds_read_b128 v[232:235], v143 offset:39936
	global_load_lds_dwordx4 v[206:207], off
	v_lshl_add_u64 v[206:207], s[40:41], 0, v[130:131]
	s_mov_b32 m0, s83
	s_nop 0
	global_load_lds_dwordx4 v[206:207], off
	s_waitcnt vmcnt(8)
	s_waitcnt lgkmcnt(0)
	s_barrier
	s_setprio 0
	s_waitcnt lgkmcnt(0)
	v_mfma_f32_16x16x32_bf16 v[124:127], v[138:141], v[172:175], v[124:127]
	v_mfma_f32_16x16x32_bf16 v[120:123], v[148:151], v[172:175], v[120:123]
	v_mfma_f32_16x16x32_bf16 v[108:111], v[138:141], v[180:183], v[108:111]
	v_mfma_f32_16x16x32_bf16 v[104:107], v[148:151], v[180:183], v[104:107]
	v_mfma_f32_16x16x32_bf16 v[92:95], v[138:141], v[188:191], v[92:95]
	v_mfma_f32_16x16x32_bf16 v[88:91], v[148:151], v[188:191], v[88:91]
	v_mfma_f32_16x16x32_bf16 v[76:79], v[138:141], v[216:219], v[76:79]
	v_mfma_f32_16x16x32_bf16 v[72:75], v[148:151], v[216:219], v[72:75]
	v_mfma_f32_16x16x32_bf16 v[124:127], v[144:147], v[176:179], v[124:127]
	v_mfma_f32_16x16x32_bf16 v[120:123], v[152:155], v[176:179], v[120:123]
	v_mfma_f32_16x16x32_bf16 v[108:111], v[144:147], v[184:187], v[108:111]
	v_mfma_f32_16x16x32_bf16 v[104:107], v[152:155], v[184:187], v[104:107]
	v_mfma_f32_16x16x32_bf16 v[92:95], v[144:147], v[212:215], v[92:95]
	v_mfma_f32_16x16x32_bf16 v[88:91], v[152:155], v[212:215], v[88:91]
	v_mfma_f32_16x16x32_bf16 v[76:79], v[144:147], v[232:235], v[76:79]
	v_mfma_f32_16x16x32_bf16 v[72:75], v[152:155], v[232:235], v[72:75]
	v_mfma_f32_16x16x32_bf16 v[116:119], v[156:159], v[172:175], v[116:119]
	v_mfma_f32_16x16x32_bf16 v[112:115], v[164:167], v[172:175], v[112:115]
	v_mfma_f32_16x16x32_bf16 v[100:103], v[156:159], v[180:183], v[100:103]
	v_mfma_f32_16x16x32_bf16 v[96:99], v[164:167], v[180:183], v[96:99]
	v_mfma_f32_16x16x32_bf16 v[84:87], v[156:159], v[188:191], v[84:87]
	v_mfma_f32_16x16x32_bf16 v[80:83], v[164:167], v[188:191], v[80:83]
	v_mfma_f32_16x16x32_bf16 v[68:71], v[156:159], v[216:219], v[68:71]
	v_mfma_f32_16x16x32_bf16 v[64:67], v[164:167], v[216:219], v[64:67]
	v_mfma_f32_16x16x32_bf16 v[116:119], v[160:163], v[176:179], v[116:119]
	v_mfma_f32_16x16x32_bf16 v[112:115], v[168:171], v[176:179], v[112:115]
	v_mfma_f32_16x16x32_bf16 v[100:103], v[160:163], v[184:187], v[100:103]
	v_mfma_f32_16x16x32_bf16 v[96:99], v[168:171], v[184:187], v[96:99]
	v_mfma_f32_16x16x32_bf16 v[84:87], v[160:163], v[212:215], v[84:87]
	v_mfma_f32_16x16x32_bf16 v[80:83], v[168:171], v[212:215], v[80:83]
	v_mfma_f32_16x16x32_bf16 v[68:71], v[160:163], v[232:235], v[68:71]
	v_mfma_f32_16x16x32_bf16 v[64:67], v[168:171], v[232:235], v[64:67]
	s_setprio 1
	s_barrier
; #define PG8_STAGE(bufoff, gbase, voff) do { _Pragma("unroll") for (int _i = 0; _i < 2; ++_i) \
;         __builtin_amdgcn_global_load_lds((const unsigned*)((const char*)(gbase) + (voff)[_i]), (PG8_LAS unsigned*)(lds + (bufoff) + ldsw + _i * 8192), 16, 0, 0); } while (0)
; #define PG8_LDA(dst, b, h) do { _Pragma("unroll") for (int m = 0; m < 4; ++m) _Pragma("unroll") for (int k = 0; k < 2; ++k) dst[m][k] = *(const PG8_LAS bf16x8*)(lds + PG8_SA(b, h) + aoff + m * 2048 + k * 1024); } while (0)
; #define PG8_MMA(ai, bj, At, Bt) do { __builtin_amdgcn_s_setprio(1); _Pragma("unroll") for (int m = 0; m < 4; ++m) _Pragma("unroll") for (int n = 0; n < 2; ++n) _Pragma("unroll") for (int k = 0; k < 2; ++k) \
;         acc[ai][bj][m][n] = __builtin_amdgcn_mfma_f32_16x16x32_bf16(Bt[n][k], At[m][k], acc[ai][bj][m][n], 0, 0, 0); __builtin_amdgcn_s_setprio(0); } while (0)
; #define PG8_WAIT_V(n) asm volatile("s_waitcnt vmcnt(" #n ")" ::: "memory")
; #define PG8_WAIT_L(n) asm volatile("s_waitcnt lgkmcnt(" #n ")" ::: "memory")
; #define PG8_BAR __builtin_amdgcn_s_barrier()
; #define PG8_SCHED __builtin_amdgcn_sched_barrier(0)
; template <class Epi, class Sched, bool ALIGN_EPI = false, bool SP2 = false>
; __device__ __forceinline__ void gemm_phase(PG8_LAS unsigned char* lds, const Gemm g, const Sched& S, const Epi& E, const int tid) {
;     ...
;         for (int t = 0; t < nt; t += 2) {
;     ...
;             PG8_LDA(At, 1, 1); PG8_STAGE(PG8_SB(1, 0), b3, voffB); PG8_STAGE(PG8_SB(1, 1), b3 + hstep, voffB); PG8_STAGE(PG8_SA(1, 0), a3, voffA);
;             PG8_WAIT_V(8); PG8_WAIT_L(0); PG8_BAR; PG8_MMA(1, 0, At, B0); PG8_MMA(1, 1, At, B1); PG8_BAR; PG8_SCHED;
;     ...
;         if constexpr (ALIGN_EPI) { if (wr == 0) PG8_BAR; }
	s_add_i32 s35, s35, s79
	v_lshl_add_u64 v[194:195], v[194:195], 0, s[36:37]
	s_mov_b32 m0, s35
	ds_read_b128 v[172:175], v143 offset:49152
	ds_read_b128 v[176:179], v143 offset:50176
	ds_read_b128 v[180:183], v143 offset:51200
	ds_read_b128 v[184:187], v143 offset:52224
	ds_read_b128 v[188:191], v143 offset:53248
	ds_read_b128 v[212:215], v143 offset:54272
	ds_read_b128 v[216:219], v143 offset:55296
	ds_read_b128 v[232:235], v143 offset:56320
	global_load_lds_dwordx4 v[194:195], off
	s_add_i32 m0, s35, 0x2000
	s_add_u32 s28, s28, 0x40080
	v_lshl_add_u64 v[194:195], v[196:197], 0, s[36:37]
	s_addc_u32 s29, s29, 0
	s_add_i32 s35, s38, s79
	global_load_lds_dwordx4 v[194:195], off
	v_lshl_add_u64 v[194:195], s[28:29], 0, v[192:193]
	s_mov_b32 m0, s35
	s_nop 0
	global_load_lds_dwordx4 v[194:195], off
	v_lshl_add_u64 v[194:195], s[28:29], 0, v[132:133]
	s_add_i32 m0, s35, 0x2000
	s_nop 0
	global_load_lds_dwordx4 v[194:195], off
	v_lshl_add_u64 v[194:195], v[202:203], 0, s[36:37]
	s_mov_b32 m0, s84
	s_nop 0
	global_load_lds_dwordx4 v[194:195], off
	v_lshl_add_u64 v[194:195], v[204:205], 0, s[36:37]
	s_mov_b32 m0, s85
	s_nop 0
	global_load_lds_dwordx4 v[194:195], off
	s_waitcnt vmcnt(8)
	s_waitcnt lgkmcnt(0)
	s_barrier
	s_setprio 0
	s_waitcnt lgkmcnt(0)
	v_mfma_f32_16x16x32_bf16 v[60:63], v[138:141], v[172:175], v[60:63]
	v_mfma_f32_16x16x32_bf16 v[56:59], v[148:151], v[172:175], v[56:59]
	v_mfma_f32_16x16x32_bf16 v[44:47], v[138:141], v[180:183], v[44:47]
	v_mfma_f32_16x16x32_bf16 v[40:43], v[148:151], v[180:183], v[40:43]
	v_mfma_f32_16x16x32_bf16 v[28:31], v[138:141], v[188:191], v[28:31]
	v_mfma_f32_16x16x32_bf16 v[24:27], v[148:151], v[188:191], v[24:27]
	v_mfma_f32_16x16x32_bf16 v[12:15], v[138:141], v[216:219], v[12:15]
	v_mfma_f32_16x16x32_bf16 v[8:11], v[148:151], v[216:219], v[8:11]
	v_mfma_f32_16x16x32_bf16 v[60:63], v[144:147], v[176:179], v[60:63]
	v_mfma_f32_16x16x32_bf16 v[56:59], v[152:155], v[176:179], v[56:59]
	v_mfma_f32_16x16x32_bf16 v[44:47], v[144:147], v[184:187], v[44:47]
	v_mfma_f32_16x16x32_bf16 v[40:43], v[152:155], v[184:187], v[40:43]
	v_mfma_f32_16x16x32_bf16 v[28:31], v[144:147], v[212:215], v[28:31]
	v_mfma_f32_16x16x32_bf16 v[24:27], v[152:155], v[212:215], v[24:27]
	v_mfma_f32_16x16x32_bf16 v[12:15], v[144:147], v[232:235], v[12:15]
	v_mfma_f32_16x16x32_bf16 v[8:11], v[152:155], v[232:235], v[8:11]
	v_mfma_f32_16x16x32_bf16 v[52:55], v[156:159], v[172:175], v[52:55]
	v_mfma_f32_16x16x32_bf16 v[48:51], v[164:167], v[172:175], v[48:51]
	v_mfma_f32_16x16x32_bf16 v[36:39], v[156:159], v[180:183], v[36:39]
	v_mfma_f32_16x16x32_bf16 v[32:35], v[164:167], v[180:183], v[32:35]
	v_mfma_f32_16x16x32_bf16 v[20:23], v[156:159], v[188:191], v[20:23]
	v_mfma_f32_16x16x32_bf16 v[16:19], v[164:167], v[188:191], v[16:19]
	v_mfma_f32_16x16x32_bf16 v[4:7], v[156:159], v[216:219], v[4:7]
	v_mfma_f32_16x16x32_bf16 v[0:3], v[164:167], v[216:219], v[0:3]
	v_mfma_f32_16x16x32_bf16 v[52:55], v[160:163], v[176:179], v[52:55]
	v_mfma_f32_16x16x32_bf16 v[48:51], v[168:171], v[176:179], v[48:51]
	v_mfma_f32_16x16x32_bf16 v[36:39], v[160:163], v[184:187], v[36:39]
	v_mfma_f32_16x16x32_bf16 v[32:35], v[168:171], v[184:187], v[32:35]
	v_mfma_f32_16x16x32_bf16 v[20:23], v[160:163], v[212:215], v[20:23]
	v_mfma_f32_16x16x32_bf16 v[16:19], v[168:171], v[212:215], v[16:19]
	v_mfma_f32_16x16x32_bf16 v[4:7], v[160:163], v[232:235], v[4:7]
	v_mfma_f32_16x16x32_bf16 v[0:3], v[168:171], v[232:235], v[0:3]
	s_setprio 1
	s_barrier
	s_add_i32 s34, s34, 2
	s_add_u32 s22, s22, 0x100
	s_addc_u32 s23, s23, 0
	s_add_u32 s21, s21, 0x100
	s_addc_u32 s26, s26, 0
	s_cmp_gt_u32 s34, 13
	s_cbranch_scc0 .LBB0_324
	s_and_b64 vcc, exec, s[10:11]
	s_cbranch_vccz .LBB0_327
	s_barrier

; #define PG8_STAGE(bufoff, gbase, voff) do { _Pragma("unroll") for (int _i = 0; _i < 2; ++_i) \
;         __builtin_amdgcn_global_load_lds((const unsigned*)((const char*)(gbase) + (voff)[_i]), (PG8_LAS unsigned*)(lds + (bufoff) + ldsw + _i * 8192), 16, 0, 0); } while (0)
; #define PG8_LDA(dst, b, h) do { _Pragma("unroll") for (int m = 0; m < 4; ++m) _Pragma("unroll") for (int k = 0; k < 2; ++k) dst[m][k] = *(const PG8_LAS bf16x8*)(lds + PG8_SA(b, h) + aoff + m * 2048 + k * 1024); } while (0)
; #define PG8_LDB(dst, b, h) do { _Pragma("unroll") for (int n = 0; n < 2; ++n) _Pragma("unroll") for (int k = 0; k < 2; ++k) dst[n][k] = *(const PG8_LAS bf16x8*)(lds + PG8_SB(b, h) + boff + n * 2048 + k * 1024); } while (0)
; #define PG8_MMA(ai, bj, At, Bt) do { __builtin_amdgcn_s_setprio(1); _Pragma("unroll") for (int m = 0; m < 4; ++m) _Pragma("unroll") for (int n = 0; n < 2; ++n) _Pragma("unroll") for (int k = 0; k < 2; ++k) \
;         acc[ai][bj][m][n] = __builtin_amdgcn_mfma_f32_16x16x32_bf16(Bt[n][k], At[m][k], acc[ai][bj][m][n], 0, 0, 0); __builtin_amdgcn_s_setprio(0); } while (0)
; #define PG8_WAIT_V(n) asm volatile("s_waitcnt vmcnt(" #n ")" ::: "memory")
; #define PG8_WAIT_L(n) asm volatile("s_waitcnt lgkmcnt(" #n ")" ::: "memory")
; #define PG8_BAR __builtin_amdgcn_s_barrier()
; #define PG8_SCHED __builtin_amdgcn_sched_barrier(0)
; template <class Epi, class Sched, bool ALIGN_EPI = false, bool SP2 = false>
; __device__ __forceinline__ void gemm_phase(PG8_LAS unsigned char* lds, const Gemm g, const Sched& S, const Epi& E, const int tid) {
;     ...
;             const bool last = (t == nt - 2);
;             const char* a1 = cA + (size_t)(t + 1) * kstep;
;             const char* a2 = last ? nA : cA + (size_t)(t + 2) * kstep; const char* b2 = last ? nB : cB + (size_t)(t + 2) * kstep;
;             const char* a3 = a2 + kstep; const char* b3 = b2 + kstep;
;             if (last && has_next) S.a_ready(nxt);
;             if constexpr (SP2) {
;             PG8_LDB(B0, 0, 0); PG8_LDB(B1, 0, 1); PG8_SCHED; PG8_LDA(At, 0, 0); PG8_STAGE(PG8_SA(1, 1), a1 + hstep, voffA);
;             PG8_WAIT_V(8); PG8_WAIT_L(0); PG8_BAR; PG8_MMA(0, 0, At, B0); PG8_MMA(0, 1, At, B1); PG8_BAR; PG8_SCHED;
;             PG8_LDA(At, 0, 1); PG8_STAGE(PG8_SB(0, 0), b2, voffB); PG8_STAGE(PG8_SB(0, 1), b2 + hstep, voffB); PG8_STAGE(PG8_SA(0, 0), a2, voffA);
.LBB0_348:
	s_add_u32 s35, s28, 0xfffe0080
	s_addc_u32 s38, s29, -1
	s_add_i32 s40, 0, 0x10000
	s_cmp_eq_u32 s34, 4
	s_cselect_b32 s59, s1, s38
	s_cselect_b32 s58, s2, s35
	s_cselect_b32 s45, s15, s26
	s_cselect_b32 s44, s17, s23
	s_add_i32 s35, 0, 0x14000
	v_add_u32_e32 v152, s40, v142
	v_add_u32_e32 v168, s35, v142
	ds_read_b128 v[138:141], v152
	ds_read_b128 v[144:147], v152 offset:1024
	ds_read_b128 v[148:151], v152 offset:2048
	ds_read_b128 v[152:155], v152 offset:3072
	ds_read_b128 v[156:159], v168
	ds_read_b128 v[160:163], v168 offset:1024
	ds_read_b128 v[164:167], v168 offset:2048
	ds_read_b128 v[168:171], v168 offset:3072
	v_lshl_add_u64 v[194:195], s[28:29], 0, v[134:135]
	s_add_i32 m0, s83, 0xc000
	ds_read_b128 v[172:175], v143
	ds_read_b128 v[176:179], v143 offset:1024
	ds_read_b128 v[180:183], v143 offset:2048
	ds_read_b128 v[184:187], v143 offset:3072
	ds_read_b128 v[188:191], v143 offset:4096
	ds_read_b128 v[212:215], v143 offset:5120
	ds_read_b128 v[216:219], v143 offset:6144
	ds_read_b128 v[232:235], v143 offset:7168
	global_load_lds_dwordx4 v[194:195], off
	v_lshl_add_u64 v[194:195], s[28:29], 0, v[136:137]
	s_add_i32 m0, s83, 0xe000
	s_nop 0
	global_load_lds_dwordx4 v[194:195], off
	s_waitcnt vmcnt(8)
	s_waitcnt lgkmcnt(0)
	s_barrier
	s_setprio 0
	s_waitcnt lgkmcnt(0)
	v_mfma_f32_16x16x32_bf16 v[124:127], v[138:141], v[172:175], v[124:127]
	v_mfma_f32_16x16x32_bf16 v[120:123], v[148:151], v[172:175], v[120:123]
	v_mfma_f32_16x16x32_bf16 v[108:111], v[138:141], v[180:183], v[108:111]
	v_mfma_f32_16x16x32_bf16 v[104:107], v[148:151], v[180:183], v[104:107]
	v_mfma_f32_16x16x32_bf16 v[92:95], v[138:141], v[188:191], v[92:95]
	v_mfma_f32_16x16x32_bf16 v[88:91], v[148:151], v[188:191], v[88:91]
	v_mfma_f32_16x16x32_bf16 v[76:79], v[138:141], v[216:219], v[76:79]
	v_mfma_f32_16x16x32_bf16 v[72:75], v[148:151], v[216:219], v[72:75]
	v_mfma_f32_16x16x32_bf16 v[124:127], v[144:147], v[176:179], v[124:127]
	v_mfma_f32_16x16x32_bf16 v[120:123], v[152:155], v[176:179], v[120:123]
	v_mfma_f32_16x16x32_bf16 v[108:111], v[144:147], v[184:187], v[108:111]
	v_mfma_f32_16x16x32_bf16 v[104:107], v[152:155], v[184:187], v[104:107]
	v_mfma_f32_16x16x32_bf16 v[92:95], v[144:147], v[212:215], v[92:95]
	v_mfma_f32_16x16x32_bf16 v[88:91], v[152:155], v[212:215], v[88:91]
	v_mfma_f32_16x16x32_bf16 v[76:79], v[144:147], v[232:235], v[76:79]
	v_mfma_f32_16x16x32_bf16 v[72:75], v[152:155], v[232:235], v[72:75]
	v_mfma_f32_16x16x32_bf16 v[116:119], v[156:159], v[172:175], v[116:119]
	v_mfma_f32_16x16x32_bf16 v[112:115], v[164:167], v[172:175], v[112:115]
	v_mfma_f32_16x16x32_bf16 v[100:103], v[156:159], v[180:183], v[100:103]
	v_mfma_f32_16x16x32_bf16 v[96:99], v[164:167], v[180:183], v[96:99]
	v_mfma_f32_16x16x32_bf16 v[84:87], v[156:159], v[188:191], v[84:87]
	v_mfma_f32_16x16x32_bf16 v[80:83], v[164:167], v[188:191], v[80:83]
	v_mfma_f32_16x16x32_bf16 v[68:71], v[156:159], v[216:219], v[68:71]
	v_mfma_f32_16x16x32_bf16 v[64:67], v[164:167], v[216:219], v[64:67]
	v_mfma_f32_16x16x32_bf16 v[116:119], v[160:163], v[176:179], v[116:119]
	v_mfma_f32_16x16x32_bf16 v[112:115], v[168:171], v[176:179], v[112:115]
	v_mfma_f32_16x16x32_bf16 v[100:103], v[160:163], v[184:187], v[100:103]
	v_mfma_f32_16x16x32_bf16 v[96:99], v[168:171], v[184:187], v[96:99]
	v_mfma_f32_16x16x32_bf16 v[84:87], v[160:163], v[212:215], v[84:87]
	v_mfma_f32_16x16x32_bf16 v[80:83], v[168:171], v[212:215], v[80:83]
	v_mfma_f32_16x16x32_bf16 v[68:71], v[160:163], v[232:235], v[68:71]
	v_mfma_f32_16x16x32_bf16 v[64:67], v[168:171], v[232:235], v[64:67]
	s_setprio 1
	s_barrier
	s_add_i32 s38, s40, s82
	v_lshl_add_u64 v[194:195], s[44:45], 0, v[192:193]
	s_mov_b32 m0, s38
	ds_read_b128 v[172:175], v143 offset:16384
	ds_read_b128 v[176:179], v143 offset:17408
	ds_read_b128 v[180:183], v143 offset:18432
	ds_read_b128 v[184:187], v143 offset:19456
	ds_read_b128 v[188:191], v143 offset:20480
	ds_read_b128 v[212:215], v143 offset:21504
	ds_read_b128 v[216:219], v143 offset:22528
	ds_read_b128 v[232:235], v143 offset:23552
	global_load_lds_dwordx4 v[194:195], off
	s_add_i32 m0, s38, 0x2000
	s_add_u32 s40, s44, 0x20000
	v_lshl_add_u64 v[196:197], s[44:45], 0, v[132:133]
	s_addc_u32 s41, s45, 0
	s_add_i32 s35, s35, s82
	global_load_lds_dwordx4 v[196:197], off
	v_lshl_add_u64 v[202:203], s[40:41], 0, v[192:193]
	s_mov_b32 m0, s35
	v_lshl_add_u64 v[204:205], s[58:59], 0, v[130:131]
	global_load_lds_dwordx4 v[202:203], off
	v_lshl_add_u64 v[202:203], s[40:41], 0, v[132:133]
	s_add_i32 m0, s35, 0x2000
	s_nop 0
	global_load_lds_dwordx4 v[202:203], off
	v_lshl_add_u64 v[202:203], s[58:59], 0, v[128:129]
	s_mov_b32 m0, s83
	s_nop 0
	global_load_lds_dwordx4 v[202:203], off
	s_mov_b32 m0, s84
	s_nop 0
	global_load_lds_dwordx4 v[204:205], off
	s_waitcnt vmcnt(8)
	s_waitcnt lgkmcnt(0)
	s_barrier
; #define PG8_STAGE(bufoff, gbase, voff) do { _Pragma("unroll") for (int _i = 0; _i < 2; ++_i) \
;         __builtin_amdgcn_global_load_lds((const unsigned*)((const char*)(gbase) + (voff)[_i]), (PG8_LAS unsigned*)(lds + (bufoff) + ldsw + _i * 8192), 16, 0, 0); } while (0)
; #define PG8_LDA(dst, b, h) do { _Pragma("unroll") for (int m = 0; m < 4; ++m) _Pragma("unroll") for (int k = 0; k < 2; ++k) dst[m][k] = *(const PG8_LAS bf16x8*)(lds + PG8_SA(b, h) + aoff + m * 2048 + k * 1024); } while (0)
; #define PG8_LDB(dst, b, h) do { _Pragma("unroll") for (int n = 0; n < 2; ++n) _Pragma("unroll") for (int k = 0; k < 2; ++k) dst[n][k] = *(const PG8_LAS bf16x8*)(lds + PG8_SB(b, h) + boff + n * 2048 + k * 1024); } while (0)
; #define PG8_MMA(ai, bj, At, Bt) do { __builtin_amdgcn_s_setprio(1); _Pragma("unroll") for (int m = 0; m < 4; ++m) _Pragma("unroll") for (int n = 0; n < 2; ++n) _Pragma("unroll") for (int k = 0; k < 2; ++k) \
;         acc[ai][bj][m][n] = __builtin_amdgcn_mfma_f32_16x16x32_bf16(Bt[n][k], At[m][k], acc[ai][bj][m][n], 0, 0, 0); __builtin_amdgcn_s_setprio(0); } while (0)
; #define PG8_WAIT_V(n) asm volatile("s_waitcnt vmcnt(" #n ")" ::: "memory")
; #define PG8_WAIT_L(n) asm volatile("s_waitcnt lgkmcnt(" #n ")" ::: "memory")
; #define PG8_BAR __builtin_amdgcn_s_barrier()
; #define PG8_SCHED __builtin_amdgcn_sched_barrier(0)
; template <class Epi, class Sched, bool ALIGN_EPI = false, bool SP2 = false>
; __device__ __forceinline__ void gemm_phase(PG8_LAS unsigned char* lds, const Gemm g, const Sched& S, const Epi& E, const int tid) {
;     ...
;             PG8_WAIT_V(8); PG8_WAIT_L(0); PG8_BAR; PG8_MMA(1, 0, At, B0); PG8_MMA(1, 1, At, B1); PG8_BAR; PG8_SCHED;
;             PG8_LDB(B0, 1, 0); PG8_LDB(B1, 1, 1); PG8_SCHED; PG8_LDA(At, 1, 0); PG8_STAGE(PG8_SA(0, 1), a2 + hstep, voffA);
;             PG8_WAIT_V(8); PG8_WAIT_L(0); PG8_BAR; PG8_MMA(0, 0, At, B0); PG8_MMA(0, 1, At, B1); PG8_BAR; PG8_SCHED;
	s_setprio 0
	s_waitcnt lgkmcnt(0)
	v_mfma_f32_16x16x32_bf16 v[60:63], v[138:141], v[172:175], v[60:63]
	v_mfma_f32_16x16x32_bf16 v[56:59], v[148:151], v[172:175], v[56:59]
	v_mfma_f32_16x16x32_bf16 v[44:47], v[138:141], v[180:183], v[44:47]
	v_mfma_f32_16x16x32_bf16 v[40:43], v[148:151], v[180:183], v[40:43]
	v_mfma_f32_16x16x32_bf16 v[28:31], v[138:141], v[188:191], v[28:31]
	v_mfma_f32_16x16x32_bf16 v[24:27], v[148:151], v[188:191], v[24:27]
	v_mfma_f32_16x16x32_bf16 v[12:15], v[138:141], v[216:219], v[12:15]
	v_mfma_f32_16x16x32_bf16 v[8:11], v[148:151], v[216:219], v[8:11]
	v_mfma_f32_16x16x32_bf16 v[60:63], v[144:147], v[176:179], v[60:63]
	v_mfma_f32_16x16x32_bf16 v[56:59], v[152:155], v[176:179], v[56:59]
	v_mfma_f32_16x16x32_bf16 v[44:47], v[144:147], v[184:187], v[44:47]
	v_mfma_f32_16x16x32_bf16 v[40:43], v[152:155], v[184:187], v[40:43]
	v_mfma_f32_16x16x32_bf16 v[28:31], v[144:147], v[212:215], v[28:31]
	v_mfma_f32_16x16x32_bf16 v[24:27], v[152:155], v[212:215], v[24:27]
	v_mfma_f32_16x16x32_bf16 v[12:15], v[144:147], v[232:235], v[12:15]
	v_mfma_f32_16x16x32_bf16 v[8:11], v[152:155], v[232:235], v[8:11]
	v_mfma_f32_16x16x32_bf16 v[52:55], v[156:159], v[172:175], v[52:55]
	v_mfma_f32_16x16x32_bf16 v[48:51], v[164:167], v[172:175], v[48:51]
	v_mfma_f32_16x16x32_bf16 v[36:39], v[156:159], v[180:183], v[36:39]
	v_mfma_f32_16x16x32_bf16 v[32:35], v[164:167], v[180:183], v[32:35]
	v_mfma_f32_16x16x32_bf16 v[20:23], v[156:159], v[188:191], v[20:23]
	v_mfma_f32_16x16x32_bf16 v[16:19], v[164:167], v[188:191], v[16:19]
	v_mfma_f32_16x16x32_bf16 v[4:7], v[156:159], v[216:219], v[4:7]
	v_mfma_f32_16x16x32_bf16 v[0:3], v[164:167], v[216:219], v[0:3]
	v_mfma_f32_16x16x32_bf16 v[52:55], v[160:163], v[176:179], v[52:55]
	v_mfma_f32_16x16x32_bf16 v[48:51], v[168:171], v[176:179], v[48:51]
	v_mfma_f32_16x16x32_bf16 v[36:39], v[160:163], v[184:187], v[36:39]
	v_mfma_f32_16x16x32_bf16 v[32:35], v[168:171], v[184:187], v[32:35]
	v_mfma_f32_16x16x32_bf16 v[20:23], v[160:163], v[212:215], v[20:23]
	v_mfma_f32_16x16x32_bf16 v[16:19], v[168:171], v[212:215], v[16:19]
	v_mfma_f32_16x16x32_bf16 v[4:7], v[160:163], v[232:235], v[4:7]
	v_mfma_f32_16x16x32_bf16 v[0:3], v[168:171], v[232:235], v[0:3]
	s_setprio 1
	s_barrier
	s_add_i32 s35, 0, 0x18000
	s_add_i32 s38, 0, 0x1c000
	v_add_u32_e32 v152, s35, v142
	v_add_u32_e32 v168, s38, v142
	ds_read_b128 v[138:141], v152
	ds_read_b128 v[144:147], v152 offset:1024
	ds_read_b128 v[148:151], v152 offset:2048
	ds_read_b128 v[152:155], v152 offset:3072
	ds_read_b128 v[156:159], v168
	ds_read_b128 v[160:163], v168 offset:1024
	ds_read_b128 v[164:167], v168 offset:2048
	ds_read_b128 v[168:171], v168 offset:3072
	s_add_u32 s40, s58, 0x20000
	s_addc_u32 s41, s59, 0
	s_mov_b32 m0, s85
	v_lshl_add_u64 v[206:207], s[40:41], 0, v[128:129]
	ds_read_b128 v[172:175], v143 offset:32768
	ds_read_b128 v[176:179], v143 offset:33792
	ds_read_b128 v[180:183], v143 offset:34816
	ds_read_b128 v[184:187], v143 offset:35840
	ds_read_b128 v[188:191], v143 offset:36864
	ds_read_b128 v[212:215], v143 offset:37888
	ds_read_b128 v[216:219], v143 offset:38912
	ds_read_b128 v[232:235], v143 offset:39936
	global_load_lds_dwordx4 v[206:207], off
	v_lshl_add_u64 v[206:207], s[40:41], 0, v[130:131]
	s_mov_b32 m0, s86
	s_nop 0
	global_load_lds_dwordx4 v[206:207], off
	s_waitcnt vmcnt(8)
	s_waitcnt lgkmcnt(0)
	s_barrier
	s_setprio 0
	s_waitcnt lgkmcnt(0)
	v_mfma_f32_16x16x32_bf16 v[124:127], v[138:141], v[172:175], v[124:127]
	v_mfma_f32_16x16x32_bf16 v[120:123], v[148:151], v[172:175], v[120:123]
	v_mfma_f32_16x16x32_bf16 v[108:111], v[138:141], v[180:183], v[108:111]
	v_mfma_f32_16x16x32_bf16 v[104:107], v[148:151], v[180:183], v[104:107]
	v_mfma_f32_16x16x32_bf16 v[92:95], v[138:141], v[188:191], v[92:95]
	v_mfma_f32_16x16x32_bf16 v[88:91], v[148:151], v[188:191], v[88:91]
	v_mfma_f32_16x16x32_bf16 v[76:79], v[138:141], v[216:219], v[76:79]
	v_mfma_f32_16x16x32_bf16 v[72:75], v[148:151], v[216:219], v[72:75]
	v_mfma_f32_16x16x32_bf16 v[124:127], v[144:147], v[176:179], v[124:127]
	v_mfma_f32_16x16x32_bf16 v[120:123], v[152:155], v[176:179], v[120:123]
	v_mfma_f32_16x16x32_bf16 v[108:111], v[144:147], v[184:187], v[108:111]
	v_mfma_f32_16x16x32_bf16 v[104:107], v[152:155], v[184:187], v[104:107]
	v_mfma_f32_16x16x32_bf16 v[92:95], v[144:147], v[212:215], v[92:95]
	v_mfma_f32_16x16x32_bf16 v[88:91], v[152:155], v[212:215], v[88:91]
	v_mfma_f32_16x16x32_bf16 v[76:79], v[144:147], v[232:235], v[76:79]
	v_mfma_f32_16x16x32_bf16 v[72:75], v[152:155], v[232:235], v[72:75]
	v_mfma_f32_16x16x32_bf16 v[116:119], v[156:159], v[172:175], v[116:119]
	v_mfma_f32_16x16x32_bf16 v[112:115], v[164:167], v[172:175], v[112:115]
	v_mfma_f32_16x16x32_bf16 v[100:103], v[156:159], v[180:183], v[100:103]
	v_mfma_f32_16x16x32_bf16 v[96:99], v[164:167], v[180:183], v[96:99]
	v_mfma_f32_16x16x32_bf16 v[84:87], v[156:159], v[188:191], v[84:87]
	v_mfma_f32_16x16x32_bf16 v[80:83], v[164:167], v[188:191], v[80:83]
	v_mfma_f32_16x16x32_bf16 v[68:71], v[156:159], v[216:219], v[68:71]
	v_mfma_f32_16x16x32_bf16 v[64:67], v[164:167], v[216:219], v[64:67]
	v_mfma_f32_16x16x32_bf16 v[116:119], v[160:163], v[176:179], v[116:119]
	v_mfma_f32_16x16x32_bf16 v[112:115], v[168:171], v[176:179], v[112:115]
	v_mfma_f32_16x16x32_bf16 v[100:103], v[160:163], v[184:187], v[100:103]
	v_mfma_f32_16x16x32_bf16 v[96:99], v[168:171], v[184:187], v[96:99]
	v_mfma_f32_16x16x32_bf16 v[84:87], v[160:163], v[212:215], v[84:87]
	v_mfma_f32_16x16x32_bf16 v[80:83], v[168:171], v[212:215], v[80:83]
	v_mfma_f32_16x16x32_bf16 v[68:71], v[160:163], v[232:235], v[68:71]
	v_mfma_f32_16x16x32_bf16 v[64:67], v[168:171], v[232:235], v[64:67]
	s_setprio 1
	s_barrier
; #define PG8_STAGE(bufoff, gbase, voff) do { _Pragma("unroll") for (int _i = 0; _i < 2; ++_i) \
;         __builtin_amdgcn_global_load_lds((const unsigned*)((const char*)(gbase) + (voff)[_i]), (PG8_LAS unsigned*)(lds + (bufoff) + ldsw + _i * 8192), 16, 0, 0); } while (0)
; #define PG8_LDA(dst, b, h) do { _Pragma("unroll") for (int m = 0; m < 4; ++m) _Pragma("unroll") for (int k = 0; k < 2; ++k) dst[m][k] = *(const PG8_LAS bf16x8*)(lds + PG8_SA(b, h) + aoff + m * 2048 + k * 1024); } while (0)
; #define PG8_MMA(ai, bj, At, Bt) do { __builtin_amdgcn_s_setprio(1); _Pragma("unroll") for (int m = 0; m < 4; ++m) _Pragma("unroll") for (int n = 0; n < 2; ++n) _Pragma("unroll") for (int k = 0; k < 2; ++k) \
;         acc[ai][bj][m][n] = __builtin_amdgcn_mfma_f32_16x16x32_bf16(Bt[n][k], At[m][k], acc[ai][bj][m][n], 0, 0, 0); __builtin_amdgcn_s_setprio(0); } while (0)
; #define PG8_WAIT_V(n) asm volatile("s_waitcnt vmcnt(" #n ")" ::: "memory")
; #define PG8_WAIT_L(n) asm volatile("s_waitcnt lgkmcnt(" #n ")" ::: "memory")
; #define PG8_BAR __builtin_amdgcn_s_barrier()
; #define PG8_SCHED __builtin_amdgcn_sched_barrier(0)
; template <class Epi, class Sched, bool ALIGN_EPI = false, bool SP2 = false>
; __device__ __forceinline__ void gemm_phase(PG8_LAS unsigned char* lds, const Gemm g, const Sched& S, const Epi& E, const int tid) {
;     ...
;         for (int t = 0; t < nt; t += 2) {
;     ...
;             PG8_LDA(At, 1, 1); PG8_STAGE(PG8_SB(1, 0), b3, voffB); PG8_STAGE(PG8_SB(1, 1), b3 + hstep, voffB); PG8_STAGE(PG8_SA(1, 0), a3, voffA);
;             PG8_WAIT_V(8); PG8_WAIT_L(0); PG8_BAR; PG8_MMA(1, 0, At, B0); PG8_MMA(1, 1, At, B1); PG8_BAR; PG8_SCHED;
;     ...
;         if constexpr (ALIGN_EPI) { if (wr == 0) PG8_BAR; }
	s_add_i32 s35, s35, s82
	v_lshl_add_u64 v[194:195], v[194:195], 0, s[36:37]
	s_mov_b32 m0, s35
	ds_read_b128 v[172:175], v143 offset:49152
	ds_read_b128 v[176:179], v143 offset:50176
	ds_read_b128 v[180:183], v143 offset:51200
	ds_read_b128 v[184:187], v143 offset:52224
	ds_read_b128 v[188:191], v143 offset:53248
	ds_read_b128 v[212:215], v143 offset:54272
	ds_read_b128 v[216:219], v143 offset:55296
	ds_read_b128 v[232:235], v143 offset:56320
	global_load_lds_dwordx4 v[194:195], off
	s_add_i32 m0, s35, 0x2000
	s_add_u32 s40, s44, 0x20080
	v_lshl_add_u64 v[194:195], v[196:197], 0, s[36:37]
	s_addc_u32 s41, s45, 0
	s_add_i32 s35, s38, s82
	global_load_lds_dwordx4 v[194:195], off
	v_lshl_add_u64 v[194:195], s[40:41], 0, v[192:193]
	s_mov_b32 m0, s35
	s_nop 0
	global_load_lds_dwordx4 v[194:195], off
	v_lshl_add_u64 v[194:195], s[40:41], 0, v[132:133]
	s_add_i32 m0, s35, 0x2000
	s_nop 0
	global_load_lds_dwordx4 v[194:195], off
	v_lshl_add_u64 v[194:195], v[202:203], 0, s[36:37]
	s_mov_b32 m0, s87
	s_nop 0
	global_load_lds_dwordx4 v[194:195], off
	v_lshl_add_u64 v[194:195], v[204:205], 0, s[36:37]
	s_mov_b32 m0, s88
	s_nop 0
	global_load_lds_dwordx4 v[194:195], off
	s_waitcnt vmcnt(8)
	s_waitcnt lgkmcnt(0)
	s_barrier
	s_setprio 0
	s_waitcnt lgkmcnt(0)
	v_mfma_f32_16x16x32_bf16 v[60:63], v[138:141], v[172:175], v[60:63]
	v_mfma_f32_16x16x32_bf16 v[56:59], v[148:151], v[172:175], v[56:59]
	v_mfma_f32_16x16x32_bf16 v[44:47], v[138:141], v[180:183], v[44:47]
	v_mfma_f32_16x16x32_bf16 v[40:43], v[148:151], v[180:183], v[40:43]
	v_mfma_f32_16x16x32_bf16 v[28:31], v[138:141], v[188:191], v[28:31]
	v_mfma_f32_16x16x32_bf16 v[24:27], v[148:151], v[188:191], v[24:27]
	v_mfma_f32_16x16x32_bf16 v[12:15], v[138:141], v[216:219], v[12:15]
	v_mfma_f32_16x16x32_bf16 v[8:11], v[148:151], v[216:219], v[8:11]
	v_mfma_f32_16x16x32_bf16 v[60:63], v[144:147], v[176:179], v[60:63]
	v_mfma_f32_16x16x32_bf16 v[56:59], v[152:155], v[176:179], v[56:59]
	v_mfma_f32_16x16x32_bf16 v[44:47], v[144:147], v[184:187], v[44:47]
	v_mfma_f32_16x16x32_bf16 v[40:43], v[152:155], v[184:187], v[40:43]
	v_mfma_f32_16x16x32_bf16 v[28:31], v[144:147], v[212:215], v[28:31]
	v_mfma_f32_16x16x32_bf16 v[24:27], v[152:155], v[212:215], v[24:27]
	v_mfma_f32_16x16x32_bf16 v[12:15], v[144:147], v[232:235], v[12:15]
	v_mfma_f32_16x16x32_bf16 v[8:11], v[152:155], v[232:235], v[8:11]
	v_mfma_f32_16x16x32_bf16 v[52:55], v[156:159], v[172:175], v[52:55]
	v_mfma_f32_16x16x32_bf16 v[48:51], v[164:167], v[172:175], v[48:51]
	v_mfma_f32_16x16x32_bf16 v[36:39], v[156:159], v[180:183], v[36:39]
	v_mfma_f32_16x16x32_bf16 v[32:35], v[164:167], v[180:183], v[32:35]
	v_mfma_f32_16x16x32_bf16 v[20:23], v[156:159], v[188:191], v[20:23]
	v_mfma_f32_16x16x32_bf16 v[16:19], v[164:167], v[188:191], v[16:19]
	v_mfma_f32_16x16x32_bf16 v[4:7], v[156:159], v[216:219], v[4:7]
	v_mfma_f32_16x16x32_bf16 v[0:3], v[164:167], v[216:219], v[0:3]
	v_mfma_f32_16x16x32_bf16 v[52:55], v[160:163], v[176:179], v[52:55]
	v_mfma_f32_16x16x32_bf16 v[48:51], v[168:171], v[176:179], v[48:51]
	v_mfma_f32_16x16x32_bf16 v[36:39], v[160:163], v[184:187], v[36:39]
	v_mfma_f32_16x16x32_bf16 v[32:35], v[168:171], v[184:187], v[32:35]
	v_mfma_f32_16x16x32_bf16 v[20:23], v[160:163], v[212:215], v[20:23]
	v_mfma_f32_16x16x32_bf16 v[16:19], v[168:171], v[212:215], v[16:19]
	v_mfma_f32_16x16x32_bf16 v[4:7], v[160:163], v[232:235], v[4:7]
	v_mfma_f32_16x16x32_bf16 v[0:3], v[168:171], v[232:235], v[0:3]
	s_setprio 1
	s_barrier
	s_add_i32 s34, s34, 2
	s_add_u32 s28, s28, 0x100
	s_addc_u32 s29, s29, 0
	s_add_u32 s23, s23, 0x100
	s_addc_u32 s26, s26, 0
	s_cmp_gt_u32 s34, 5
	s_cbranch_scc0 .LBB0_348
	s_and_b64 vcc, exec, s[12:13]
	s_cbranch_vccz .LBB0_351
	s_barrier

; #define PG8_STAGE(bufoff, gbase, voff) do { _Pragma("unroll") for (int _i = 0; _i < 2; ++_i) \
;         __builtin_amdgcn_global_load_lds((const unsigned*)((const char*)(gbase) + (voff)[_i]), (PG8_LAS unsigned*)(lds + (bufoff) + ldsw + _i * 8192), 16, 0, 0); } while (0)
; #define PG8_LDA(dst, b, h) do { _Pragma("unroll") for (int m = 0; m < 4; ++m) _Pragma("unroll") for (int k = 0; k < 2; ++k) dst[m][k] = *(const PG8_LAS bf16x8*)(lds + PG8_SA(b, h) + aoff + m * 2048 + k * 1024); } while (0)
; #define PG8_LDB(dst, b, h) do { _Pragma("unroll") for (int n = 0; n < 2; ++n) _Pragma("unroll") for (int k = 0; k < 2; ++k) dst[n][k] = *(const PG8_LAS bf16x8*)(lds + PG8_SB(b, h) + boff + n * 2048 + k * 1024); } while (0)
; #define PG8_MMA(ai, bj, At, Bt) do { __builtin_amdgcn_s_setprio(1); _Pragma("unroll") for (int m = 0; m < 4; ++m) _Pragma("unroll") for (int n = 0; n < 2; ++n) _Pragma("unroll") for (int k = 0; k < 2; ++k) \
;         acc[ai][bj][m][n] = __builtin_amdgcn_mfma_f32_16x16x32_bf16(Bt[n][k], At[m][k], acc[ai][bj][m][n], 0, 0, 0); __builtin_amdgcn_s_setprio(0); } while (0)
; #define PG8_WAIT_V(n) asm volatile("s_waitcnt vmcnt(" #n ")" ::: "memory")
; #define PG8_WAIT_L(n) asm volatile("s_waitcnt lgkmcnt(" #n ")" ::: "memory")
; #define PG8_BAR __builtin_amdgcn_s_barrier()
; #define PG8_SCHED __builtin_amdgcn_sched_barrier(0)
; template <class Epi, class Sched, bool ALIGN_EPI = false, bool SP2 = false>
; __device__ __forceinline__ void gemm_phase(PG8_LAS unsigned char* lds, const Gemm g, const Sched& S, const Epi& E, const int tid) {
;     ...
;             const bool last = (t == nt - 2);
;             const char* a1 = cA + (size_t)(t + 1) * kstep;
;             const char* a2 = last ? nA : cA + (size_t)(t + 2) * kstep; const char* b2 = last ? nB : cB + (size_t)(t + 2) * kstep;
;             const char* a3 = a2 + kstep; const char* b3 = b2 + kstep;
;             if (last && has_next) S.a_ready(nxt);
;             if constexpr (SP2) {
;             PG8_LDB(B0, 0, 0); PG8_LDB(B1, 0, 1); PG8_SCHED; PG8_LDA(At, 0, 0); PG8_STAGE(PG8_SA(1, 1), a1 + hstep, voffA);
;             PG8_WAIT_V(8); PG8_WAIT_L(0); PG8_BAR; PG8_MMA(0, 0, At, B0); PG8_MMA(0, 1, At, B1); PG8_BAR; PG8_SCHED;
;             PG8_LDA(At, 0, 1); PG8_STAGE(PG8_SB(0, 0), b2, voffB); PG8_STAGE(PG8_SB(0, 1), b2 + hstep, voffB); PG8_STAGE(PG8_SA(0, 0), a2, voffA);
.LBB0_485:
	s_add_u32 s38, s8, 0xfffc0080
	s_addc_u32 s40, s9, -1
	s_add_i32 s41, 0, 0x10000
	s_cmp_eq_u32 s35, 12
	s_cselect_b32 s59, s0, s40
	s_cselect_b32 s58, s1, s38
	s_cselect_b32 s45, s2, s34
	s_cselect_b32 s44, s15, s17
	s_add_i32 s38, 0, 0x14000
	v_add_u32_e32 v140, s41, v184
	v_add_u32_e32 v168, s38, v184
	ds_read_b128 v[128:131], v140
	ds_read_b128 v[132:135], v140 offset:1024
	ds_read_b128 v[136:139], v140 offset:2048
	ds_read_b128 v[140:143], v140 offset:3072
	ds_read_b128 v[144:147], v168
	ds_read_b128 v[148:151], v168 offset:1024
	ds_read_b128 v[164:167], v168 offset:2048
	ds_read_b128 v[168:171], v168 offset:3072
	v_lshl_add_u64 v[190:191], s[8:9], 0, v[160:161]
	s_add_i32 m0, s23, 0xc000
	ds_read_b128 v[172:175], v185
	ds_read_b128 v[176:179], v185 offset:1024
	ds_read_b128 v[180:183], v185 offset:2048
	ds_read_b128 v[186:189], v185 offset:3072
	ds_read_b128 v[212:215], v185 offset:4096
	ds_read_b128 v[216:219], v185 offset:5120
	ds_read_b128 v[232:235], v185 offset:6144
	ds_read_b128 v[236:239], v185 offset:7168
	global_load_lds_dwordx4 v[190:191], off
	v_lshl_add_u64 v[190:191], s[8:9], 0, v[162:163]
	s_add_i32 m0, s23, 0xe000
	s_nop 0
	global_load_lds_dwordx4 v[190:191], off
	s_waitcnt vmcnt(8)
	s_waitcnt lgkmcnt(0)
	s_barrier
	s_setprio 0
	s_waitcnt lgkmcnt(0)
	v_mfma_f32_16x16x32_bf16 v[124:127], v[128:131], v[172:175], v[124:127]
	v_mfma_f32_16x16x32_bf16 v[120:123], v[136:139], v[172:175], v[120:123]
	v_mfma_f32_16x16x32_bf16 v[108:111], v[128:131], v[180:183], v[108:111]
	v_mfma_f32_16x16x32_bf16 v[104:107], v[136:139], v[180:183], v[104:107]
	v_mfma_f32_16x16x32_bf16 v[92:95], v[128:131], v[212:215], v[92:95]
	v_mfma_f32_16x16x32_bf16 v[88:91], v[136:139], v[212:215], v[88:91]
	v_mfma_f32_16x16x32_bf16 v[76:79], v[128:131], v[232:235], v[76:79]
	v_mfma_f32_16x16x32_bf16 v[72:75], v[136:139], v[232:235], v[72:75]
	v_mfma_f32_16x16x32_bf16 v[124:127], v[132:135], v[176:179], v[124:127]
	v_mfma_f32_16x16x32_bf16 v[120:123], v[140:143], v[176:179], v[120:123]
	v_mfma_f32_16x16x32_bf16 v[108:111], v[132:135], v[186:189], v[108:111]
	v_mfma_f32_16x16x32_bf16 v[104:107], v[140:143], v[186:189], v[104:107]
	v_mfma_f32_16x16x32_bf16 v[92:95], v[132:135], v[216:219], v[92:95]
	v_mfma_f32_16x16x32_bf16 v[88:91], v[140:143], v[216:219], v[88:91]
	v_mfma_f32_16x16x32_bf16 v[76:79], v[132:135], v[236:239], v[76:79]
	v_mfma_f32_16x16x32_bf16 v[72:75], v[140:143], v[236:239], v[72:75]
	v_mfma_f32_16x16x32_bf16 v[116:119], v[144:147], v[172:175], v[116:119]
	v_mfma_f32_16x16x32_bf16 v[112:115], v[164:167], v[172:175], v[112:115]
	v_mfma_f32_16x16x32_bf16 v[100:103], v[144:147], v[180:183], v[100:103]
	v_mfma_f32_16x16x32_bf16 v[96:99], v[164:167], v[180:183], v[96:99]
	v_mfma_f32_16x16x32_bf16 v[84:87], v[144:147], v[212:215], v[84:87]
	v_mfma_f32_16x16x32_bf16 v[80:83], v[164:167], v[212:215], v[80:83]
	v_mfma_f32_16x16x32_bf16 v[68:71], v[144:147], v[232:235], v[68:71]
	v_mfma_f32_16x16x32_bf16 v[64:67], v[164:167], v[232:235], v[64:67]
	v_mfma_f32_16x16x32_bf16 v[116:119], v[148:151], v[176:179], v[116:119]
	v_mfma_f32_16x16x32_bf16 v[112:115], v[168:171], v[176:179], v[112:115]
	v_mfma_f32_16x16x32_bf16 v[100:103], v[148:151], v[186:189], v[100:103]
	v_mfma_f32_16x16x32_bf16 v[96:99], v[168:171], v[186:189], v[96:99]
	v_mfma_f32_16x16x32_bf16 v[84:87], v[148:151], v[216:219], v[84:87]
	v_mfma_f32_16x16x32_bf16 v[80:83], v[168:171], v[216:219], v[80:83]
	v_mfma_f32_16x16x32_bf16 v[68:71], v[148:151], v[236:239], v[68:71]
	v_mfma_f32_16x16x32_bf16 v[64:67], v[168:171], v[236:239], v[64:67]
	s_setprio 1
	s_barrier
	s_add_i32 s40, s41, s83
	v_lshl_add_u64 v[190:191], s[44:45], 0, v[154:155]
	s_mov_b32 m0, s40
	ds_read_b128 v[172:175], v185 offset:16384
	ds_read_b128 v[176:179], v185 offset:17408
	ds_read_b128 v[180:183], v185 offset:18432
	ds_read_b128 v[186:189], v185 offset:19456
	ds_read_b128 v[212:215], v185 offset:20480
	ds_read_b128 v[216:219], v185 offset:21504
	ds_read_b128 v[232:235], v185 offset:22528
	ds_read_b128 v[236:239], v185 offset:23552
	global_load_lds_dwordx4 v[190:191], off
	s_add_i32 m0, s40, 0x2000
	s_add_u32 s40, s44, 0x40000
	v_lshl_add_u64 v[194:195], s[44:45], 0, v[158:159]
	s_addc_u32 s41, s45, 0
	s_add_i32 s38, s38, s83
	global_load_lds_dwordx4 v[194:195], off
	v_lshl_add_u64 v[196:197], s[40:41], 0, v[154:155]
	s_mov_b32 m0, s38
	v_lshl_add_u64 v[202:203], s[58:59], 0, v[156:157]
	global_load_lds_dwordx4 v[196:197], off
	v_lshl_add_u64 v[196:197], s[40:41], 0, v[158:159]
	s_add_i32 m0, s38, 0x2000
	s_nop 0
	global_load_lds_dwordx4 v[196:197], off
	v_lshl_add_u64 v[196:197], s[58:59], 0, v[152:153]
	s_mov_b32 m0, s23
	s_nop 0
	global_load_lds_dwordx4 v[196:197], off
	s_mov_b32 m0, s29
	s_nop 0
	global_load_lds_dwordx4 v[202:203], off
	s_waitcnt vmcnt(8)
	s_waitcnt lgkmcnt(0)
	s_barrier
; #define PG8_STAGE(bufoff, gbase, voff) do { _Pragma("unroll") for (int _i = 0; _i < 2; ++_i) \
;         __builtin_amdgcn_global_load_lds((const unsigned*)((const char*)(gbase) + (voff)[_i]), (PG8_LAS unsigned*)(lds + (bufoff) + ldsw + _i * 8192), 16, 0, 0); } while (0)
; #define PG8_LDA(dst, b, h) do { _Pragma("unroll") for (int m = 0; m < 4; ++m) _Pragma("unroll") for (int k = 0; k < 2; ++k) dst[m][k] = *(const PG8_LAS bf16x8*)(lds + PG8_SA(b, h) + aoff + m * 2048 + k * 1024); } while (0)
; #define PG8_LDB(dst, b, h) do { _Pragma("unroll") for (int n = 0; n < 2; ++n) _Pragma("unroll") for (int k = 0; k < 2; ++k) dst[n][k] = *(const PG8_LAS bf16x8*)(lds + PG8_SB(b, h) + boff + n * 2048 + k * 1024); } while (0)
; #define PG8_MMA(ai, bj, At, Bt) do { __builtin_amdgcn_s_setprio(1); _Pragma("unroll") for (int m = 0; m < 4; ++m) _Pragma("unroll") for (int n = 0; n < 2; ++n) _Pragma("unroll") for (int k = 0; k < 2; ++k) \
;         acc[ai][bj][m][n] = __builtin_amdgcn_mfma_f32_16x16x32_bf16(Bt[n][k], At[m][k], acc[ai][bj][m][n], 0, 0, 0); __builtin_amdgcn_s_setprio(0); } while (0)
; #define PG8_WAIT_V(n) asm volatile("s_waitcnt vmcnt(" #n ")" ::: "memory")
; #define PG8_WAIT_L(n) asm volatile("s_waitcnt lgkmcnt(" #n ")" ::: "memory")
; #define PG8_BAR __builtin_amdgcn_s_barrier()
; #define PG8_SCHED __builtin_amdgcn_sched_barrier(0)
; template <class Epi, class Sched, bool ALIGN_EPI = false, bool SP2 = false>
; __device__ __forceinline__ void gemm_phase(PG8_LAS unsigned char* lds, const Gemm g, const Sched& S, const Epi& E, const int tid) {
;     ...
;             PG8_WAIT_V(8); PG8_WAIT_L(0); PG8_BAR; PG8_MMA(1, 0, At, B0); PG8_MMA(1, 1, At, B1); PG8_BAR; PG8_SCHED;
;             PG8_LDB(B0, 1, 0); PG8_LDB(B1, 1, 1); PG8_SCHED; PG8_LDA(At, 1, 0); PG8_STAGE(PG8_SA(0, 1), a2 + hstep, voffA);
;             PG8_WAIT_V(8); PG8_WAIT_L(0); PG8_BAR; PG8_MMA(0, 0, At, B0); PG8_MMA(0, 1, At, B1); PG8_BAR; PG8_SCHED;
	s_setprio 0
	s_waitcnt lgkmcnt(0)
	v_mfma_f32_16x16x32_bf16 v[60:63], v[128:131], v[172:175], v[60:63]
	v_mfma_f32_16x16x32_bf16 v[56:59], v[136:139], v[172:175], v[56:59]
	v_mfma_f32_16x16x32_bf16 v[44:47], v[128:131], v[180:183], v[44:47]
	v_mfma_f32_16x16x32_bf16 v[40:43], v[136:139], v[180:183], v[40:43]
	v_mfma_f32_16x16x32_bf16 v[28:31], v[128:131], v[212:215], v[28:31]
	v_mfma_f32_16x16x32_bf16 v[24:27], v[136:139], v[212:215], v[24:27]
	v_mfma_f32_16x16x32_bf16 v[12:15], v[128:131], v[232:235], v[12:15]
	v_mfma_f32_16x16x32_bf16 v[8:11], v[136:139], v[232:235], v[8:11]
	v_mfma_f32_16x16x32_bf16 v[60:63], v[132:135], v[176:179], v[60:63]
	v_mfma_f32_16x16x32_bf16 v[56:59], v[140:143], v[176:179], v[56:59]
	v_mfma_f32_16x16x32_bf16 v[44:47], v[132:135], v[186:189], v[44:47]
	v_mfma_f32_16x16x32_bf16 v[40:43], v[140:143], v[186:189], v[40:43]
	v_mfma_f32_16x16x32_bf16 v[28:31], v[132:135], v[216:219], v[28:31]
	v_mfma_f32_16x16x32_bf16 v[24:27], v[140:143], v[216:219], v[24:27]
	v_mfma_f32_16x16x32_bf16 v[12:15], v[132:135], v[236:239], v[12:15]
	v_mfma_f32_16x16x32_bf16 v[8:11], v[140:143], v[236:239], v[8:11]
	v_mfma_f32_16x16x32_bf16 v[52:55], v[144:147], v[172:175], v[52:55]
	v_mfma_f32_16x16x32_bf16 v[48:51], v[164:167], v[172:175], v[48:51]
	v_mfma_f32_16x16x32_bf16 v[36:39], v[144:147], v[180:183], v[36:39]
	v_mfma_f32_16x16x32_bf16 v[32:35], v[164:167], v[180:183], v[32:35]
	v_mfma_f32_16x16x32_bf16 v[20:23], v[144:147], v[212:215], v[20:23]
	v_mfma_f32_16x16x32_bf16 v[16:19], v[164:167], v[212:215], v[16:19]
	v_mfma_f32_16x16x32_bf16 v[4:7], v[144:147], v[232:235], v[4:7]
	v_mfma_f32_16x16x32_bf16 v[0:3], v[164:167], v[232:235], v[0:3]
	v_mfma_f32_16x16x32_bf16 v[52:55], v[148:151], v[176:179], v[52:55]
	v_mfma_f32_16x16x32_bf16 v[48:51], v[168:171], v[176:179], v[48:51]
	v_mfma_f32_16x16x32_bf16 v[36:39], v[148:151], v[186:189], v[36:39]
	v_mfma_f32_16x16x32_bf16 v[32:35], v[168:171], v[186:189], v[32:35]
	v_mfma_f32_16x16x32_bf16 v[20:23], v[148:151], v[216:219], v[20:23]
	v_mfma_f32_16x16x32_bf16 v[16:19], v[168:171], v[216:219], v[16:19]
	v_mfma_f32_16x16x32_bf16 v[4:7], v[148:151], v[236:239], v[4:7]
	v_mfma_f32_16x16x32_bf16 v[0:3], v[168:171], v[236:239], v[0:3]
	s_setprio 1
	s_barrier
	s_add_i32 s38, 0, 0x18000
	s_add_i32 s46, 0, 0x1c000
	v_add_u32_e32 v140, s38, v184
	v_add_u32_e32 v168, s46, v184
	ds_read_b128 v[128:131], v140
	ds_read_b128 v[132:135], v140 offset:1024
	ds_read_b128 v[136:139], v140 offset:2048
	ds_read_b128 v[140:143], v140 offset:3072
	ds_read_b128 v[144:147], v168
	ds_read_b128 v[148:151], v168 offset:1024
	ds_read_b128 v[164:167], v168 offset:2048
	ds_read_b128 v[168:171], v168 offset:3072
	s_add_u32 s40, s58, 0x40000
	s_addc_u32 s41, s59, 0
	s_mov_b32 m0, s84
	v_lshl_add_u64 v[204:205], s[40:41], 0, v[152:153]
	ds_read_b128 v[172:175], v185 offset:32768
	ds_read_b128 v[176:179], v185 offset:33792
	ds_read_b128 v[180:183], v185 offset:34816
	ds_read_b128 v[186:189], v185 offset:35840
	ds_read_b128 v[212:215], v185 offset:36864
	ds_read_b128 v[216:219], v185 offset:37888
	ds_read_b128 v[232:235], v185 offset:38912
	ds_read_b128 v[236:239], v185 offset:39936
	global_load_lds_dwordx4 v[204:205], off
	v_lshl_add_u64 v[204:205], s[40:41], 0, v[156:157]
	s_mov_b32 m0, s85
	s_nop 0
	global_load_lds_dwordx4 v[204:205], off
	s_waitcnt vmcnt(8)
	s_waitcnt lgkmcnt(0)
	s_barrier
	s_setprio 0
	s_waitcnt lgkmcnt(0)
	v_mfma_f32_16x16x32_bf16 v[124:127], v[128:131], v[172:175], v[124:127]
	v_mfma_f32_16x16x32_bf16 v[120:123], v[136:139], v[172:175], v[120:123]
	v_mfma_f32_16x16x32_bf16 v[108:111], v[128:131], v[180:183], v[108:111]
	v_mfma_f32_16x16x32_bf16 v[104:107], v[136:139], v[180:183], v[104:107]
	v_mfma_f32_16x16x32_bf16 v[92:95], v[128:131], v[212:215], v[92:95]
	v_mfma_f32_16x16x32_bf16 v[88:91], v[136:139], v[212:215], v[88:91]
	v_mfma_f32_16x16x32_bf16 v[76:79], v[128:131], v[232:235], v[76:79]
	v_mfma_f32_16x16x32_bf16 v[72:75], v[136:139], v[232:235], v[72:75]
	v_mfma_f32_16x16x32_bf16 v[124:127], v[132:135], v[176:179], v[124:127]
	v_mfma_f32_16x16x32_bf16 v[120:123], v[140:143], v[176:179], v[120:123]
	v_mfma_f32_16x16x32_bf16 v[108:111], v[132:135], v[186:189], v[108:111]
	v_mfma_f32_16x16x32_bf16 v[104:107], v[140:143], v[186:189], v[104:107]
	v_mfma_f32_16x16x32_bf16 v[92:95], v[132:135], v[216:219], v[92:95]
	v_mfma_f32_16x16x32_bf16 v[88:91], v[140:143], v[216:219], v[88:91]
	v_mfma_f32_16x16x32_bf16 v[76:79], v[132:135], v[236:239], v[76:79]
	v_mfma_f32_16x16x32_bf16 v[72:75], v[140:143], v[236:239], v[72:75]
	v_mfma_f32_16x16x32_bf16 v[116:119], v[144:147], v[172:175], v[116:119]
	v_mfma_f32_16x16x32_bf16 v[112:115], v[164:167], v[172:175], v[112:115]
	v_mfma_f32_16x16x32_bf16 v[100:103], v[144:147], v[180:183], v[100:103]
	v_mfma_f32_16x16x32_bf16 v[96:99], v[164:167], v[180:183], v[96:99]
	v_mfma_f32_16x16x32_bf16 v[84:87], v[144:147], v[212:215], v[84:87]
	v_mfma_f32_16x16x32_bf16 v[80:83], v[164:167], v[212:215], v[80:83]
	v_mfma_f32_16x16x32_bf16 v[68:71], v[144:147], v[232:235], v[68:71]
	v_mfma_f32_16x16x32_bf16 v[64:67], v[164:167], v[232:235], v[64:67]
	v_mfma_f32_16x16x32_bf16 v[116:119], v[148:151], v[176:179], v[116:119]
	v_mfma_f32_16x16x32_bf16 v[112:115], v[168:171], v[176:179], v[112:115]
	v_mfma_f32_16x16x32_bf16 v[100:103], v[148:151], v[186:189], v[100:103]
	v_mfma_f32_16x16x32_bf16 v[96:99], v[168:171], v[186:189], v[96:99]
	v_mfma_f32_16x16x32_bf16 v[84:87], v[148:151], v[216:219], v[84:87]
	v_mfma_f32_16x16x32_bf16 v[80:83], v[168:171], v[216:219], v[80:83]
	v_mfma_f32_16x16x32_bf16 v[68:71], v[148:151], v[236:239], v[68:71]
	v_mfma_f32_16x16x32_bf16 v[64:67], v[168:171], v[236:239], v[64:67]
	s_setprio 1
	s_barrier
; #define PG8_STAGE(bufoff, gbase, voff) do { _Pragma("unroll") for (int _i = 0; _i < 2; ++_i) \
;         __builtin_amdgcn_global_load_lds((const unsigned*)((const char*)(gbase) + (voff)[_i]), (PG8_LAS unsigned*)(lds + (bufoff) + ldsw + _i * 8192), 16, 0, 0); } while (0)
; #define PG8_LDA(dst, b, h) do { _Pragma("unroll") for (int m = 0; m < 4; ++m) _Pragma("unroll") for (int k = 0; k < 2; ++k) dst[m][k] = *(const PG8_LAS bf16x8*)(lds + PG8_SA(b, h) + aoff + m * 2048 + k * 1024); } while (0)
; #define PG8_MMA(ai, bj, At, Bt) do { __builtin_amdgcn_s_setprio(1); _Pragma("unroll") for (int m = 0; m < 4; ++m) _Pragma("unroll") for (int n = 0; n < 2; ++n) _Pragma("unroll") for (int k = 0; k < 2; ++k) \
;         acc[ai][bj][m][n] = __builtin_amdgcn_mfma_f32_16x16x32_bf16(Bt[n][k], At[m][k], acc[ai][bj][m][n], 0, 0, 0); __builtin_amdgcn_s_setprio(0); } while (0)
; #define PG8_WAIT_V(n) asm volatile("s_waitcnt vmcnt(" #n ")" ::: "memory")
; #define PG8_WAIT_L(n) asm volatile("s_waitcnt lgkmcnt(" #n ")" ::: "memory")
; #define PG8_BAR __builtin_amdgcn_s_barrier()
; #define PG8_SCHED __builtin_amdgcn_sched_barrier(0)
; template <class Epi, class Sched, bool ALIGN_EPI = false, bool SP2 = false>
; __device__ __forceinline__ void gemm_phase(PG8_LAS unsigned char* lds, const Gemm g, const Sched& S, const Epi& E, const int tid) {
;     ...
;         for (int t = 0; t < nt; t += 2) {
;     ...
;             PG8_LDA(At, 1, 1); PG8_STAGE(PG8_SB(1, 0), b3, voffB); PG8_STAGE(PG8_SB(1, 1), b3 + hstep, voffB); PG8_STAGE(PG8_SA(1, 0), a3, voffA);
;             PG8_WAIT_V(8); PG8_WAIT_L(0); PG8_BAR; PG8_MMA(1, 0, At, B0); PG8_MMA(1, 1, At, B1); PG8_BAR; PG8_SCHED;
;     ...
;         if constexpr (ALIGN_EPI) { if (wr == 0) PG8_BAR; }
	s_add_i32 s38, s38, s83
	v_lshl_add_u64 v[190:191], v[190:191], 0, s[36:37]
	s_mov_b32 m0, s38
	ds_read_b128 v[172:175], v185 offset:49152
	ds_read_b128 v[176:179], v185 offset:50176
	ds_read_b128 v[180:183], v185 offset:51200
	ds_read_b128 v[186:189], v185 offset:52224
	ds_read_b128 v[212:215], v185 offset:53248
	ds_read_b128 v[216:219], v185 offset:54272
	ds_read_b128 v[232:235], v185 offset:55296
	ds_read_b128 v[236:239], v185 offset:56320
	global_load_lds_dwordx4 v[190:191], off
	s_add_i32 m0, s38, 0x2000
	s_add_u32 s40, s44, 0x40080
	v_lshl_add_u64 v[190:191], v[194:195], 0, s[36:37]
	s_addc_u32 s41, s45, 0
	s_add_i32 s38, s46, s83
	global_load_lds_dwordx4 v[190:191], off
	v_lshl_add_u64 v[190:191], s[40:41], 0, v[154:155]
	s_mov_b32 m0, s38
	s_nop 0
	global_load_lds_dwordx4 v[190:191], off
	v_lshl_add_u64 v[190:191], s[40:41], 0, v[158:159]
	s_add_i32 m0, s38, 0x2000
	s_nop 0
	global_load_lds_dwordx4 v[190:191], off
	v_lshl_add_u64 v[190:191], v[196:197], 0, s[36:37]
	s_mov_b32 m0, s86
	s_nop 0
	global_load_lds_dwordx4 v[190:191], off
	v_lshl_add_u64 v[190:191], v[202:203], 0, s[36:37]
	s_mov_b32 m0, s87
	s_nop 0
	global_load_lds_dwordx4 v[190:191], off
	s_waitcnt vmcnt(8)
	s_waitcnt lgkmcnt(0)
	s_barrier
	s_setprio 0
	s_waitcnt lgkmcnt(0)
	v_mfma_f32_16x16x32_bf16 v[60:63], v[128:131], v[172:175], v[60:63]
	v_mfma_f32_16x16x32_bf16 v[56:59], v[136:139], v[172:175], v[56:59]
	v_mfma_f32_16x16x32_bf16 v[44:47], v[128:131], v[180:183], v[44:47]
	v_mfma_f32_16x16x32_bf16 v[40:43], v[136:139], v[180:183], v[40:43]
	v_mfma_f32_16x16x32_bf16 v[28:31], v[128:131], v[212:215], v[28:31]
	v_mfma_f32_16x16x32_bf16 v[24:27], v[136:139], v[212:215], v[24:27]
	v_mfma_f32_16x16x32_bf16 v[12:15], v[128:131], v[232:235], v[12:15]
	v_mfma_f32_16x16x32_bf16 v[8:11], v[136:139], v[232:235], v[8:11]
	v_mfma_f32_16x16x32_bf16 v[60:63], v[132:135], v[176:179], v[60:63]
	v_mfma_f32_16x16x32_bf16 v[56:59], v[140:143], v[176:179], v[56:59]
	v_mfma_f32_16x16x32_bf16 v[44:47], v[132:135], v[186:189], v[44:47]
	v_mfma_f32_16x16x32_bf16 v[40:43], v[140:143], v[186:189], v[40:43]
	v_mfma_f32_16x16x32_bf16 v[28:31], v[132:135], v[216:219], v[28:31]
	v_mfma_f32_16x16x32_bf16 v[24:27], v[140:143], v[216:219], v[24:27]
	v_mfma_f32_16x16x32_bf16 v[12:15], v[132:135], v[236:239], v[12:15]
	v_mfma_f32_16x16x32_bf16 v[8:11], v[140:143], v[236:239], v[8:11]
	v_mfma_f32_16x16x32_bf16 v[52:55], v[144:147], v[172:175], v[52:55]
	v_mfma_f32_16x16x32_bf16 v[48:51], v[164:167], v[172:175], v[48:51]
	v_mfma_f32_16x16x32_bf16 v[36:39], v[144:147], v[180:183], v[36:39]
	v_mfma_f32_16x16x32_bf16 v[32:35], v[164:167], v[180:183], v[32:35]
	v_mfma_f32_16x16x32_bf16 v[20:23], v[144:147], v[212:215], v[20:23]
	v_mfma_f32_16x16x32_bf16 v[16:19], v[164:167], v[212:215], v[16:19]
	v_mfma_f32_16x16x32_bf16 v[4:7], v[144:147], v[232:235], v[4:7]
	v_mfma_f32_16x16x32_bf16 v[0:3], v[164:167], v[232:235], v[0:3]
	v_mfma_f32_16x16x32_bf16 v[52:55], v[148:151], v[176:179], v[52:55]
	v_mfma_f32_16x16x32_bf16 v[48:51], v[168:171], v[176:179], v[48:51]
	v_mfma_f32_16x16x32_bf16 v[36:39], v[148:151], v[186:189], v[36:39]
	v_mfma_f32_16x16x32_bf16 v[32:35], v[168:171], v[186:189], v[32:35]
	v_mfma_f32_16x16x32_bf16 v[20:23], v[148:151], v[216:219], v[20:23]
	v_mfma_f32_16x16x32_bf16 v[16:19], v[168:171], v[216:219], v[16:19]
	v_mfma_f32_16x16x32_bf16 v[4:7], v[148:151], v[236:239], v[4:7]
	v_mfma_f32_16x16x32_bf16 v[0:3], v[168:171], v[236:239], v[0:3]
	s_setprio 1
	s_barrier
	s_add_i32 s35, s35, 2
	s_add_u32 s8, s8, 0x100
	s_addc_u32 s9, s9, 0
	s_add_u32 s17, s17, 0x100
	s_addc_u32 s34, s34, 0
	s_cmp_gt_u32 s35, 13
	s_cbranch_scc0 .LBB0_485
	s_and_b64 vcc, exec, s[12:13]
	s_cbranch_vccz .LBB0_488
	s_barrier
